# gated and residual GEMM epilogues prefetch tile loads ahead of use with counted waits; rwkv_fix state fragment 16 loads issued up front
# speedup vs baseline: 1.0743x; 1.0154x over previous
; __device__ __forceinline__ unsigned cvt_pk_bf16(float lo, float hi) { const f32x2_cv v = {lo, hi}; const bf16x2_cv b = __builtin_convertvector(v, bf16x2_cv); return __builtin_bit_cast(unsigned, b); }
;     __device__ __forceinline__ void operator()(const f32x4 (&acc)[2][2][4][2], const pg8::Unit& u, int wr, int wc, int fr, int fq) const {
;     ...
;         for (int ai = 0; ai < 2; ++ai)
; #pragma unroll
;             for (int m = 0; m < 4; ++m) {
;                 const int row = row0 + ai * 128 + m * 16;
;                 float* xp = X + (size_t)row * 1024 + col0; bf16_t* bp = XB + (size_t)row * 1024 + col0;
;                 const float* xi = Xp0 ? (row < T_P ? Xp0 + (size_t)row * 1024 + col0 : Xs0 + (size_t)(row - T_P) * 1024 + col0) : xp;
;                 float ss = 0.f;
; #pragma unroll
;                 for (int bj = 0; bj < 2; ++bj)
; #pragma unroll
;                     for (int n = 0; n < 2; ++n) {
;                         f32x4 xv = *(const f32x4*)(xi + bj * 128 + n * 16) + acc[ai][bj][m][n];
;                         *(f32x4*)(xp + bj * 128 + n * 16) = xv;
;                         ss += (xv[0] * xv[0] + xv[1] * xv[1]) + (xv[2] * xv[2] + xv[3] * xv[3]);
;                         u32x2 w; w.x = cvt_pk_bf16(xv[0], xv[1]); w.y = cvt_pk_bf16(xv[2], xv[3]);
;                         *(u32x2*)(bp + bj * 128 + n * 16) = w; }
;                 ss += __shfl_xor(ss, 16); ss += __shfl_xor(ss, 32);
;                 if (fq == 0) atomicAdd(rowss_out + row, ss); }
.LBB0_148:
	global_load_dwordx4 v[192:195], v[162:163], off
	global_load_dwordx4 v[196:199], v[162:163], off offset:64
	global_load_dwordx4 v[200:203], v[162:163], off offset:512
	global_load_dwordx4 v[204:207], v[162:163], off offset:576
	v_add_co_u32_e32 v224, vcc, 0x10000, v162
	s_nop 1
	v_addc_co_u32_e32 v225, vcc, 0, v163, vcc
	global_load_dwordx4 v[208:211], v[224:225], off
	global_load_dwordx4 v[212:215], v[224:225], off offset:64
	global_load_dwordx4 v[216:219], v[224:225], off offset:512
	global_load_dwordx4 v[220:223], v[224:225], off offset:576
	v_lshl_add_u64 v[164:165], v[164:165], 1, s[6:7]
	v_lshl_add_u64 v[174:175], v[156:157], 1, v[164:165]
	s_waitcnt vmcnt(4)
	v_mov_b32_e32 v170, v192
	v_mov_b32_e32 v171, v193
	v_mov_b32_e32 v172, v194
	v_mov_b32_e32 v173, v195
	v_pk_add_f32 v[126:127], v[126:127], v[172:173]
	v_pk_add_f32 v[124:125], v[124:125], v[170:171]
	v_cvt_pk_bf16_f32 v165, v126, v127
	v_cvt_pk_bf16_f32 v164, v124, v125
	global_store_dwordx4 v[160:161], v[124:127], off
	global_store_dwordx2 v[174:175], v[164:165], off
	s_nop 1
	v_mov_b32_e32 v170, v196
	v_mov_b32_e32 v171, v197
	v_mov_b32_e32 v172, v198
	v_mov_b32_e32 v173, v199
	v_pk_add_f32 v[172:173], v[122:123], v[172:173]
	v_pk_add_f32 v[170:171], v[120:121], v[170:171]
	v_cvt_pk_bf16_f32 v121, v172, v173
	v_cvt_pk_bf16_f32 v120, v170, v171
	global_store_dwordx4 v[160:161], v[170:173], off offset:64
	global_store_dwordx2 v[174:175], v[120:121], off offset:32
	s_nop 1
	v_mov_b32_e32 v120, v200
	v_mov_b32_e32 v121, v201
	v_mov_b32_e32 v122, v202
	v_mov_b32_e32 v123, v203
	v_pk_add_f32 v[118:119], v[118:119], v[122:123]
	v_pk_add_f32 v[116:117], v[116:117], v[120:121]
	v_cvt_pk_bf16_f32 v121, v118, v119
	v_cvt_pk_bf16_f32 v120, v116, v117
	global_store_dwordx4 v[160:161], v[116:119], off offset:512
	global_store_dwordx2 v[174:175], v[120:121], off offset:256
	s_nop 1
	v_mov_b32_e32 v162, v204
	v_mov_b32_e32 v163, v205
	v_mov_b32_e32 v164, v206
	v_mov_b32_e32 v165, v207
	v_and_b32_e32 v121, 64, v189
	v_xor_b32_e32 v120, 16, v189
	v_add_u32_e32 v121, 64, v121
	v_cmp_lt_i32_e32 vcc, v120, v121
	v_mul_f32_e32 v117, v117, v117
	v_mul_f32_e32 v119, v119, v119
	v_cndmask_b32_e32 v120, v189, v120, vcc
	v_lshlrev_b32_e32 v122, 2, v120
	v_mul_f32_e32 v120, v125, v125
	v_mul_f32_e32 v125, v127, v127
	v_fmac_f32_e32 v120, v124, v124
	v_fmac_f32_e32 v125, v126, v126
	v_add_f32_e32 v120, v120, v125
	v_mul_f32_e32 v124, v171, v171
	v_mul_f32_e32 v125, v173, v173
	v_fmac_f32_e32 v124, v170, v170
	v_fmac_f32_e32 v125, v172, v172
	v_add_f32_e32 v124, v124, v125
	v_fmac_f32_e32 v117, v116, v116
	v_fmac_f32_e32 v119, v118, v118
	v_add_f32_e32 v120, v120, v124
	v_add_f32_e32 v116, v117, v119
	v_add_f32_e32 v120, v120, v116
	v_xor_b32_e32 v123, 32, v189
	v_cmp_lt_i32_e32 vcc, v123, v121
	v_pk_add_f32 v[118:119], v[114:115], v[164:165]
	v_pk_add_f32 v[116:117], v[112:113], v[162:163]
	v_mul_f32_e32 v113, v119, v119
	v_mul_f32_e32 v112, v117, v117
	v_fmac_f32_e32 v112, v116, v116
	v_fmac_f32_e32 v113, v118, v118
	v_add_f32_e32 v112, v112, v113
	v_add_f32_e32 v112, v120, v112
	ds_bpermute_b32 v113, v122, v112
	v_cndmask_b32_e32 v114, v189, v123, vcc
	v_lshlrev_b32_e32 v123, 2, v114
	global_store_dwordx4 v[160:161], v[116:119], off offset:576
	s_waitcnt lgkmcnt(0)
	v_add_f32_e32 v114, v112, v113
	ds_bpermute_b32 v115, v123, v114
	v_cvt_pk_bf16_f32 v112, v116, v117
	v_cvt_pk_bf16_f32 v113, v118, v119
	global_store_dwordx2 v[174:175], v[112:113], off offset:288
	v_lshl_add_u64 v[112:113], v[158:159], 2, s[2:3]
	s_and_saveexec_b64 s[30:31], s[40:41]
	s_cbranch_execz .LBB0_150
	s_waitcnt lgkmcnt(0)
	v_add_f32_e32 v114, v114, v115
	global_atomic_add_f32 v[112:113], v114, off

; __device__ __forceinline__ unsigned cvt_pk_bf16(float lo, float hi) { const f32x2_cv v = {lo, hi}; const bf16x2_cv b = __builtin_convertvector(v, bf16x2_cv); return __builtin_bit_cast(unsigned, b); }
;     __device__ __forceinline__ void operator()(const f32x4 (&acc)[2][2][4][2], const pg8::Unit& u, int wr, int wc, int fr, int fq) const {
;     ...
;         for (int ai = 0; ai < 2; ++ai)
; #pragma unroll
;             for (int m = 0; m < 4; ++m) {
;                 const int row = row0 + ai * 128 + m * 16;
;                 float* xp = X + (size_t)row * 1024 + col0; bf16_t* bp = XB + (size_t)row * 1024 + col0;
;                 const float* xi = Xp0 ? (row < T_P ? Xp0 + (size_t)row * 1024 + col0 : Xs0 + (size_t)(row - T_P) * 1024 + col0) : xp;
;                 float ss = 0.f;
; #pragma unroll
;                 for (int bj = 0; bj < 2; ++bj)
; #pragma unroll
;                     for (int n = 0; n < 2; ++n) {
;                         f32x4 xv = *(const f32x4*)(xi + bj * 128 + n * 16) + acc[ai][bj][m][n];
;                         *(f32x4*)(xp + bj * 128 + n * 16) = xv;
;                         ss += (xv[0] * xv[0] + xv[1] * xv[1]) + (xv[2] * xv[2] + xv[3] * xv[3]);
;                         u32x2 w; w.x = cvt_pk_bf16(xv[0], xv[1]); w.y = cvt_pk_bf16(xv[2], xv[3]);
;                         *(u32x2*)(bp + bj * 128 + n * 16) = w; }
;                 ss += __shfl_xor(ss, 16); ss += __shfl_xor(ss, 32);
;                 if (fq == 0) atomicAdd(rowss_out + row, ss); }
.LBB0_156:
	v_add_co_u32_e32 v224, vcc, 0x10000, v116
	s_nop 1
	v_addc_co_u32_e32 v225, vcc, 0, v117, vcc
	global_load_dwordx4 v[192:195], v[224:225], off
	global_load_dwordx4 v[196:199], v[224:225], off offset:64
	global_load_dwordx4 v[200:203], v[224:225], off offset:512
	global_load_dwordx4 v[204:207], v[224:225], off offset:576
	v_lshl_add_u64 v[118:119], v[118:119], 1, s[6:7]
	v_lshl_add_u64 v[160:161], v[156:157], 1, v[118:119]
	s_waitcnt vmcnt(12)
	v_mov_b32_e32 v124, v208
	v_mov_b32_e32 v125, v209
	v_mov_b32_e32 v126, v210
	v_mov_b32_e32 v127, v211
	v_pk_add_f32 v[110:111], v[110:111], v[126:127]
	v_pk_add_f32 v[108:109], v[108:109], v[124:125]
	v_cvt_pk_bf16_f32 v119, v110, v111
	v_cvt_pk_bf16_f32 v118, v108, v109
	global_store_dwordx4 v[114:115], v[108:111], off
	global_store_dwordx2 v[160:161], v[118:119], off
	s_nop 1
	v_mov_b32_e32 v118, v212
	v_mov_b32_e32 v119, v213
	v_mov_b32_e32 v120, v214
	v_mov_b32_e32 v121, v215
	v_mul_f32_e32 v109, v109, v109
	v_mul_f32_e32 v111, v111, v111
	v_fmac_f32_e32 v109, v108, v108
	v_fmac_f32_e32 v111, v110, v110
	v_add_f32_e32 v108, v109, v111
	v_pk_add_f32 v[106:107], v[106:107], v[120:121]
	v_pk_add_f32 v[104:105], v[104:105], v[118:119]
	v_cvt_pk_bf16_f32 v119, v106, v107
	v_cvt_pk_bf16_f32 v118, v104, v105
	global_store_dwordx4 v[114:115], v[104:107], off offset:64
	global_store_dwordx2 v[160:161], v[118:119], off offset:32
	s_nop 1
	v_mov_b32_e32 v118, v216
	v_mov_b32_e32 v119, v217
	v_mov_b32_e32 v120, v218
	v_mov_b32_e32 v121, v219
	v_mul_f32_e32 v105, v105, v105
	v_mul_f32_e32 v107, v107, v107
	v_fmac_f32_e32 v105, v104, v104
	v_fmac_f32_e32 v107, v106, v106
	v_add_f32_e32 v104, v105, v107
	v_add_f32_e32 v104, v108, v104
	v_pk_add_f32 v[102:103], v[102:103], v[120:121]
	v_pk_add_f32 v[100:101], v[100:101], v[118:119]
	v_cvt_pk_bf16_f32 v119, v102, v103
	v_cvt_pk_bf16_f32 v118, v100, v101
	global_store_dwordx4 v[114:115], v[100:103], off offset:512
	global_store_dwordx2 v[160:161], v[118:119], off offset:256
	s_nop 1
	v_mov_b32_e32 v116, v220
	v_mov_b32_e32 v117, v221
	v_mov_b32_e32 v118, v222
	v_mov_b32_e32 v119, v223
	v_mul_f32_e32 v101, v101, v101
	v_mul_f32_e32 v103, v103, v103
	v_fmac_f32_e32 v101, v100, v100
	v_fmac_f32_e32 v103, v102, v102
	v_add_f32_e32 v100, v101, v103
	v_add_f32_e32 v102, v104, v100
	v_pk_add_f32 v[100:101], v[98:99], v[118:119]
	v_pk_add_f32 v[98:99], v[96:97], v[116:117]
	v_mul_f32_e32 v97, v101, v101
	v_mul_f32_e32 v96, v99, v99
	v_fmac_f32_e32 v96, v98, v98
	v_fmac_f32_e32 v97, v100, v100
	v_add_f32_e32 v96, v96, v97
	v_add_f32_e32 v96, v102, v96
	ds_bpermute_b32 v97, v122, v96
	global_store_dwordx4 v[114:115], v[98:101], off offset:576
	s_waitcnt lgkmcnt(0)
	v_add_f32_e32 v96, v96, v97
	ds_bpermute_b32 v97, v123, v96
	v_cvt_pk_bf16_f32 v98, v98, v99
	v_cvt_pk_bf16_f32 v99, v100, v101
	global_store_dwordx2 v[160:161], v[98:99], off offset:288
	s_and_saveexec_b64 s[30:31], s[40:41]
	s_cbranch_execz .LBB0_158
	s_waitcnt lgkmcnt(0)
	v_add_f32_e32 v96, v96, v97
	global_atomic_add_f32 v[112:113], v96, off offset:64

; __device__ __forceinline__ unsigned cvt_pk_bf16(float lo, float hi) { const f32x2_cv v = {lo, hi}; const bf16x2_cv b = __builtin_convertvector(v, bf16x2_cv); return __builtin_bit_cast(unsigned, b); }
;     __device__ __forceinline__ void operator()(const f32x4 (&acc)[2][2][4][2], const pg8::Unit& u, int wr, int wc, int fr, int fq) const {
;     ...
;         for (int ai = 0; ai < 2; ++ai)
; #pragma unroll
;             for (int m = 0; m < 4; ++m) {
;                 const int row = row0 + ai * 128 + m * 16;
;                 float* xp = X + (size_t)row * 1024 + col0; bf16_t* bp = XB + (size_t)row * 1024 + col0;
;                 const float* xi = Xp0 ? (row < T_P ? Xp0 + (size_t)row * 1024 + col0 : Xs0 + (size_t)(row - T_P) * 1024 + col0) : xp;
;                 float ss = 0.f;
; #pragma unroll
;                 for (int bj = 0; bj < 2; ++bj)
; #pragma unroll
;                     for (int n = 0; n < 2; ++n) {
;                         f32x4 xv = *(const f32x4*)(xi + bj * 128 + n * 16) + acc[ai][bj][m][n];
;                         *(f32x4*)(xp + bj * 128 + n * 16) = xv;
;                         ss += (xv[0] * xv[0] + xv[1] * xv[1]) + (xv[2] * xv[2] + xv[3] * xv[3]);
;                         u32x2 w; w.x = cvt_pk_bf16(xv[0], xv[1]); w.y = cvt_pk_bf16(xv[2], xv[3]);
;                         *(u32x2*)(bp + bj * 128 + n * 16) = w; }
;                 ss += __shfl_xor(ss, 16); ss += __shfl_xor(ss, 32);
;                 if (fq == 0) atomicAdd(rowss_out + row, ss); }
.LBB0_164:
	v_add_co_u32_e32 v224, vcc, 0x10000, v98
	s_nop 1
	v_addc_co_u32_e32 v225, vcc, 0, v99, vcc
	global_load_dwordx4 v[208:211], v[224:225], off
	global_load_dwordx4 v[212:215], v[224:225], off offset:64
	global_load_dwordx4 v[216:219], v[224:225], off offset:512
	global_load_dwordx4 v[220:223], v[224:225], off offset:576
	v_lshl_add_u64 v[100:101], v[100:101], 1, s[6:7]
	v_lshl_add_u64 v[106:107], v[156:157], 1, v[100:101]
	s_waitcnt vmcnt(12)
	v_mov_b32_e32 v102, v192
	v_mov_b32_e32 v103, v193
	v_mov_b32_e32 v104, v194
	v_mov_b32_e32 v105, v195
	v_pk_add_f32 v[94:95], v[94:95], v[104:105]
	v_pk_add_f32 v[92:93], v[92:93], v[102:103]
	v_cvt_pk_bf16_f32 v101, v94, v95
	v_cvt_pk_bf16_f32 v100, v92, v93
	global_store_dwordx4 v[96:97], v[92:95], off
	global_store_dwordx2 v[106:107], v[100:101], off
	s_nop 1
	v_mov_b32_e32 v100, v196
	v_mov_b32_e32 v101, v197
	v_mov_b32_e32 v102, v198
	v_mov_b32_e32 v103, v199
	v_mul_f32_e32 v93, v93, v93
	v_mul_f32_e32 v95, v95, v95
	v_fmac_f32_e32 v93, v92, v92
	v_fmac_f32_e32 v95, v94, v94
	v_add_f32_e32 v92, v93, v95
	v_pk_add_f32 v[90:91], v[90:91], v[102:103]
	v_pk_add_f32 v[88:89], v[88:89], v[100:101]
	v_cvt_pk_bf16_f32 v101, v90, v91
	v_cvt_pk_bf16_f32 v100, v88, v89
	global_store_dwordx4 v[96:97], v[88:91], off offset:64
	global_store_dwordx2 v[106:107], v[100:101], off offset:32
	s_nop 1
	v_mov_b32_e32 v100, v200
	v_mov_b32_e32 v101, v201
	v_mov_b32_e32 v102, v202
	v_mov_b32_e32 v103, v203
	v_mul_f32_e32 v89, v89, v89
	v_mul_f32_e32 v91, v91, v91
	v_fmac_f32_e32 v89, v88, v88
	v_fmac_f32_e32 v91, v90, v90
	v_add_f32_e32 v88, v89, v91
	v_add_f32_e32 v88, v92, v88
	v_pk_add_f32 v[86:87], v[86:87], v[102:103]
	v_pk_add_f32 v[84:85], v[84:85], v[100:101]
	v_cvt_pk_bf16_f32 v101, v86, v87
	v_cvt_pk_bf16_f32 v100, v84, v85
	global_store_dwordx4 v[96:97], v[84:87], off offset:512
	global_store_dwordx2 v[106:107], v[100:101], off offset:256
	s_nop 1
	v_mov_b32_e32 v98, v204
	v_mov_b32_e32 v99, v205
	v_mov_b32_e32 v100, v206
	v_mov_b32_e32 v101, v207
	v_mul_f32_e32 v85, v85, v85
	v_mul_f32_e32 v87, v87, v87
	v_fmac_f32_e32 v85, v84, v84
	v_fmac_f32_e32 v87, v86, v86
	v_add_f32_e32 v84, v85, v87
	v_add_f32_e32 v86, v88, v84
	v_pk_add_f32 v[84:85], v[82:83], v[100:101]
	v_pk_add_f32 v[82:83], v[80:81], v[98:99]
	v_mul_f32_e32 v81, v85, v85
	v_mul_f32_e32 v80, v83, v83
	v_fmac_f32_e32 v80, v82, v82
	v_fmac_f32_e32 v81, v84, v84
	v_add_f32_e32 v80, v80, v81
	v_add_f32_e32 v80, v86, v80
	ds_bpermute_b32 v81, v122, v80
	global_store_dwordx4 v[96:97], v[82:85], off offset:576
	s_waitcnt lgkmcnt(0)
	v_add_f32_e32 v80, v80, v81
	ds_bpermute_b32 v81, v123, v80
	v_cvt_pk_bf16_f32 v82, v82, v83
	v_cvt_pk_bf16_f32 v83, v84, v85
	global_store_dwordx2 v[106:107], v[82:83], off offset:288
	s_and_saveexec_b64 s[30:31], s[40:41]
	s_cbranch_execz .LBB0_166
	s_waitcnt lgkmcnt(0)
	v_add_f32_e32 v80, v80, v81
	global_atomic_add_f32 v[112:113], v80, off offset:128

; __device__ __forceinline__ unsigned cvt_pk_bf16(float lo, float hi) { const f32x2_cv v = {lo, hi}; const bf16x2_cv b = __builtin_convertvector(v, bf16x2_cv); return __builtin_bit_cast(unsigned, b); }
;     __device__ __forceinline__ void operator()(const f32x4 (&acc)[2][2][4][2], const pg8::Unit& u, int wr, int wc, int fr, int fq) const {
;     ...
;         for (int ai = 0; ai < 2; ++ai)
; #pragma unroll
;             for (int m = 0; m < 4; ++m) {
;                 const int row = row0 + ai * 128 + m * 16;
;                 float* xp = X + (size_t)row * 1024 + col0; bf16_t* bp = XB + (size_t)row * 1024 + col0;
;                 const float* xi = Xp0 ? (row < T_P ? Xp0 + (size_t)row * 1024 + col0 : Xs0 + (size_t)(row - T_P) * 1024 + col0) : xp;
;                 float ss = 0.f;
; #pragma unroll
;                 for (int bj = 0; bj < 2; ++bj)
; #pragma unroll
;                     for (int n = 0; n < 2; ++n) {
;                         f32x4 xv = *(const f32x4*)(xi + bj * 128 + n * 16) + acc[ai][bj][m][n];
;                         *(f32x4*)(xp + bj * 128 + n * 16) = xv;
;                         ss += (xv[0] * xv[0] + xv[1] * xv[1]) + (xv[2] * xv[2] + xv[3] * xv[3]);
;                         u32x2 w; w.x = cvt_pk_bf16(xv[0], xv[1]); w.y = cvt_pk_bf16(xv[2], xv[3]);
;                         *(u32x2*)(bp + bj * 128 + n * 16) = w; }
;                 ss += __shfl_xor(ss, 16); ss += __shfl_xor(ss, 32);
;                 if (fq == 0) atomicAdd(rowss_out + row, ss); }
.LBB0_172:
	v_add_co_u32_e32 v224, vcc, 0x50000, v82
	s_nop 1
	v_addc_co_u32_e32 v225, vcc, 0, v83, vcc
	global_load_dwordx4 v[192:195], v[224:225], off
	global_load_dwordx4 v[196:199], v[224:225], off offset:64
	global_load_dwordx4 v[200:203], v[224:225], off offset:512
	global_load_dwordx4 v[204:207], v[224:225], off offset:576
	v_lshl_add_u64 v[84:85], v[84:85], 1, s[6:7]
	v_lshl_add_u64 v[90:91], v[156:157], 1, v[84:85]
	s_waitcnt vmcnt(12)
	v_mov_b32_e32 v86, v208
	v_mov_b32_e32 v87, v209
	v_mov_b32_e32 v88, v210
	v_mov_b32_e32 v89, v211
	v_pk_add_f32 v[78:79], v[78:79], v[88:89]
	v_pk_add_f32 v[76:77], v[76:77], v[86:87]
	v_cvt_pk_bf16_f32 v85, v78, v79
	v_cvt_pk_bf16_f32 v84, v76, v77
	global_store_dwordx4 v[80:81], v[76:79], off
	global_store_dwordx2 v[90:91], v[84:85], off
	s_nop 1
	v_mov_b32_e32 v84, v212
	v_mov_b32_e32 v85, v213
	v_mov_b32_e32 v86, v214
	v_mov_b32_e32 v87, v215
	v_mul_f32_e32 v77, v77, v77
	v_mul_f32_e32 v79, v79, v79
	v_fmac_f32_e32 v77, v76, v76
	v_fmac_f32_e32 v79, v78, v78
	v_add_f32_e32 v76, v77, v79
	v_pk_add_f32 v[74:75], v[74:75], v[86:87]
	v_pk_add_f32 v[72:73], v[72:73], v[84:85]
	v_cvt_pk_bf16_f32 v85, v74, v75
	v_cvt_pk_bf16_f32 v84, v72, v73
	global_store_dwordx4 v[80:81], v[72:75], off offset:64
	global_store_dwordx2 v[90:91], v[84:85], off offset:32
	s_nop 1
	v_mov_b32_e32 v84, v216
	v_mov_b32_e32 v85, v217
	v_mov_b32_e32 v86, v218
	v_mov_b32_e32 v87, v219
	v_mul_f32_e32 v73, v73, v73
	v_mul_f32_e32 v75, v75, v75
	v_fmac_f32_e32 v73, v72, v72
	v_fmac_f32_e32 v75, v74, v74
	v_add_f32_e32 v72, v73, v75
	v_add_f32_e32 v72, v76, v72
	v_pk_add_f32 v[70:71], v[70:71], v[86:87]
	v_pk_add_f32 v[68:69], v[68:69], v[84:85]
	v_cvt_pk_bf16_f32 v85, v70, v71
	v_cvt_pk_bf16_f32 v84, v68, v69
	global_store_dwordx4 v[80:81], v[68:71], off offset:512
	global_store_dwordx2 v[90:91], v[84:85], off offset:256
	s_nop 1
	v_mov_b32_e32 v82, v220
	v_mov_b32_e32 v83, v221
	v_mov_b32_e32 v84, v222
	v_mov_b32_e32 v85, v223
	v_mul_f32_e32 v69, v69, v69
	v_mul_f32_e32 v71, v71, v71
	v_fmac_f32_e32 v69, v68, v68
	v_fmac_f32_e32 v71, v70, v70
	v_add_f32_e32 v68, v69, v71
	v_add_f32_e32 v70, v72, v68
	v_pk_add_f32 v[68:69], v[66:67], v[84:85]
	v_pk_add_f32 v[66:67], v[64:65], v[82:83]
	v_mul_f32_e32 v65, v69, v69
	v_mul_f32_e32 v64, v67, v67
	v_fmac_f32_e32 v64, v66, v66
	v_fmac_f32_e32 v65, v68, v68
	v_add_f32_e32 v64, v64, v65
	v_add_f32_e32 v64, v70, v64
	ds_bpermute_b32 v65, v122, v64
	global_store_dwordx4 v[80:81], v[66:69], off offset:576
	s_waitcnt lgkmcnt(0)
	v_add_f32_e32 v64, v64, v65
	ds_bpermute_b32 v65, v123, v64
	v_cvt_pk_bf16_f32 v66, v66, v67
	v_cvt_pk_bf16_f32 v67, v68, v69
	global_store_dwordx2 v[90:91], v[66:67], off offset:288
	s_and_saveexec_b64 s[30:31], s[40:41]
	s_cbranch_execz .LBB0_174
	s_waitcnt lgkmcnt(0)
	v_add_f32_e32 v64, v64, v65
	global_atomic_add_f32 v[112:113], v64, off offset:192

; __device__ __forceinline__ unsigned cvt_pk_bf16(float lo, float hi) { const f32x2_cv v = {lo, hi}; const bf16x2_cv b = __builtin_convertvector(v, bf16x2_cv); return __builtin_bit_cast(unsigned, b); }
;     __device__ __forceinline__ void operator()(const f32x4 (&acc)[2][2][4][2], const pg8::Unit& u, int wr, int wc, int fr, int fq) const {
;     ...
;         for (int ai = 0; ai < 2; ++ai)
; #pragma unroll
;             for (int m = 0; m < 4; ++m) {
;                 const int row = row0 + ai * 128 + m * 16;
;                 float* xp = X + (size_t)row * 1024 + col0; bf16_t* bp = XB + (size_t)row * 1024 + col0;
;                 const float* xi = Xp0 ? (row < T_P ? Xp0 + (size_t)row * 1024 + col0 : Xs0 + (size_t)(row - T_P) * 1024 + col0) : xp;
;                 float ss = 0.f;
; #pragma unroll
;                 for (int bj = 0; bj < 2; ++bj)
; #pragma unroll
;                     for (int n = 0; n < 2; ++n) {
;                         f32x4 xv = *(const f32x4*)(xi + bj * 128 + n * 16) + acc[ai][bj][m][n];
;                         *(f32x4*)(xp + bj * 128 + n * 16) = xv;
;                         ss += (xv[0] * xv[0] + xv[1] * xv[1]) + (xv[2] * xv[2] + xv[3] * xv[3]);
;                         u32x2 w; w.x = cvt_pk_bf16(xv[0], xv[1]); w.y = cvt_pk_bf16(xv[2], xv[3]);
;                         *(u32x2*)(bp + bj * 128 + n * 16) = w; }
;                 ss += __shfl_xor(ss, 16); ss += __shfl_xor(ss, 32);
;                 if (fq == 0) atomicAdd(rowss_out + row, ss); }
.LBB0_180:
	v_add_co_u32_e32 v224, vcc, 0x10000, v66
	s_nop 1
	v_addc_co_u32_e32 v225, vcc, 0, v67, vcc
	global_load_dwordx4 v[208:211], v[224:225], off
	global_load_dwordx4 v[212:215], v[224:225], off offset:64
	global_load_dwordx4 v[216:219], v[224:225], off offset:512
	global_load_dwordx4 v[220:223], v[224:225], off offset:576
	v_lshl_add_u64 v[68:69], v[68:69], 1, s[6:7]
	v_lshl_add_u64 v[74:75], v[156:157], 1, v[68:69]
	s_waitcnt vmcnt(12)
	v_mov_b32_e32 v70, v192
	v_mov_b32_e32 v71, v193
	v_mov_b32_e32 v72, v194
	v_mov_b32_e32 v73, v195
	v_pk_add_f32 v[62:63], v[62:63], v[72:73]
	v_pk_add_f32 v[60:61], v[60:61], v[70:71]
	v_cvt_pk_bf16_f32 v69, v62, v63
	v_cvt_pk_bf16_f32 v68, v60, v61
	global_store_dwordx4 v[64:65], v[60:63], off
	global_store_dwordx2 v[74:75], v[68:69], off
	s_nop 1
	v_mov_b32_e32 v68, v196
	v_mov_b32_e32 v69, v197
	v_mov_b32_e32 v70, v198
	v_mov_b32_e32 v71, v199
	v_mul_f32_e32 v61, v61, v61
	v_mul_f32_e32 v63, v63, v63
	v_fmac_f32_e32 v61, v60, v60
	v_fmac_f32_e32 v63, v62, v62
	v_add_f32_e32 v60, v61, v63
	v_pk_add_f32 v[58:59], v[58:59], v[70:71]
	v_pk_add_f32 v[56:57], v[56:57], v[68:69]
	v_cvt_pk_bf16_f32 v69, v58, v59
	v_cvt_pk_bf16_f32 v68, v56, v57
	global_store_dwordx4 v[64:65], v[56:59], off offset:64
	global_store_dwordx2 v[74:75], v[68:69], off offset:32
	s_nop 1
	v_mov_b32_e32 v68, v200
	v_mov_b32_e32 v69, v201
	v_mov_b32_e32 v70, v202
	v_mov_b32_e32 v71, v203
	v_mul_f32_e32 v57, v57, v57
	v_mul_f32_e32 v59, v59, v59
	v_fmac_f32_e32 v57, v56, v56
	v_fmac_f32_e32 v59, v58, v58
	v_add_f32_e32 v56, v57, v59
	v_add_f32_e32 v56, v60, v56
	v_pk_add_f32 v[54:55], v[54:55], v[70:71]
	v_pk_add_f32 v[52:53], v[52:53], v[68:69]
	v_cvt_pk_bf16_f32 v69, v54, v55
	v_cvt_pk_bf16_f32 v68, v52, v53
	global_store_dwordx4 v[64:65], v[52:55], off offset:512
	global_store_dwordx2 v[74:75], v[68:69], off offset:256
	s_nop 1
	v_mov_b32_e32 v66, v204
	v_mov_b32_e32 v67, v205
	v_mov_b32_e32 v68, v206
	v_mov_b32_e32 v69, v207
	v_mul_f32_e32 v53, v53, v53
	v_mul_f32_e32 v55, v55, v55
	v_fmac_f32_e32 v53, v52, v52
	v_fmac_f32_e32 v55, v54, v54
	v_add_f32_e32 v52, v53, v55
	v_add_f32_e32 v54, v56, v52
	v_pk_add_f32 v[52:53], v[50:51], v[68:69]
	v_pk_add_f32 v[50:51], v[48:49], v[66:67]
	v_mul_f32_e32 v49, v53, v53
	v_mul_f32_e32 v48, v51, v51
	v_fmac_f32_e32 v48, v50, v50
	v_fmac_f32_e32 v49, v52, v52
	v_add_f32_e32 v48, v48, v49
	v_add_f32_e32 v48, v54, v48
	ds_bpermute_b32 v49, v122, v48
	global_store_dwordx4 v[64:65], v[50:53], off offset:576
	s_waitcnt lgkmcnt(0)
	v_add_f32_e32 v48, v48, v49
	ds_bpermute_b32 v49, v123, v48
	v_cvt_pk_bf16_f32 v50, v50, v51
	v_cvt_pk_bf16_f32 v51, v52, v53
	global_store_dwordx2 v[74:75], v[50:51], off offset:288
	s_and_saveexec_b64 s[30:31], s[40:41]
	s_cbranch_execz .LBB0_182
	s_waitcnt lgkmcnt(0)
	v_add_f32_e32 v48, v48, v49
	global_atomic_add_f32 v[112:113], v48, off offset:512

; __device__ __forceinline__ unsigned cvt_pk_bf16(float lo, float hi) { const f32x2_cv v = {lo, hi}; const bf16x2_cv b = __builtin_convertvector(v, bf16x2_cv); return __builtin_bit_cast(unsigned, b); }
;     __device__ __forceinline__ void operator()(const f32x4 (&acc)[2][2][4][2], const pg8::Unit& u, int wr, int wc, int fr, int fq) const {
;     ...
;         for (int ai = 0; ai < 2; ++ai)
; #pragma unroll
;             for (int m = 0; m < 4; ++m) {
;                 const int row = row0 + ai * 128 + m * 16;
;                 float* xp = X + (size_t)row * 1024 + col0; bf16_t* bp = XB + (size_t)row * 1024 + col0;
;                 const float* xi = Xp0 ? (row < T_P ? Xp0 + (size_t)row * 1024 + col0 : Xs0 + (size_t)(row - T_P) * 1024 + col0) : xp;
;                 float ss = 0.f;
; #pragma unroll
;                 for (int bj = 0; bj < 2; ++bj)
; #pragma unroll
;                     for (int n = 0; n < 2; ++n) {
;                         f32x4 xv = *(const f32x4*)(xi + bj * 128 + n * 16) + acc[ai][bj][m][n];
;                         *(f32x4*)(xp + bj * 128 + n * 16) = xv;
;                         ss += (xv[0] * xv[0] + xv[1] * xv[1]) + (xv[2] * xv[2] + xv[3] * xv[3]);
;                         u32x2 w; w.x = cvt_pk_bf16(xv[0], xv[1]); w.y = cvt_pk_bf16(xv[2], xv[3]);
;                         *(u32x2*)(bp + bj * 128 + n * 16) = w; }
;                 ss += __shfl_xor(ss, 16); ss += __shfl_xor(ss, 32);
;                 if (fq == 0) atomicAdd(rowss_out + row, ss); }
.LBB0_188:
	v_add_co_u32_e32 v224, vcc, 0x10000, v50
	s_nop 1
	v_addc_co_u32_e32 v225, vcc, 0, v51, vcc
	global_load_dwordx4 v[192:195], v[224:225], off
	global_load_dwordx4 v[196:199], v[224:225], off offset:64
	global_load_dwordx4 v[200:203], v[224:225], off offset:512
	global_load_dwordx4 v[204:207], v[224:225], off offset:576
	v_lshl_add_u64 v[52:53], v[52:53], 1, s[6:7]
	v_lshl_add_u64 v[58:59], v[156:157], 1, v[52:53]
	s_waitcnt vmcnt(12)
	v_mov_b32_e32 v54, v208
	v_mov_b32_e32 v55, v209
	v_mov_b32_e32 v56, v210
	v_mov_b32_e32 v57, v211
	v_pk_add_f32 v[46:47], v[46:47], v[56:57]
	v_pk_add_f32 v[44:45], v[44:45], v[54:55]
	v_cvt_pk_bf16_f32 v53, v46, v47
	v_cvt_pk_bf16_f32 v52, v44, v45
	global_store_dwordx4 v[48:49], v[44:47], off
	global_store_dwordx2 v[58:59], v[52:53], off
	s_nop 1
	v_mov_b32_e32 v52, v212
	v_mov_b32_e32 v53, v213
	v_mov_b32_e32 v54, v214
	v_mov_b32_e32 v55, v215
	v_mul_f32_e32 v45, v45, v45
	v_mul_f32_e32 v47, v47, v47
	v_fmac_f32_e32 v45, v44, v44
	v_fmac_f32_e32 v47, v46, v46
	v_add_f32_e32 v44, v45, v47
	v_pk_add_f32 v[42:43], v[42:43], v[54:55]
	v_pk_add_f32 v[40:41], v[40:41], v[52:53]
	v_cvt_pk_bf16_f32 v53, v42, v43
	v_cvt_pk_bf16_f32 v52, v40, v41
	global_store_dwordx4 v[48:49], v[40:43], off offset:64
	global_store_dwordx2 v[58:59], v[52:53], off offset:32
	s_nop 1
	v_mov_b32_e32 v52, v216
	v_mov_b32_e32 v53, v217
	v_mov_b32_e32 v54, v218
	v_mov_b32_e32 v55, v219
	v_mul_f32_e32 v41, v41, v41
	v_mul_f32_e32 v43, v43, v43
	v_fmac_f32_e32 v41, v40, v40
	v_fmac_f32_e32 v43, v42, v42
	v_add_f32_e32 v40, v41, v43
	v_add_f32_e32 v40, v44, v40
	v_pk_add_f32 v[38:39], v[38:39], v[54:55]
	v_pk_add_f32 v[36:37], v[36:37], v[52:53]
	v_cvt_pk_bf16_f32 v53, v38, v39
	v_cvt_pk_bf16_f32 v52, v36, v37
	global_store_dwordx4 v[48:49], v[36:39], off offset:512
	global_store_dwordx2 v[58:59], v[52:53], off offset:256
	s_nop 1
	v_mov_b32_e32 v50, v220
	v_mov_b32_e32 v51, v221
	v_mov_b32_e32 v52, v222
	v_mov_b32_e32 v53, v223
	v_mul_f32_e32 v37, v37, v37
	v_mul_f32_e32 v39, v39, v39
	v_fmac_f32_e32 v37, v36, v36
	v_fmac_f32_e32 v39, v38, v38
	v_add_f32_e32 v36, v37, v39
	v_add_f32_e32 v38, v40, v36
	v_pk_add_f32 v[36:37], v[34:35], v[52:53]
	v_pk_add_f32 v[34:35], v[32:33], v[50:51]
	v_mul_f32_e32 v33, v37, v37
	v_mul_f32_e32 v32, v35, v35
	v_fmac_f32_e32 v32, v34, v34
	v_fmac_f32_e32 v33, v36, v36
	v_add_f32_e32 v32, v32, v33
	v_add_f32_e32 v32, v38, v32
	ds_bpermute_b32 v33, v122, v32
	global_store_dwordx4 v[48:49], v[34:37], off offset:576
	s_waitcnt lgkmcnt(0)
	v_add_f32_e32 v32, v32, v33
	ds_bpermute_b32 v33, v123, v32
	v_cvt_pk_bf16_f32 v34, v34, v35
	v_cvt_pk_bf16_f32 v35, v36, v37
	global_store_dwordx2 v[58:59], v[34:35], off offset:288
	s_and_saveexec_b64 s[30:31], s[40:41]
	s_cbranch_execz .LBB0_190
	s_waitcnt lgkmcnt(0)
	v_add_f32_e32 v32, v32, v33
	global_atomic_add_f32 v[112:113], v32, off offset:576

; __device__ __forceinline__ unsigned cvt_pk_bf16(float lo, float hi) { const f32x2_cv v = {lo, hi}; const bf16x2_cv b = __builtin_convertvector(v, bf16x2_cv); return __builtin_bit_cast(unsigned, b); }
;     __device__ __forceinline__ void operator()(const f32x4 (&acc)[2][2][4][2], const pg8::Unit& u, int wr, int wc, int fr, int fq) const {
;     ...
;         for (int ai = 0; ai < 2; ++ai)
; #pragma unroll
;             for (int m = 0; m < 4; ++m) {
;                 const int row = row0 + ai * 128 + m * 16;
;                 float* xp = X + (size_t)row * 1024 + col0; bf16_t* bp = XB + (size_t)row * 1024 + col0;
;                 const float* xi = Xp0 ? (row < T_P ? Xp0 + (size_t)row * 1024 + col0 : Xs0 + (size_t)(row - T_P) * 1024 + col0) : xp;
;                 float ss = 0.f;
; #pragma unroll
;                 for (int bj = 0; bj < 2; ++bj)
; #pragma unroll
;                     for (int n = 0; n < 2; ++n) {
;                         f32x4 xv = *(const f32x4*)(xi + bj * 128 + n * 16) + acc[ai][bj][m][n];
;                         *(f32x4*)(xp + bj * 128 + n * 16) = xv;
;                         ss += (xv[0] * xv[0] + xv[1] * xv[1]) + (xv[2] * xv[2] + xv[3] * xv[3]);
;                         u32x2 w; w.x = cvt_pk_bf16(xv[0], xv[1]); w.y = cvt_pk_bf16(xv[2], xv[3]);
;                         *(u32x2*)(bp + bj * 128 + n * 16) = w; }
;                 ss += __shfl_xor(ss, 16); ss += __shfl_xor(ss, 32);
;                 if (fq == 0) atomicAdd(rowss_out + row, ss); }
.LBB0_196:
	v_add_co_u32_e32 v224, vcc, 0x10000, v34
	s_nop 1
	v_addc_co_u32_e32 v225, vcc, 0, v35, vcc
	global_load_dwordx4 v[208:211], v[224:225], off
	global_load_dwordx4 v[212:215], v[224:225], off offset:64
	global_load_dwordx4 v[216:219], v[224:225], off offset:512
	global_load_dwordx4 v[220:223], v[224:225], off offset:576
	v_lshl_add_u64 v[36:37], v[36:37], 1, s[6:7]
	v_lshl_add_u64 v[42:43], v[156:157], 1, v[36:37]
	s_waitcnt vmcnt(12)
	v_mov_b32_e32 v38, v192
	v_mov_b32_e32 v39, v193
	v_mov_b32_e32 v40, v194
	v_mov_b32_e32 v41, v195
	v_pk_add_f32 v[30:31], v[30:31], v[40:41]
	v_pk_add_f32 v[28:29], v[28:29], v[38:39]
	v_cvt_pk_bf16_f32 v37, v30, v31
	v_cvt_pk_bf16_f32 v36, v28, v29
	global_store_dwordx4 v[32:33], v[28:31], off
	global_store_dwordx2 v[42:43], v[36:37], off
	s_nop 1
	v_mov_b32_e32 v36, v196
	v_mov_b32_e32 v37, v197
	v_mov_b32_e32 v38, v198
	v_mov_b32_e32 v39, v199
	v_mul_f32_e32 v29, v29, v29
	v_mul_f32_e32 v31, v31, v31
	v_fmac_f32_e32 v29, v28, v28
	v_fmac_f32_e32 v31, v30, v30
	v_add_f32_e32 v28, v29, v31
	v_pk_add_f32 v[26:27], v[26:27], v[38:39]
	v_pk_add_f32 v[24:25], v[24:25], v[36:37]
	v_cvt_pk_bf16_f32 v37, v26, v27
	v_cvt_pk_bf16_f32 v36, v24, v25
	global_store_dwordx4 v[32:33], v[24:27], off offset:64
	global_store_dwordx2 v[42:43], v[36:37], off offset:32
	s_nop 1
	v_mov_b32_e32 v36, v200
	v_mov_b32_e32 v37, v201
	v_mov_b32_e32 v38, v202
	v_mov_b32_e32 v39, v203
	v_mul_f32_e32 v25, v25, v25
	v_mul_f32_e32 v27, v27, v27
	v_fmac_f32_e32 v25, v24, v24
	v_fmac_f32_e32 v27, v26, v26
	v_add_f32_e32 v24, v25, v27
	v_add_f32_e32 v24, v28, v24
	v_pk_add_f32 v[22:23], v[22:23], v[38:39]
	v_pk_add_f32 v[20:21], v[20:21], v[36:37]
	v_cvt_pk_bf16_f32 v37, v22, v23
	v_cvt_pk_bf16_f32 v36, v20, v21
	global_store_dwordx4 v[32:33], v[20:23], off offset:512
	global_store_dwordx2 v[42:43], v[36:37], off offset:256
	s_nop 1
	v_mov_b32_e32 v34, v204
	v_mov_b32_e32 v35, v205
	v_mov_b32_e32 v36, v206
	v_mov_b32_e32 v37, v207
	v_mul_f32_e32 v21, v21, v21
	v_mul_f32_e32 v23, v23, v23
	v_fmac_f32_e32 v21, v20, v20
	v_fmac_f32_e32 v23, v22, v22
	v_add_f32_e32 v20, v21, v23
	v_add_f32_e32 v22, v24, v20
	v_pk_add_f32 v[20:21], v[18:19], v[36:37]
	v_pk_add_f32 v[18:19], v[16:17], v[34:35]
	v_mul_f32_e32 v17, v21, v21
	v_mul_f32_e32 v16, v19, v19
	v_fmac_f32_e32 v16, v18, v18
	v_fmac_f32_e32 v17, v20, v20
	v_add_f32_e32 v16, v16, v17
	v_add_f32_e32 v16, v22, v16
	ds_bpermute_b32 v17, v122, v16
	global_store_dwordx4 v[32:33], v[18:21], off offset:576
	s_waitcnt lgkmcnt(0)
	v_add_f32_e32 v16, v16, v17
	ds_bpermute_b32 v17, v123, v16
	v_cvt_pk_bf16_f32 v18, v18, v19
	v_cvt_pk_bf16_f32 v19, v20, v21
	global_store_dwordx2 v[42:43], v[18:19], off offset:288
	s_and_saveexec_b64 s[30:31], s[40:41]
	s_cbranch_execz .LBB0_198
	s_waitcnt lgkmcnt(0)
	v_add_f32_e32 v16, v16, v17
	global_atomic_add_f32 v[112:113], v16, off offset:640

; __device__ __forceinline__ unsigned cvt_pk_bf16(float lo, float hi) { const f32x2_cv v = {lo, hi}; const bf16x2_cv b = __builtin_convertvector(v, bf16x2_cv); return __builtin_bit_cast(unsigned, b); }
;     __device__ __forceinline__ void operator()(const f32x4 (&acc)[2][2][4][2], const pg8::Unit& u, int wr, int wc, int fr, int fq) const {
;     ...
;         for (int ai = 0; ai < 2; ++ai)
; #pragma unroll
;             for (int m = 0; m < 4; ++m) {
;                 const int row = row0 + ai * 128 + m * 16;
;                 float* xp = X + (size_t)row * 1024 + col0; bf16_t* bp = XB + (size_t)row * 1024 + col0;
;                 const float* xi = Xp0 ? (row < T_P ? Xp0 + (size_t)row * 1024 + col0 : Xs0 + (size_t)(row - T_P) * 1024 + col0) : xp;
;                 float ss = 0.f;
; #pragma unroll
;                 for (int bj = 0; bj < 2; ++bj)
; #pragma unroll
;                     for (int n = 0; n < 2; ++n) {
;                         f32x4 xv = *(const f32x4*)(xi + bj * 128 + n * 16) + acc[ai][bj][m][n];
;                         *(f32x4*)(xp + bj * 128 + n * 16) = xv;
;                         ss += (xv[0] * xv[0] + xv[1] * xv[1]) + (xv[2] * xv[2] + xv[3] * xv[3]);
;                         u32x2 w; w.x = cvt_pk_bf16(xv[0], xv[1]); w.y = cvt_pk_bf16(xv[2], xv[3]);
;                         *(u32x2*)(bp + bj * 128 + n * 16) = w; }
;                 ss += __shfl_xor(ss, 16); ss += __shfl_xor(ss, 32);
;                 if (fq == 0) atomicAdd(rowss_out + row, ss); }
.LBB0_204:
	v_lshl_add_u64 v[18:19], v[18:19], 1, s[6:7]
	v_lshl_add_u64 v[18:19], v[156:157], 1, v[18:19]
	s_waitcnt vmcnt(8)
	v_mov_b32_e32 v22, v208
	v_mov_b32_e32 v23, v209
	v_mov_b32_e32 v24, v210
	v_mov_b32_e32 v25, v211
	v_pk_add_f32 v[12:13], v[12:13], v[22:23]
	v_pk_add_f32 v[14:15], v[14:15], v[24:25]
	v_mul_f32_e32 v22, v13, v13
	global_store_dwordx4 v[16:17], v[12:15], off
	v_fmac_f32_e32 v22, v12, v12
	v_mul_f32_e32 v23, v15, v15
	v_cvt_pk_bf16_f32 v12, v12, v13
	v_cvt_pk_bf16_f32 v13, v14, v15
	global_store_dwordx2 v[18:19], v[12:13], off
	v_fmac_f32_e32 v23, v14, v14
	s_nop 1
	v_mov_b32_e32 v12, v212
	v_mov_b32_e32 v13, v213
	v_mov_b32_e32 v14, v214
	v_mov_b32_e32 v15, v215
	v_add_f32_e32 v22, v22, v23
	v_pk_add_f32 v[8:9], v[8:9], v[12:13]
	v_pk_add_f32 v[10:11], v[10:11], v[14:15]
	v_mul_f32_e32 v12, v9, v9
	global_store_dwordx4 v[16:17], v[8:11], off offset:64
	v_fmac_f32_e32 v12, v8, v8
	v_mul_f32_e32 v13, v11, v11
	v_cvt_pk_bf16_f32 v8, v8, v9
	v_cvt_pk_bf16_f32 v9, v10, v11
	global_store_dwordx2 v[18:19], v[8:9], off offset:32
	v_fmac_f32_e32 v13, v10, v10
	s_nop 1
	v_mov_b32_e32 v8, v216
	v_mov_b32_e32 v9, v217
	v_mov_b32_e32 v10, v218
	v_mov_b32_e32 v11, v219
	v_add_f32_e32 v12, v12, v13
	v_add_f32_e32 v12, v22, v12
	v_pk_add_f32 v[4:5], v[4:5], v[8:9]
	v_pk_add_f32 v[6:7], v[6:7], v[10:11]
	v_mul_f32_e32 v8, v5, v5
	global_store_dwordx4 v[16:17], v[4:7], off offset:512
	v_fmac_f32_e32 v8, v4, v4
	v_mul_f32_e32 v9, v7, v7
	v_cvt_pk_bf16_f32 v4, v4, v5
	v_cvt_pk_bf16_f32 v5, v6, v7
	global_store_dwordx2 v[18:19], v[4:5], off offset:256
	v_fmac_f32_e32 v9, v6, v6
	s_nop 1
	v_mov_b32_e32 v4, v220
	v_mov_b32_e32 v5, v221
	v_mov_b32_e32 v6, v222
	v_mov_b32_e32 v7, v223
	v_add_f32_e32 v8, v8, v9
	v_add_f32_e32 v8, v12, v8
	v_pk_add_f32 v[2:3], v[2:3], v[6:7]
	v_pk_add_f32 v[0:1], v[0:1], v[4:5]
	v_mul_f32_e32 v5, v3, v3
	v_mul_f32_e32 v4, v1, v1
	v_fmac_f32_e32 v4, v0, v0
	v_fmac_f32_e32 v5, v2, v2
	v_add_f32_e32 v4, v4, v5
	global_store_dwordx4 v[16:17], v[0:3], off offset:576
	v_add_f32_e32 v4, v8, v4
	s_nop 0
	v_cvt_pk_bf16_f32 v0, v0, v1
	v_cvt_pk_bf16_f32 v1, v2, v3
	global_store_dwordx2 v[18:19], v[0:1], off offset:288
	ds_bpermute_b32 v0, v122, v4
	s_waitcnt lgkmcnt(0)
	v_add_f32_e32 v0, v4, v0
	ds_bpermute_b32 v1, v123, v0
	s_and_saveexec_b64 s[30:31], s[40:41]
	s_cbranch_execz .LBB0_133
	s_waitcnt lgkmcnt(0)
	v_add_f32_e32 v0, v0, v1
	global_atomic_add_f32 v[112:113], v0, off offset:704
	s_branch .LBB0_133

; #define PG8_STAGE(bufoff, gbase, voff) do { _Pragma("unroll") for (int _i = 0; _i < 2; ++_i) \
;         __builtin_amdgcn_global_load_lds((const unsigned*)((const char*)(gbase) + (voff)[_i]), (PG8_LAS unsigned*)(lds + (bufoff) + ldsw + _i * 8192), 16, 0, 0); } while (0)
; #define PG8_LDA(dst, b, h) do { _Pragma("unroll") for (int m = 0; m < 4; ++m) _Pragma("unroll") for (int k = 0; k < 2; ++k) dst[m][k] = *(const PG8_LAS bf16x8*)(lds + PG8_SA(b, h) + aoff + m * 2048 + k * 1024); } while (0)
; #define PG8_LDB(dst, b, h) do { _Pragma("unroll") for (int n = 0; n < 2; ++n) _Pragma("unroll") for (int k = 0; k < 2; ++k) dst[n][k] = *(const PG8_LAS bf16x8*)(lds + PG8_SB(b, h) + boff + n * 2048 + k * 1024); } while (0)
; #define PG8_MMA(ai, bj, At, Bt) do { __builtin_amdgcn_s_setprio(1); _Pragma("unroll") for (int m = 0; m < 4; ++m) _Pragma("unroll") for (int n = 0; n < 2; ++n) _Pragma("unroll") for (int k = 0; k < 2; ++k) \
;         acc[ai][bj][m][n] = __builtin_amdgcn_mfma_f32_16x16x32_bf16(Bt[n][k], At[m][k], acc[ai][bj][m][n], 0, 0, 0); __builtin_amdgcn_s_setprio(0); } while (0)
; #define PG8_WAIT_V(n) asm volatile("s_waitcnt vmcnt(" #n ")" ::: "memory")
; #define PG8_WAIT_L(n) asm volatile("s_waitcnt lgkmcnt(" #n ")" ::: "memory")
; template <class Epi, class Sched, bool STAMP = false>
; __device__ __forceinline__ void gemm_phase(PG8_LAS unsigned char* lds, const Gemm g, const Sched& S, const Epi& E, unsigned long long* stamps) {
;     ...
;             const char* a1 = cA + (size_t)(t + 1) * kstep;
;             const char* a2 = last ? nA : cA + (size_t)(t + 2) * kstep; const char* b2 = last ? nB : cB + (size_t)(t + 2) * kstep;
;             const char* a3 = a2 + kstep; const char* b3 = b2 + kstep;
;             if (last && has_next) S.a_ready(nxt);
;             PG8_LDB(B0, 0, 0); PG8_SCHED; PG8_LDA(At, 0, 0); PG8_STAGE(PG8_SA(1, 1), a1 + hstep, voffA);
;             PG8_WAIT_L(8); PG8_BAR; PG8_WAIT_L(0); PG8_MMA(0, 0, At, B0); PG8_BAR; PG8_SCHED;
;             PG8_LDB(B1, 0, 1); PG8_STAGE(PG8_SB(0, 0), b2, voffB);
;             PG8_BAR; PG8_WAIT_L(0); PG8_MMA(0, 1, At, B1); PG8_BAR;
;             PG8_LDA(At, 0, 1); PG8_STAGE(PG8_SA(0, 0), a2, voffA);
;             PG8_BAR; PG8_WAIT_L(0); PG8_MMA(1, 0, At, B0); PG8_BAR; PG8_SCHED;
;             PG8_STAGE(PG8_SB(0, 1), b2 + hstep, voffB);
;             PG8_WAIT_V(6); PG8_BAR; PG8_MMA(1, 1, At, B1); PG8_BAR;
.LBB0_313:
	s_add_u32 s12, s4, 0xfffc0080
	s_addc_u32 s13, s5, -1
	s_add_i32 s14, 0, 0x10000
	v_add_u32_e32 v166, s14, v167
	ds_read_b128 v[158:161], v166
	ds_read_b128 v[162:165], v166 offset:1024
	ds_read_b128 v[170:173], v166 offset:2048
	ds_read_b128 v[174:177], v166 offset:3072
	s_cmp_eq_u32 s65, 12
	s_cselect_b32 s27, s31, s13
	s_cselect_b32 s26, s47, s12
	s_cselect_b32 s13, s7, s63
	s_cselect_b32 s12, s53, s62
	v_lshl_add_u64 v[182:183], s[4:5], 0, v[154:155]
	s_add_i32 m0, s3, 0xc000
	ds_read_b128 v[178:181], v169
	ds_read_b128 v[192:195], v169 offset:1024
	ds_read_b128 v[196:199], v169 offset:2048
	ds_read_b128 v[200:203], v169 offset:3072
	ds_read_b128 v[204:207], v169 offset:4096
	ds_read_b128 v[208:211], v169 offset:5120
	ds_read_b128 v[212:215], v169 offset:6144
	ds_read_b128 v[216:219], v169 offset:7168
	global_load_lds_dwordx4 v[182:183], off
	v_lshl_add_u64 v[182:183], s[4:5], 0, v[156:157]
	s_add_i32 m0, s3, 0xe000
	s_nop 0
	global_load_lds_dwordx4 v[182:183], off
	s_waitcnt lgkmcnt(8)
	s_barrier
	s_waitcnt lgkmcnt(0)
	s_setprio 1
	s_waitcnt lgkmcnt(0)
	v_mfma_f32_16x16x32_bf16 v[124:127], v[158:161], v[178:181], v[124:127]
	v_mfma_f32_16x16x32_bf16 v[120:123], v[170:173], v[178:181], v[120:123]
	v_mfma_f32_16x16x32_bf16 v[108:111], v[158:161], v[196:199], v[108:111]
	v_mfma_f32_16x16x32_bf16 v[104:107], v[170:173], v[196:199], v[104:107]
	v_mfma_f32_16x16x32_bf16 v[92:95], v[158:161], v[204:207], v[92:95]
	v_mfma_f32_16x16x32_bf16 v[88:91], v[170:173], v[204:207], v[88:91]
	v_mfma_f32_16x16x32_bf16 v[76:79], v[158:161], v[212:215], v[76:79]
	v_mfma_f32_16x16x32_bf16 v[72:75], v[170:173], v[212:215], v[72:75]
	v_mfma_f32_16x16x32_bf16 v[124:127], v[162:165], v[192:195], v[124:127]
	v_mfma_f32_16x16x32_bf16 v[120:123], v[174:177], v[192:195], v[120:123]
	v_mfma_f32_16x16x32_bf16 v[108:111], v[162:165], v[200:203], v[108:111]
	v_mfma_f32_16x16x32_bf16 v[104:107], v[174:177], v[200:203], v[104:107]
	v_mfma_f32_16x16x32_bf16 v[92:95], v[162:165], v[208:211], v[92:95]
	v_mfma_f32_16x16x32_bf16 v[88:91], v[174:177], v[208:211], v[88:91]
	v_mfma_f32_16x16x32_bf16 v[76:79], v[162:165], v[216:219], v[76:79]
	v_mfma_f32_16x16x32_bf16 v[72:75], v[174:177], v[216:219], v[72:75]
	s_setprio 0
	s_barrier
	s_add_i32 s16, 0, 0x14000
	s_add_i32 s14, s14, s56
	v_add_u32_e32 v166, s16, v167
	v_lshl_add_u64 v[182:183], s[12:13], 0, v[128:129]
	s_mov_b32 m0, s14
	ds_read_b128 v[220:223], v166
	ds_read_b128 v[224:227], v166 offset:1024
	ds_read_b128 v[228:231], v166 offset:2048
	ds_read_b128 v[232:235], v166 offset:3072
	global_load_lds_dwordx4 v[182:183], off
	v_lshl_add_u64 v[236:237], s[12:13], 0, v[152:153]
	s_add_i32 m0, s14, 0x2000
	s_nop 0
	global_load_lds_dwordx4 v[236:237], off
	s_barrier
	s_waitcnt lgkmcnt(0)
	s_setprio 1
	s_waitcnt lgkmcnt(0)
	v_mfma_f32_16x16x32_bf16 v[116:119], v[220:223], v[178:181], v[116:119]
	v_mfma_f32_16x16x32_bf16 v[112:115], v[228:231], v[178:181], v[112:115]
	v_mfma_f32_16x16x32_bf16 v[100:103], v[220:223], v[196:199], v[100:103]
	v_mfma_f32_16x16x32_bf16 v[96:99], v[228:231], v[196:199], v[96:99]
	v_mfma_f32_16x16x32_bf16 v[84:87], v[220:223], v[204:207], v[84:87]
	v_mfma_f32_16x16x32_bf16 v[80:83], v[228:231], v[204:207], v[80:83]
	v_mfma_f32_16x16x32_bf16 v[68:71], v[220:223], v[212:215], v[68:71]
	v_mfma_f32_16x16x32_bf16 v[64:67], v[228:231], v[212:215], v[64:67]
	v_mfma_f32_16x16x32_bf16 v[116:119], v[224:227], v[192:195], v[116:119]
	v_mfma_f32_16x16x32_bf16 v[112:115], v[232:235], v[192:195], v[112:115]
	v_mfma_f32_16x16x32_bf16 v[100:103], v[224:227], v[200:203], v[100:103]
	v_mfma_f32_16x16x32_bf16 v[96:99], v[232:235], v[200:203], v[96:99]
	v_mfma_f32_16x16x32_bf16 v[84:87], v[224:227], v[208:211], v[84:87]
	v_mfma_f32_16x16x32_bf16 v[80:83], v[232:235], v[208:211], v[80:83]
	v_mfma_f32_16x16x32_bf16 v[68:71], v[224:227], v[216:219], v[68:71]
	v_mfma_f32_16x16x32_bf16 v[64:67], v[232:235], v[216:219], v[64:67]
	s_setprio 0
	s_mov_b32 m0, s3
	v_lshl_add_u64 v[238:239], s[26:27], 0, v[148:149]
	s_barrier
	ds_read_b128 v[178:181], v169 offset:16384
	ds_read_b128 v[192:195], v169 offset:17408
	ds_read_b128 v[196:199], v169 offset:18432
	ds_read_b128 v[200:203], v169 offset:19456
	ds_read_b128 v[204:207], v169 offset:20480
	ds_read_b128 v[208:211], v169 offset:21504
	ds_read_b128 v[212:215], v169 offset:22528
	ds_read_b128 v[216:219], v169 offset:23552
	global_load_lds_dwordx4 v[238:239], off
	v_lshl_add_u64 v[240:241], s[26:27], 0, v[150:151]
	s_mov_b32 m0, s57
	s_nop 0
	global_load_lds_dwordx4 v[240:241], off
	s_barrier
	s_waitcnt lgkmcnt(0)
	s_setprio 1
	s_waitcnt lgkmcnt(0)
	v_mfma_f32_16x16x32_bf16 v[60:63], v[158:161], v[178:181], v[60:63]
	v_mfma_f32_16x16x32_bf16 v[56:59], v[170:173], v[178:181], v[56:59]
	v_mfma_f32_16x16x32_bf16 v[44:47], v[158:161], v[196:199], v[44:47]
	v_mfma_f32_16x16x32_bf16 v[40:43], v[170:173], v[196:199], v[40:43]
	v_mfma_f32_16x16x32_bf16 v[28:31], v[158:161], v[204:207], v[28:31]
	v_mfma_f32_16x16x32_bf16 v[24:27], v[170:173], v[204:207], v[24:27]
	v_mfma_f32_16x16x32_bf16 v[12:15], v[158:161], v[212:215], v[12:15]
	v_mfma_f32_16x16x32_bf16 v[8:11], v[170:173], v[212:215], v[8:11]
	v_mfma_f32_16x16x32_bf16 v[60:63], v[162:165], v[192:195], v[60:63]
	v_mfma_f32_16x16x32_bf16 v[56:59], v[174:177], v[192:195], v[56:59]
	v_mfma_f32_16x16x32_bf16 v[44:47], v[162:165], v[200:203], v[44:47]
	v_mfma_f32_16x16x32_bf16 v[40:43], v[174:177], v[200:203], v[40:43]
	v_mfma_f32_16x16x32_bf16 v[28:31], v[162:165], v[208:211], v[28:31]
	v_mfma_f32_16x16x32_bf16 v[24:27], v[174:177], v[208:211], v[24:27]
	v_mfma_f32_16x16x32_bf16 v[12:15], v[162:165], v[216:219], v[12:15]
	v_mfma_f32_16x16x32_bf16 v[8:11], v[174:177], v[216:219], v[8:11]
	s_setprio 0
	s_barrier
; #define PG8_STAGE(bufoff, gbase, voff) do { _Pragma("unroll") for (int _i = 0; _i < 2; ++_i) \
;         __builtin_amdgcn_global_load_lds((const unsigned*)((const char*)(gbase) + (voff)[_i]), (PG8_LAS unsigned*)(lds + (bufoff) + ldsw + _i * 8192), 16, 0, 0); } while (0)
; #define PG8_LDA(dst, b, h) do { _Pragma("unroll") for (int m = 0; m < 4; ++m) _Pragma("unroll") for (int k = 0; k < 2; ++k) dst[m][k] = *(const PG8_LAS bf16x8*)(lds + PG8_SA(b, h) + aoff + m * 2048 + k * 1024); } while (0)
; #define PG8_LDB(dst, b, h) do { _Pragma("unroll") for (int n = 0; n < 2; ++n) _Pragma("unroll") for (int k = 0; k < 2; ++k) dst[n][k] = *(const PG8_LAS bf16x8*)(lds + PG8_SB(b, h) + boff + n * 2048 + k * 1024); } while (0)
; #define PG8_MMA(ai, bj, At, Bt) do { __builtin_amdgcn_s_setprio(1); _Pragma("unroll") for (int m = 0; m < 4; ++m) _Pragma("unroll") for (int n = 0; n < 2; ++n) _Pragma("unroll") for (int k = 0; k < 2; ++k) \
;         acc[ai][bj][m][n] = __builtin_amdgcn_mfma_f32_16x16x32_bf16(Bt[n][k], At[m][k], acc[ai][bj][m][n], 0, 0, 0); __builtin_amdgcn_s_setprio(0); } while (0)
; #define PG8_WAIT_V(n) asm volatile("s_waitcnt vmcnt(" #n ")" ::: "memory")
; #define PG8_WAIT_L(n) asm volatile("s_waitcnt lgkmcnt(" #n ")" ::: "memory")
; #define PG8_BAR __builtin_amdgcn_s_barrier()
; #define PG8_SCHED __builtin_amdgcn_sched_barrier(0)
; template <class Epi, class Sched, bool STAMP = false>
; __device__ __forceinline__ void gemm_phase(PG8_LAS unsigned char* lds, const Gemm g, const Sched& S, const Epi& E, unsigned long long* stamps) {
;     ...
;             PG8_STAGE(PG8_SB(0, 1), b2 + hstep, voffB);
;             PG8_WAIT_V(6); PG8_BAR; PG8_MMA(1, 1, At, B1); PG8_BAR;
;             PG8_LDB(B0, 1, 0); PG8_SCHED; PG8_LDA(At, 1, 0); PG8_STAGE(PG8_SA(0, 1), a2 + hstep, voffA);
;             PG8_WAIT_L(8); PG8_BAR; PG8_WAIT_L(0); PG8_MMA(0, 0, At, B0); PG8_BAR; PG8_SCHED;
;             PG8_LDB(B1, 1, 1); PG8_STAGE(PG8_SB(1, 0), b3, voffB);
;             PG8_BAR; PG8_WAIT_L(0); PG8_MMA(0, 1, At, B1); PG8_BAR;
;             PG8_LDA(At, 1, 1); PG8_STAGE(PG8_SA(1, 0), a3, voffA);
;             PG8_BAR; PG8_WAIT_L(0); PG8_MMA(1, 0, At, B0); PG8_BAR; PG8_SCHED;
;             PG8_STAGE(PG8_SB(1, 1), b3 + hstep, voffB);
;             PG8_WAIT_V(6); PG8_BAR; PG8_MMA(1, 1, At, B1); PG8_BAR;
	s_add_u32 s14, s12, 0x40000
	s_addc_u32 s15, s13, 0
	s_add_i32 s16, s16, s56
	v_lshl_add_u64 v[158:159], s[14:15], 0, v[128:129]
	s_mov_b32 m0, s16
	s_nop 0
	global_load_lds_dwordx4 v[158:159], off
	v_lshl_add_u64 v[158:159], s[14:15], 0, v[152:153]
	s_add_i32 m0, s16, 0x2000
	s_nop 0
	global_load_lds_dwordx4 v[158:159], off
	s_waitcnt vmcnt(6)
	s_barrier
	s_setprio 1
	v_mfma_f32_16x16x32_bf16 v[52:55], v[220:223], v[178:181], v[52:55]
	v_mfma_f32_16x16x32_bf16 v[48:51], v[228:231], v[178:181], v[48:51]
	v_mfma_f32_16x16x32_bf16 v[36:39], v[220:223], v[196:199], v[36:39]
	v_mfma_f32_16x16x32_bf16 v[32:35], v[228:231], v[196:199], v[32:35]
	v_mfma_f32_16x16x32_bf16 v[20:23], v[220:223], v[204:207], v[20:23]
	v_mfma_f32_16x16x32_bf16 v[16:19], v[228:231], v[204:207], v[16:19]
	v_mfma_f32_16x16x32_bf16 v[4:7], v[220:223], v[212:215], v[4:7]
	v_mfma_f32_16x16x32_bf16 v[0:3], v[228:231], v[212:215], v[0:3]
	v_mfma_f32_16x16x32_bf16 v[52:55], v[224:227], v[192:195], v[52:55]
	v_mfma_f32_16x16x32_bf16 v[48:51], v[232:235], v[192:195], v[48:51]
	v_mfma_f32_16x16x32_bf16 v[36:39], v[224:227], v[200:203], v[36:39]
	v_mfma_f32_16x16x32_bf16 v[32:35], v[232:235], v[200:203], v[32:35]
	v_mfma_f32_16x16x32_bf16 v[20:23], v[224:227], v[208:211], v[20:23]
	v_mfma_f32_16x16x32_bf16 v[16:19], v[232:235], v[208:211], v[16:19]
	v_mfma_f32_16x16x32_bf16 v[4:7], v[224:227], v[216:219], v[4:7]
	v_mfma_f32_16x16x32_bf16 v[0:3], v[232:235], v[216:219], v[0:3]
	s_setprio 0
	s_add_i32 s16, 0, 0x18000
	v_add_u32_e32 v166, s16, v167
	s_barrier
	ds_read_b128 v[158:161], v166
	ds_read_b128 v[162:165], v166 offset:1024
	ds_read_b128 v[170:173], v166 offset:2048
	ds_read_b128 v[174:177], v166 offset:3072
	s_add_u32 s14, s26, 0x40000
	s_addc_u32 s15, s27, 0
	s_mov_b32 m0, s58
	v_lshl_add_u64 v[220:221], s[14:15], 0, v[148:149]
	ds_read_b128 v[178:181], v169 offset:32768
	ds_read_b128 v[192:195], v169 offset:33792
	ds_read_b128 v[196:199], v169 offset:34816
	ds_read_b128 v[200:203], v169 offset:35840
	ds_read_b128 v[204:207], v169 offset:36864
	ds_read_b128 v[208:211], v169 offset:37888
	ds_read_b128 v[212:215], v169 offset:38912
	ds_read_b128 v[216:219], v169 offset:39936
	global_load_lds_dwordx4 v[220:221], off
	v_lshl_add_u64 v[220:221], s[14:15], 0, v[150:151]
	s_mov_b32 m0, s59
	s_nop 0
	global_load_lds_dwordx4 v[220:221], off
	s_waitcnt lgkmcnt(8)
	s_barrier
	s_waitcnt lgkmcnt(0)
	s_setprio 1
	s_waitcnt lgkmcnt(0)
	v_mfma_f32_16x16x32_bf16 v[124:127], v[158:161], v[178:181], v[124:127]
	v_mfma_f32_16x16x32_bf16 v[120:123], v[170:173], v[178:181], v[120:123]
	v_mfma_f32_16x16x32_bf16 v[108:111], v[158:161], v[196:199], v[108:111]
	v_mfma_f32_16x16x32_bf16 v[104:107], v[170:173], v[196:199], v[104:107]
	v_mfma_f32_16x16x32_bf16 v[92:95], v[158:161], v[204:207], v[92:95]
	v_mfma_f32_16x16x32_bf16 v[88:91], v[170:173], v[204:207], v[88:91]
	v_mfma_f32_16x16x32_bf16 v[76:79], v[158:161], v[212:215], v[76:79]
	v_mfma_f32_16x16x32_bf16 v[72:75], v[170:173], v[212:215], v[72:75]
	v_mfma_f32_16x16x32_bf16 v[124:127], v[162:165], v[192:195], v[124:127]
	v_mfma_f32_16x16x32_bf16 v[120:123], v[174:177], v[192:195], v[120:123]
	v_mfma_f32_16x16x32_bf16 v[108:111], v[162:165], v[200:203], v[108:111]
	v_mfma_f32_16x16x32_bf16 v[104:107], v[174:177], v[200:203], v[104:107]
	v_mfma_f32_16x16x32_bf16 v[92:95], v[162:165], v[208:211], v[92:95]
	v_mfma_f32_16x16x32_bf16 v[88:91], v[174:177], v[208:211], v[88:91]
	v_mfma_f32_16x16x32_bf16 v[76:79], v[162:165], v[216:219], v[76:79]
	v_mfma_f32_16x16x32_bf16 v[72:75], v[174:177], v[216:219], v[72:75]
	s_setprio 0
	s_barrier
	s_add_i32 s14, 0, 0x1c000
	s_add_i32 s15, s16, s56
	v_add_u32_e32 v166, s14, v167
	v_lshl_add_u64 v[182:183], v[182:183], 0, s[18:19]
	s_mov_b32 m0, s15
	ds_read_b128 v[220:223], v166
	ds_read_b128 v[224:227], v166 offset:1024
	ds_read_b128 v[228:231], v166 offset:2048
	ds_read_b128 v[232:235], v166 offset:3072
	global_load_lds_dwordx4 v[182:183], off
	v_lshl_add_u64 v[182:183], v[236:237], 0, s[18:19]
	s_add_i32 m0, s15, 0x2000
	s_nop 0
	global_load_lds_dwordx4 v[182:183], off
	s_barrier
	s_waitcnt lgkmcnt(0)
	s_setprio 1
	s_waitcnt lgkmcnt(0)
	v_mfma_f32_16x16x32_bf16 v[116:119], v[220:223], v[178:181], v[116:119]
	v_mfma_f32_16x16x32_bf16 v[112:115], v[228:231], v[178:181], v[112:115]
	v_mfma_f32_16x16x32_bf16 v[100:103], v[220:223], v[196:199], v[100:103]
	v_mfma_f32_16x16x32_bf16 v[96:99], v[228:231], v[196:199], v[96:99]
	v_mfma_f32_16x16x32_bf16 v[84:87], v[220:223], v[204:207], v[84:87]
	v_mfma_f32_16x16x32_bf16 v[80:83], v[228:231], v[204:207], v[80:83]
	v_mfma_f32_16x16x32_bf16 v[68:71], v[220:223], v[212:215], v[68:71]
	v_mfma_f32_16x16x32_bf16 v[64:67], v[228:231], v[212:215], v[64:67]
	v_mfma_f32_16x16x32_bf16 v[116:119], v[224:227], v[192:195], v[116:119]
	v_mfma_f32_16x16x32_bf16 v[112:115], v[232:235], v[192:195], v[112:115]
	v_mfma_f32_16x16x32_bf16 v[100:103], v[224:227], v[200:203], v[100:103]
	v_mfma_f32_16x16x32_bf16 v[96:99], v[232:235], v[200:203], v[96:99]
	v_mfma_f32_16x16x32_bf16 v[84:87], v[224:227], v[208:211], v[84:87]
	v_mfma_f32_16x16x32_bf16 v[80:83], v[232:235], v[208:211], v[80:83]
	v_mfma_f32_16x16x32_bf16 v[68:71], v[224:227], v[216:219], v[68:71]
	v_mfma_f32_16x16x32_bf16 v[64:67], v[232:235], v[216:219], v[64:67]
	s_setprio 0
	s_mov_b32 m0, s60
	v_lshl_add_u64 v[182:183], v[238:239], 0, s[18:19]
	s_barrier
	ds_read_b128 v[178:181], v169 offset:49152
	ds_read_b128 v[192:195], v169 offset:50176
	ds_read_b128 v[196:199], v169 offset:51200
	ds_read_b128 v[200:203], v169 offset:52224
	ds_read_b128 v[204:207], v169 offset:53248
	ds_read_b128 v[208:211], v169 offset:54272
	ds_read_b128 v[212:215], v169 offset:55296
	ds_read_b128 v[216:219], v169 offset:56320
	global_load_lds_dwordx4 v[182:183], off
	v_lshl_add_u64 v[182:183], v[240:241], 0, s[18:19]
	s_mov_b32 m0, s61
	s_nop 0
	global_load_lds_dwordx4 v[182:183], off
	s_barrier
; #define PG8_STAGE(bufoff, gbase, voff) do { _Pragma("unroll") for (int _i = 0; _i < 2; ++_i) \
;         __builtin_amdgcn_global_load_lds((const unsigned*)((const char*)(gbase) + (voff)[_i]), (PG8_LAS unsigned*)(lds + (bufoff) + ldsw + _i * 8192), 16, 0, 0); } while (0)
; #define PG8_MMA(ai, bj, At, Bt) do { __builtin_amdgcn_s_setprio(1); _Pragma("unroll") for (int m = 0; m < 4; ++m) _Pragma("unroll") for (int n = 0; n < 2; ++n) _Pragma("unroll") for (int k = 0; k < 2; ++k) \
;         acc[ai][bj][m][n] = __builtin_amdgcn_mfma_f32_16x16x32_bf16(Bt[n][k], At[m][k], acc[ai][bj][m][n], 0, 0, 0); __builtin_amdgcn_s_setprio(0); } while (0)
; #define PG8_WAIT_V(n) asm volatile("s_waitcnt vmcnt(" #n ")" ::: "memory")
; #define PG8_WAIT_L(n) asm volatile("s_waitcnt lgkmcnt(" #n ")" ::: "memory")
; #define PG8_BAR __builtin_amdgcn_s_barrier()
; #define PG8_SCHED __builtin_amdgcn_sched_barrier(0)
; __device__ __forceinline__ float rstd_of(const float* rowss, int row) { return rsqrtf(rowss[row] * (1.0f / 1024.0f) + 1e-6f); }
; template <class Epi, class Sched, bool STAMP = false>
; __device__ __forceinline__ void gemm_phase(PG8_LAS unsigned char* lds, const Gemm g, const Sched& S, const Epi& E, unsigned long long* stamps) {
;     ...
;             PG8_BAR; PG8_WAIT_L(0); PG8_MMA(1, 0, At, B0); PG8_BAR; PG8_SCHED;
;             PG8_STAGE(PG8_SB(1, 1), b3 + hstep, voffB);
;             PG8_WAIT_V(6); PG8_BAR; PG8_MMA(1, 1, At, B1); PG8_BAR;
;         }
;     __device__ __forceinline__ void operator()(const f32x4 (&acc)[2][2][4][2], const pg8::Unit& u, int wr, int wc, int fr, int fq) const {
;         const int row0 = u.pm * 256 + wr * 64 + fr, col0 = u.pn * 256 + wc * 32 + 8 * fq;
; #pragma unroll
;         for (int ai = 0; ai < 2; ++ai)
; #pragma unroll
;             for (int m = 0; m < 4; ++m) {
;                 const int row = row0 + ai * 128 + m * 16;
;                 const float s = rstd_of(rowss, row);
; #pragma unroll
;                 for (int bj = 0; bj < 2; ++bj) {
;                     const size_t off = (size_t)row * 1024 + col0 + bj * 128;
;                     const u32x4 tv = *(const u32x4*)(Tm + off);
;                     u32x4 pv = (u32x4){0u, 0u, 0u, 0u};
;                     if (ACC) pv = *(const u32x4*)(M + off);
;                     const f32x4 a0 = acc[ai][bj][m][0] * s, a1 = acc[ai][bj][m][1] * s;
	s_waitcnt lgkmcnt(0)
	s_setprio 1
	s_waitcnt lgkmcnt(0)
	v_mfma_f32_16x16x32_bf16 v[60:63], v[158:161], v[178:181], v[60:63]
	v_mfma_f32_16x16x32_bf16 v[56:59], v[170:173], v[178:181], v[56:59]
	v_mfma_f32_16x16x32_bf16 v[44:47], v[158:161], v[196:199], v[44:47]
	v_mfma_f32_16x16x32_bf16 v[40:43], v[170:173], v[196:199], v[40:43]
	v_mfma_f32_16x16x32_bf16 v[28:31], v[158:161], v[204:207], v[28:31]
	v_mfma_f32_16x16x32_bf16 v[24:27], v[170:173], v[204:207], v[24:27]
	v_mfma_f32_16x16x32_bf16 v[12:15], v[158:161], v[212:215], v[12:15]
	v_mfma_f32_16x16x32_bf16 v[8:11], v[170:173], v[212:215], v[8:11]
	v_mfma_f32_16x16x32_bf16 v[60:63], v[162:165], v[192:195], v[60:63]
	v_mfma_f32_16x16x32_bf16 v[56:59], v[174:177], v[192:195], v[56:59]
	v_mfma_f32_16x16x32_bf16 v[44:47], v[162:165], v[200:203], v[44:47]
	v_mfma_f32_16x16x32_bf16 v[40:43], v[174:177], v[200:203], v[40:43]
	v_mfma_f32_16x16x32_bf16 v[28:31], v[162:165], v[208:211], v[28:31]
	v_mfma_f32_16x16x32_bf16 v[24:27], v[174:177], v[208:211], v[24:27]
	v_mfma_f32_16x16x32_bf16 v[12:15], v[162:165], v[216:219], v[12:15]
	v_mfma_f32_16x16x32_bf16 v[8:11], v[174:177], v[216:219], v[8:11]
	s_setprio 0
	s_barrier
	s_add_u32 s12, s12, 0x40080
	s_addc_u32 s13, s13, 0
	s_add_i32 s14, s14, s56
	v_lshl_add_u64 v[158:159], s[12:13], 0, v[128:129]
	s_mov_b32 m0, s14
	s_nop 0
	global_load_lds_dwordx4 v[158:159], off
	v_lshl_add_u64 v[158:159], s[12:13], 0, v[152:153]
	s_add_i32 m0, s14, 0x2000
	s_nop 0
	global_load_lds_dwordx4 v[158:159], off
	s_waitcnt vmcnt(6)
	s_barrier
	s_setprio 1
	v_mfma_f32_16x16x32_bf16 v[52:55], v[220:223], v[178:181], v[52:55]
	v_mfma_f32_16x16x32_bf16 v[48:51], v[228:231], v[178:181], v[48:51]
	v_mfma_f32_16x16x32_bf16 v[36:39], v[220:223], v[196:199], v[36:39]
	v_mfma_f32_16x16x32_bf16 v[32:35], v[228:231], v[196:199], v[32:35]
	v_mfma_f32_16x16x32_bf16 v[20:23], v[220:223], v[204:207], v[20:23]
	v_mfma_f32_16x16x32_bf16 v[16:19], v[228:231], v[204:207], v[16:19]
	v_mfma_f32_16x16x32_bf16 v[4:7], v[220:223], v[212:215], v[4:7]
	v_mfma_f32_16x16x32_bf16 v[0:3], v[228:231], v[212:215], v[0:3]
	v_mfma_f32_16x16x32_bf16 v[52:55], v[224:227], v[192:195], v[52:55]
	v_mfma_f32_16x16x32_bf16 v[48:51], v[232:235], v[192:195], v[48:51]
	v_mfma_f32_16x16x32_bf16 v[36:39], v[224:227], v[200:203], v[36:39]
	v_mfma_f32_16x16x32_bf16 v[32:35], v[232:235], v[200:203], v[32:35]
	v_mfma_f32_16x16x32_bf16 v[20:23], v[224:227], v[208:211], v[20:23]
	v_mfma_f32_16x16x32_bf16 v[16:19], v[232:235], v[208:211], v[16:19]
	v_mfma_f32_16x16x32_bf16 v[4:7], v[224:227], v[216:219], v[4:7]
	v_mfma_f32_16x16x32_bf16 v[0:3], v[232:235], v[216:219], v[0:3]
	s_setprio 0
	s_add_i32 s65, s65, 2
	s_add_u32 s4, s4, 0x100
	s_addc_u32 s5, s5, 0
	s_add_u32 s62, s62, 0x100
	s_addc_u32 s63, s63, 0
	s_cmp_gt_u32 s65, 13
	s_barrier
	s_cbranch_scc0 .LBB0_313
	v_lshl_add_u32 v162, s2, 8, v139
	v_ashrrev_i32_e32 v163, 31, v162
	v_lshl_add_u64 v[160:161], v[162:163], 2, s[40:41]
	global_load_dword v164, v[160:161], off
	v_lshl_or_b32 v158, s46, 8, v168
	v_ashrrev_i32_e32 v159, 31, v158
	s_mov_b32 s2, 0x40000
	s_mov_b64 s[4:5], 0x40000
	s_mov_b32 s46, s6
	s_mov_b64 s[12:13], s[24:25]
	s_mov_b32 s62, 0x1800000
	s_waitcnt vmcnt(0)
	v_fmamk_f32 v164, v164, 0x3a800000, v187
	v_cmp_gt_f32_e32 vcc, s67, v164
	v_mul_f32_e32 v165, 0x4b800000, v164
	s_nop 0
	v_cndmask_b32_e32 v164, v164, v165, vcc
	v_rsq_f32_e32 v164, v164
	s_nop 0
	v_mul_f32_e32 v165, 0x45800000, v164
	v_cndmask_b32_e32 v166, v164, v165, vcc
	v_lshlrev_b64 v[164:165], 11, v[162:163]
	v_lshl_add_u64 v[170:171], s[0:1], 0, v[164:165]
	v_lshlrev_b64 v[164:165], 1, v[158:159]
	v_lshl_add_u64 v[158:159], v[170:171], 0, v[164:165]
	v_mov_b32_e32 v170, v158
	v_mov_b32_e32 v171, v159
	global_load_dwordx4 v[192:195], v[170:171], off
	global_load_dwordx4 v[196:199], v[170:171], off offset:256
	v_add_co_u32_e32 v170, vcc, 0x8000, v170
	s_nop 1
	v_addc_co_u32_e32 v171, vcc, 0, v171, vcc
	global_load_dwordx4 v[200:203], v[170:171], off
	global_load_dwordx4 v[204:207], v[170:171], off offset:256
	v_add_co_u32_e32 v170, vcc, 0x8000, v170
	s_nop 1
	v_addc_co_u32_e32 v171, vcc, 0, v171, vcc
	global_load_dwordx4 v[208:211], v[170:171], off
	global_load_dwordx4 v[212:215], v[170:171], off offset:256
	v_add_co_u32_e32 v170, vcc, 0x8000, v170
	s_nop 1
	v_addc_co_u32_e32 v171, vcc, 0, v171, vcc
	global_load_dwordx4 v[216:219], v[170:171], off
	global_load_dwordx4 v[220:223], v[170:171], off offset:256
	v_lshl_add_u64 v[170:171], v[158:159], 0, s[4:5]
	global_load_dwordx4 v[224:227], v[170:171], off
	global_load_dwordx4 v[228:231], v[170:171], off offset:256
	v_add_co_u32_e32 v170, vcc, 0x8000, v170
	s_nop 1
	v_addc_co_u32_e32 v171, vcc, 0, v171, vcc
	global_load_dwordx4 v[232:235], v[170:171], off
	global_load_dwordx4 v[236:239], v[170:171], off offset:256
	v_add_co_u32_e32 v170, vcc, 0x8000, v170
	s_nop 1
	v_addc_co_u32_e32 v171, vcc, 0, v171, vcc
	global_load_dwordx4 v[244:247], v[170:171], off
	global_load_dwordx4 v[248:251], v[170:171], off offset:256
	v_add_co_u32_e32 v170, vcc, 0x8000, v170
	s_nop 1
	v_addc_co_u32_e32 v171, vcc, 0, v171, vcc
	global_load_dwordx4 v[176:179], v[170:171], off
	global_load_dwordx4 v[252:255], v[170:171], off offset:256
	global_load_dword v180, v[160:161], off offset:64
	global_load_dword v181, v[160:161], off offset:128
	global_load_dword v182, v[160:161], off offset:192
	global_load_dword v183, v[160:161], off offset:512
	global_load_dword v240, v[160:161], off offset:576
	global_load_dword v241, v[160:161], off offset:640
	global_load_dword v169, v[160:161], off offset:704
	v_pk_mul_f32 v[126:127], v[126:127], v[166:167] op_sel_hi:[1,0]
; __device__ __forceinline__ unsigned cvt_pk_bf16(float lo, float hi) { const f32x2_cv v = {lo, hi}; const bf16x2_cv b = __builtin_convertvector(v, bf16x2_cv); return __builtin_bit_cast(unsigned, b); }
; __device__ __forceinline__ float sigm(float x) { return __builtin_amdgcn_rcpf(1.0f + __expf(-x)); }
; __device__ __forceinline__ float lo16(unsigned w) { return __uint_as_float(w << 16); }
; __device__ __forceinline__ float hi16(unsigned w) { return __uint_as_float(w & 0xffff0000u); }
; __device__ __forceinline__ float rstd_of(const float* rowss, int row) { return rsqrtf(rowss[row] * (1.0f / 1024.0f) + 1e-6f); }
;     __device__ __forceinline__ void operator()(const f32x4 (&acc)[2][2][4][2], const pg8::Unit& u, int wr, int wc, int fr, int fq) const {
;     ...
;             for (int m = 0; m < 4; ++m) {
;                 const int row = row0 + ai * 128 + m * 16;
;                 const float s = rstd_of(rowss, row);
; #pragma unroll
;                 for (int bj = 0; bj < 2; ++bj) {
;                     const size_t off = (size_t)row * 1024 + col0 + bj * 128;
;                     const u32x4 tv = *(const u32x4*)(Tm + off);
;                     u32x4 pv = (u32x4){0u, 0u, 0u, 0u};
;                     if (ACC) pv = *(const u32x4*)(M + off);
;                     const f32x4 a0 = acc[ai][bj][m][0] * s, a1 = acc[ai][bj][m][1] * s;
;                     float o[8];
;                     o[0] = sigm(a0[0]) * lo16(tv.x); o[1] = sigm(a0[1]) * hi16(tv.x); o[2] = sigm(a0[2]) * lo16(tv.y); o[3] = sigm(a0[3]) * hi16(tv.y);
;                     o[4] = sigm(a1[0]) * lo16(tv.z); o[5] = sigm(a1[1]) * hi16(tv.z); o[6] = sigm(a1[2]) * lo16(tv.w); o[7] = sigm(a1[3]) * hi16(tv.w);
;                     if (ACC) { o[0] += lo16(pv.x); o[1] += hi16(pv.x); o[2] += lo16(pv.y); o[3] += hi16(pv.y); o[4] += lo16(pv.z); o[5] += hi16(pv.z); o[6] += lo16(pv.w); o[7] += hi16(pv.w); }
;                     u32x4 w; w.x = cvt_pk_bf16(o[0], o[1]); w.y = cvt_pk_bf16(o[2], o[3]); w.z = cvt_pk_bf16(o[4], o[5]); w.w = cvt_pk_bf16(o[6], o[7]);
;                     *(u32x4*)(M + off) = w; } }
	v_pk_mul_f32 v[120:121], v[120:121], v[166:167] op_sel_hi:[1,0]
	v_mul_f32_e32 v126, 0xbfb8aa3b, v126
	v_mul_f32_e32 v127, 0xbfb8aa3b, v127
	v_exp_f32_e32 v126, v126
	v_exp_f32_e32 v127, v127
	v_mul_f32_e32 v120, 0xbfb8aa3b, v120
	v_mul_f32_e32 v121, 0xbfb8aa3b, v121
	v_exp_f32_e32 v120, v120
	v_exp_f32_e32 v121, v121
	v_add_f32_e32 v126, 1.0, v126
	v_add_f32_e32 v127, 1.0, v127
	v_rcp_f32_e32 v126, v126
	v_rcp_f32_e32 v127, v127
	v_add_f32_e32 v120, 1.0, v120
	v_add_f32_e32 v121, 1.0, v121
	v_rcp_f32_e32 v120, v120
	v_rcp_f32_e32 v121, v121
	v_pk_mul_f32 v[124:125], v[124:125], v[166:167] op_sel_hi:[1,0]
	v_pk_mul_f32 v[122:123], v[122:123], v[166:167] op_sel_hi:[1,0]
	v_mul_f32_e32 v124, 0xbfb8aa3b, v124
	v_mul_f32_e32 v125, 0xbfb8aa3b, v125
	v_exp_f32_e32 v124, v124
	v_exp_f32_e32 v125, v125
	v_pk_mul_f32 v[118:119], v[118:119], v[166:167] op_sel_hi:[1,0]
	v_pk_mul_f32 v[112:113], v[112:113], v[166:167] op_sel_hi:[1,0]
	v_add_f32_e32 v124, 1.0, v124
	v_add_f32_e32 v125, 1.0, v125
	v_rcp_f32_e32 v124, v124
	v_rcp_f32_e32 v125, v125
	v_mul_f32_e32 v118, 0xbfb8aa3b, v118
	v_mul_f32_e32 v119, 0xbfb8aa3b, v119
	v_exp_f32_e32 v118, v118
	v_exp_f32_e32 v119, v119
	v_mul_f32_e32 v112, 0xbfb8aa3b, v112
	v_mul_f32_e32 v113, 0xbfb8aa3b, v113
	v_exp_f32_e32 v112, v112
	v_exp_f32_e32 v113, v113
	v_add_f32_e32 v118, 1.0, v118
	v_add_f32_e32 v119, 1.0, v119
	v_rcp_f32_e32 v118, v118
	v_rcp_f32_e32 v119, v119
	v_add_f32_e32 v112, 1.0, v112
	v_add_f32_e32 v113, 1.0, v113
	v_rcp_f32_e32 v112, v112
	v_rcp_f32_e32 v113, v113
	v_pk_mul_f32 v[116:117], v[116:117], v[166:167] op_sel_hi:[1,0]
	v_pk_mul_f32 v[114:115], v[114:115], v[166:167] op_sel_hi:[1,0]
	v_mul_f32_e32 v116, 0xbfb8aa3b, v116
	v_mul_f32_e32 v117, 0xbfb8aa3b, v117
	v_exp_f32_e32 v116, v116
	v_exp_f32_e32 v117, v117
	v_add_f32_e32 v116, 1.0, v116
	v_add_f32_e32 v117, 1.0, v117
	v_rcp_f32_e32 v116, v116
	v_rcp_f32_e32 v117, v117
	s_waitcnt vmcnt(0)
	v_mov_b32_e32 v170, v192
	v_mov_b32_e32 v171, v193
	v_mov_b32_e32 v172, v194
	v_mov_b32_e32 v173, v195
	v_lshlrev_b32_e32 v174, 16, v170
	v_and_b32_e32 v175, 0xffff0000, v170
	v_lshlrev_b32_e32 v170, 16, v171
	v_and_b32_e32 v171, 0xffff0000, v171
	v_pk_mul_f32 v[126:127], v[126:127], v[170:171]
	v_lshlrev_b32_e32 v170, 16, v172
	v_and_b32_e32 v171, 0xffff0000, v172
	v_pk_mul_f32 v[170:171], v[120:121], v[170:171]
	v_mul_f32_e32 v120, 0xbfb8aa3b, v122
	v_mul_f32_e32 v121, 0xbfb8aa3b, v123
	v_exp_f32_e32 v120, v120
	v_exp_f32_e32 v121, v121
	v_lshlrev_b32_e32 v122, 16, v173
	v_and_b32_e32 v123, 0xffff0000, v173
	v_add_f32_e32 v120, 1.0, v120
	v_add_f32_e32 v121, 1.0, v121
	v_rcp_f32_e32 v120, v120
	v_rcp_f32_e32 v121, v121
	v_pk_mul_f32 v[124:125], v[124:125], v[174:175]
	v_pk_mul_f32 v[172:173], v[120:121], v[122:123]
	v_cvt_pk_bf16_f32 v120, v124, v125
	v_cvt_pk_bf16_f32 v121, v126, v127
	v_cvt_pk_bf16_f32 v122, v170, v171
	v_cvt_pk_bf16_f32 v123, v172, v173
	global_store_dwordx4 v[158:159], v[120:123], off
	s_nop 1
	v_mov_b32_e32 v120, v196
	v_mov_b32_e32 v121, v197
	v_mov_b32_e32 v122, v198
	v_mov_b32_e32 v123, v199
	v_lshlrev_b32_e32 v124, 16, v120
	v_and_b32_e32 v125, 0xffff0000, v120
	v_lshlrev_b32_e32 v120, 16, v121
	v_and_b32_e32 v121, 0xffff0000, v121
	v_pk_mul_f32 v[118:119], v[118:119], v[120:121]
	v_lshlrev_b32_e32 v120, 16, v122
	v_and_b32_e32 v121, 0xffff0000, v122
	v_pk_mul_f32 v[120:121], v[112:113], v[120:121]
	v_mul_f32_e32 v112, 0xbfb8aa3b, v114
	v_mul_f32_e32 v113, 0xbfb8aa3b, v115
	v_exp_f32_e32 v112, v112
	v_exp_f32_e32 v113, v113
	v_lshlrev_b32_e32 v114, 16, v123
	v_and_b32_e32 v115, 0xffff0000, v123
	v_add_f32_e32 v112, 1.0, v112
	v_add_f32_e32 v113, 1.0, v113
	v_rcp_f32_e32 v112, v112
	v_rcp_f32_e32 v113, v113
	v_pk_mul_f32 v[116:117], v[116:117], v[124:125]
	v_pk_mul_f32 v[122:123], v[112:113], v[114:115]
	v_cvt_pk_bf16_f32 v112, v116, v117
	v_cvt_pk_bf16_f32 v113, v118, v119
	v_cvt_pk_bf16_f32 v114, v120, v121
	v_cvt_pk_bf16_f32 v115, v122, v123
	global_store_dwordx4 v[158:159], v[112:115], off offset:256
	s_nop 1
	v_mov_b32_e32 v114, v180
	s_nop 0
	v_or_b32_e32 v112, 16, v162
	v_ashrrev_i32_e32 v113, 31, v112
	v_lshlrev_b64 v[112:113], 11, v[112:113]
	v_lshl_add_u64 v[112:113], s[0:1], 0, v[112:113]
	v_lshl_add_u64 v[112:113], v[112:113], 0, v[164:165]
	s_nop 1
	v_mov_b32_e32 v116, v200
	v_mov_b32_e32 v117, v201
	v_mov_b32_e32 v118, v202
	v_mov_b32_e32 v119, v203
	v_fmamk_f32 v114, v114, 0x3a800000, v187
	v_cmp_gt_f32_e32 vcc, s67, v114
	v_mul_f32_e32 v115, 0x4b800000, v114
	v_lshlrev_b32_e32 v120, 16, v116
	v_cndmask_b32_e32 v114, v114, v115, vcc
	v_rsq_f32_e32 v114, v114
	v_and_b32_e32 v121, 0xffff0000, v116
	v_lshlrev_b32_e32 v116, 16, v117
	v_and_b32_e32 v117, 0xffff0000, v117
	v_mul_f32_e32 v115, 0x45800000, v114
	v_cndmask_b32_e32 v114, v114, v115, vcc
	v_pk_mul_f32 v[110:111], v[110:111], v[114:115] op_sel_hi:[1,0]
	v_pk_mul_f32 v[104:105], v[104:105], v[114:115] op_sel_hi:[1,0]
	v_mul_f32_e32 v110, 0xbfb8aa3b, v110
	v_mul_f32_e32 v111, 0xbfb8aa3b, v111
	v_exp_f32_e32 v110, v110
	v_exp_f32_e32 v111, v111
	v_mul_f32_e32 v104, 0xbfb8aa3b, v104
	v_mul_f32_e32 v105, 0xbfb8aa3b, v105
	v_exp_f32_e32 v104, v104
	v_exp_f32_e32 v105, v105
	v_add_f32_e32 v110, 1.0, v110
	v_add_f32_e32 v111, 1.0, v111
	v_rcp_f32_e32 v110, v110
	v_rcp_f32_e32 v111, v111
	v_add_f32_e32 v104, 1.0, v104
	v_add_f32_e32 v105, 1.0, v105
	v_rcp_f32_e32 v104, v104
	v_rcp_f32_e32 v105, v105
	v_pk_mul_f32 v[108:109], v[108:109], v[114:115] op_sel_hi:[1,0]
	v_pk_mul_f32 v[106:107], v[106:107], v[114:115] op_sel_hi:[1,0]
	v_pk_mul_f32 v[110:111], v[110:111], v[116:117]
	v_lshlrev_b32_e32 v116, 16, v118
	v_and_b32_e32 v117, 0xffff0000, v118
; __device__ __forceinline__ unsigned cvt_pk_bf16(float lo, float hi) { const f32x2_cv v = {lo, hi}; const bf16x2_cv b = __builtin_convertvector(v, bf16x2_cv); return __builtin_bit_cast(unsigned, b); }
; __device__ __forceinline__ float sigm(float x) { return __builtin_amdgcn_rcpf(1.0f + __expf(-x)); }
; __device__ __forceinline__ float lo16(unsigned w) { return __uint_as_float(w << 16); }
; __device__ __forceinline__ float hi16(unsigned w) { return __uint_as_float(w & 0xffff0000u); }
; __device__ __forceinline__ float rstd_of(const float* rowss, int row) { return rsqrtf(rowss[row] * (1.0f / 1024.0f) + 1e-6f); }
;     __device__ __forceinline__ void operator()(const f32x4 (&acc)[2][2][4][2], const pg8::Unit& u, int wr, int wc, int fr, int fq) const {
;     ...
;             for (int m = 0; m < 4; ++m) {
;                 const int row = row0 + ai * 128 + m * 16;
;                 const float s = rstd_of(rowss, row);
; #pragma unroll
;                 for (int bj = 0; bj < 2; ++bj) {
;                     const size_t off = (size_t)row * 1024 + col0 + bj * 128;
;                     const u32x4 tv = *(const u32x4*)(Tm + off);
;                     u32x4 pv = (u32x4){0u, 0u, 0u, 0u};
;                     if (ACC) pv = *(const u32x4*)(M + off);
;                     const f32x4 a0 = acc[ai][bj][m][0] * s, a1 = acc[ai][bj][m][1] * s;
;                     float o[8];
;                     o[0] = sigm(a0[0]) * lo16(tv.x); o[1] = sigm(a0[1]) * hi16(tv.x); o[2] = sigm(a0[2]) * lo16(tv.y); o[3] = sigm(a0[3]) * hi16(tv.y);
;                     o[4] = sigm(a1[0]) * lo16(tv.z); o[5] = sigm(a1[1]) * hi16(tv.z); o[6] = sigm(a1[2]) * lo16(tv.w); o[7] = sigm(a1[3]) * hi16(tv.w);
;                     if (ACC) { o[0] += lo16(pv.x); o[1] += hi16(pv.x); o[2] += lo16(pv.y); o[3] += hi16(pv.y); o[4] += lo16(pv.z); o[5] += hi16(pv.z); o[6] += lo16(pv.w); o[7] += hi16(pv.w); }
;                     u32x4 w; w.x = cvt_pk_bf16(o[0], o[1]); w.y = cvt_pk_bf16(o[2], o[3]); w.z = cvt_pk_bf16(o[4], o[5]); w.w = cvt_pk_bf16(o[6], o[7]);
;                     *(u32x4*)(M + off) = w; } }
	v_mul_f32_e32 v108, 0xbfb8aa3b, v108
	v_mul_f32_e32 v109, 0xbfb8aa3b, v109
	v_pk_mul_f32 v[116:117], v[104:105], v[116:117]
	v_mul_f32_e32 v104, 0xbfb8aa3b, v106
	v_mul_f32_e32 v105, 0xbfb8aa3b, v107
	v_exp_f32_e32 v108, v108
	v_exp_f32_e32 v109, v109
	v_exp_f32_e32 v104, v104
	v_exp_f32_e32 v105, v105
	v_add_f32_e32 v108, 1.0, v108
	v_add_f32_e32 v109, 1.0, v109
	v_add_f32_e32 v104, 1.0, v104
	v_add_f32_e32 v105, 1.0, v105
	v_rcp_f32_e32 v108, v108
	v_rcp_f32_e32 v109, v109
	v_rcp_f32_e32 v104, v104
	v_rcp_f32_e32 v105, v105
	v_lshlrev_b32_e32 v106, 16, v119
	v_and_b32_e32 v107, 0xffff0000, v119
	v_pk_mul_f32 v[108:109], v[108:109], v[120:121]
	v_pk_mul_f32 v[118:119], v[104:105], v[106:107]
	v_cvt_pk_bf16_f32 v104, v108, v109
	v_cvt_pk_bf16_f32 v105, v110, v111
	v_cvt_pk_bf16_f32 v106, v116, v117
	v_cvt_pk_bf16_f32 v107, v118, v119
	global_store_dwordx4 v[112:113], v[104:107], off
	s_nop 1
	v_mov_b32_e32 v104, v204
	v_mov_b32_e32 v105, v205
	v_mov_b32_e32 v106, v206
	v_mov_b32_e32 v107, v207
	v_pk_mul_f32 v[102:103], v[102:103], v[114:115] op_sel_hi:[1,0]
	v_pk_mul_f32 v[96:97], v[96:97], v[114:115] op_sel_hi:[1,0]
	v_mul_f32_e32 v102, 0xbfb8aa3b, v102
	v_mul_f32_e32 v103, 0xbfb8aa3b, v103
	v_exp_f32_e32 v102, v102
	v_exp_f32_e32 v103, v103
	v_mul_f32_e32 v96, 0xbfb8aa3b, v96
	v_mul_f32_e32 v97, 0xbfb8aa3b, v97
	v_exp_f32_e32 v96, v96
	v_exp_f32_e32 v97, v97
	v_add_f32_e32 v102, 1.0, v102
	v_add_f32_e32 v103, 1.0, v103
	v_rcp_f32_e32 v102, v102
	v_rcp_f32_e32 v103, v103
	v_add_f32_e32 v96, 1.0, v96
	v_add_f32_e32 v97, 1.0, v97
	v_rcp_f32_e32 v96, v96
	v_rcp_f32_e32 v97, v97
	v_pk_mul_f32 v[100:101], v[100:101], v[114:115] op_sel_hi:[1,0]
	v_pk_mul_f32 v[98:99], v[98:99], v[114:115] op_sel_hi:[1,0]
	v_mul_f32_e32 v100, 0xbfb8aa3b, v100
	v_mul_f32_e32 v101, 0xbfb8aa3b, v101
	v_exp_f32_e32 v100, v100
	v_exp_f32_e32 v101, v101
	v_add_f32_e32 v100, 1.0, v100
	v_add_f32_e32 v101, 1.0, v101
	v_rcp_f32_e32 v100, v100
	v_rcp_f32_e32 v101, v101
	v_lshlrev_b32_e32 v108, 16, v104
	v_and_b32_e32 v109, 0xffff0000, v104
	v_lshlrev_b32_e32 v104, 16, v105
	v_and_b32_e32 v105, 0xffff0000, v105
	v_pk_mul_f32 v[102:103], v[102:103], v[104:105]
	v_lshlrev_b32_e32 v104, 16, v106
	v_and_b32_e32 v105, 0xffff0000, v106
	v_pk_mul_f32 v[104:105], v[96:97], v[104:105]
	v_mul_f32_e32 v96, 0xbfb8aa3b, v98
	v_mul_f32_e32 v97, 0xbfb8aa3b, v99
	v_exp_f32_e32 v96, v96
	v_exp_f32_e32 v97, v97
	v_lshlrev_b32_e32 v98, 16, v107
	v_and_b32_e32 v99, 0xffff0000, v107
	v_add_f32_e32 v96, 1.0, v96
	v_add_f32_e32 v97, 1.0, v97
	v_rcp_f32_e32 v96, v96
	v_rcp_f32_e32 v97, v97
	v_pk_mul_f32 v[100:101], v[100:101], v[108:109]
	v_pk_mul_f32 v[106:107], v[96:97], v[98:99]
	v_cvt_pk_bf16_f32 v96, v100, v101
	v_cvt_pk_bf16_f32 v97, v102, v103
	v_cvt_pk_bf16_f32 v98, v104, v105
	v_cvt_pk_bf16_f32 v99, v106, v107
	global_store_dwordx4 v[112:113], v[96:99], off offset:256
	s_nop 1
	v_mov_b32_e32 v98, v181
	s_nop 0
	v_or_b32_e32 v96, 32, v162
	v_ashrrev_i32_e32 v97, 31, v96
	v_lshlrev_b64 v[96:97], 11, v[96:97]
	v_lshl_add_u64 v[96:97], s[0:1], 0, v[96:97]
	v_lshl_add_u64 v[96:97], v[96:97], 0, v[164:165]
	s_nop 1
	v_mov_b32_e32 v100, v208
	v_mov_b32_e32 v101, v209
	v_mov_b32_e32 v102, v210
	v_mov_b32_e32 v103, v211
	v_fmamk_f32 v98, v98, 0x3a800000, v187
	v_cmp_gt_f32_e32 vcc, s67, v98
	v_mul_f32_e32 v99, 0x4b800000, v98
	v_lshlrev_b32_e32 v104, 16, v100
	v_cndmask_b32_e32 v98, v98, v99, vcc
	v_rsq_f32_e32 v98, v98
	v_and_b32_e32 v105, 0xffff0000, v100
	v_lshlrev_b32_e32 v100, 16, v101
	v_and_b32_e32 v101, 0xffff0000, v101
	v_mul_f32_e32 v99, 0x45800000, v98
	v_cndmask_b32_e32 v98, v98, v99, vcc
	v_pk_mul_f32 v[94:95], v[94:95], v[98:99] op_sel_hi:[1,0]
	v_pk_mul_f32 v[88:89], v[88:89], v[98:99] op_sel_hi:[1,0]
	v_mul_f32_e32 v94, 0xbfb8aa3b, v94
	v_mul_f32_e32 v95, 0xbfb8aa3b, v95
	v_exp_f32_e32 v94, v94
	v_exp_f32_e32 v95, v95
	v_mul_f32_e32 v88, 0xbfb8aa3b, v88
	v_mul_f32_e32 v89, 0xbfb8aa3b, v89
	v_exp_f32_e32 v88, v88
	v_exp_f32_e32 v89, v89
	v_add_f32_e32 v94, 1.0, v94
	v_add_f32_e32 v95, 1.0, v95
	v_rcp_f32_e32 v94, v94
	v_rcp_f32_e32 v95, v95
	v_add_f32_e32 v88, 1.0, v88
	v_add_f32_e32 v89, 1.0, v89
	v_rcp_f32_e32 v88, v88
	v_rcp_f32_e32 v89, v89
	v_pk_mul_f32 v[92:93], v[92:93], v[98:99] op_sel_hi:[1,0]
	v_pk_mul_f32 v[90:91], v[90:91], v[98:99] op_sel_hi:[1,0]
	v_pk_mul_f32 v[94:95], v[94:95], v[100:101]
	v_lshlrev_b32_e32 v100, 16, v102
	v_and_b32_e32 v101, 0xffff0000, v102
	v_mul_f32_e32 v92, 0xbfb8aa3b, v92
	v_mul_f32_e32 v93, 0xbfb8aa3b, v93
	v_pk_mul_f32 v[100:101], v[88:89], v[100:101]
	v_mul_f32_e32 v88, 0xbfb8aa3b, v90
	v_mul_f32_e32 v89, 0xbfb8aa3b, v91
	v_exp_f32_e32 v92, v92
	v_exp_f32_e32 v93, v93
	v_exp_f32_e32 v88, v88
	v_exp_f32_e32 v89, v89
	v_add_f32_e32 v92, 1.0, v92
	v_add_f32_e32 v93, 1.0, v93
	v_add_f32_e32 v88, 1.0, v88
	v_add_f32_e32 v89, 1.0, v89
	v_rcp_f32_e32 v92, v92
	v_rcp_f32_e32 v93, v93
	v_rcp_f32_e32 v88, v88
	v_rcp_f32_e32 v89, v89
	v_lshlrev_b32_e32 v90, 16, v103
	v_and_b32_e32 v91, 0xffff0000, v103
	v_pk_mul_f32 v[92:93], v[92:93], v[104:105]
	v_pk_mul_f32 v[102:103], v[88:89], v[90:91]
	v_cvt_pk_bf16_f32 v88, v92, v93
	v_cvt_pk_bf16_f32 v89, v94, v95
	v_cvt_pk_bf16_f32 v90, v100, v101
	v_cvt_pk_bf16_f32 v91, v102, v103
	global_store_dwordx4 v[96:97], v[88:91], off
	s_nop 1
	v_mov_b32_e32 v88, v212
	v_mov_b32_e32 v89, v213
	v_mov_b32_e32 v90, v214
	v_mov_b32_e32 v91, v215
	v_pk_mul_f32 v[86:87], v[86:87], v[98:99] op_sel_hi:[1,0]
	v_pk_mul_f32 v[80:81], v[80:81], v[98:99] op_sel_hi:[1,0]
	v_mul_f32_e32 v86, 0xbfb8aa3b, v86
	v_mul_f32_e32 v87, 0xbfb8aa3b, v87
	v_exp_f32_e32 v86, v86
	v_exp_f32_e32 v87, v87
	v_mul_f32_e32 v80, 0xbfb8aa3b, v80
; __device__ __forceinline__ unsigned cvt_pk_bf16(float lo, float hi) { const f32x2_cv v = {lo, hi}; const bf16x2_cv b = __builtin_convertvector(v, bf16x2_cv); return __builtin_bit_cast(unsigned, b); }
; __device__ __forceinline__ float sigm(float x) { return __builtin_amdgcn_rcpf(1.0f + __expf(-x)); }
; __device__ __forceinline__ float lo16(unsigned w) { return __uint_as_float(w << 16); }
; __device__ __forceinline__ float hi16(unsigned w) { return __uint_as_float(w & 0xffff0000u); }
; __device__ __forceinline__ float rstd_of(const float* rowss, int row) { return rsqrtf(rowss[row] * (1.0f / 1024.0f) + 1e-6f); }
;     __device__ __forceinline__ void operator()(const f32x4 (&acc)[2][2][4][2], const pg8::Unit& u, int wr, int wc, int fr, int fq) const {
;     ...
;             for (int m = 0; m < 4; ++m) {
;                 const int row = row0 + ai * 128 + m * 16;
;                 const float s = rstd_of(rowss, row);
; #pragma unroll
;                 for (int bj = 0; bj < 2; ++bj) {
;                     const size_t off = (size_t)row * 1024 + col0 + bj * 128;
;                     const u32x4 tv = *(const u32x4*)(Tm + off);
;                     u32x4 pv = (u32x4){0u, 0u, 0u, 0u};
;                     if (ACC) pv = *(const u32x4*)(M + off);
;                     const f32x4 a0 = acc[ai][bj][m][0] * s, a1 = acc[ai][bj][m][1] * s;
;                     float o[8];
;                     o[0] = sigm(a0[0]) * lo16(tv.x); o[1] = sigm(a0[1]) * hi16(tv.x); o[2] = sigm(a0[2]) * lo16(tv.y); o[3] = sigm(a0[3]) * hi16(tv.y);
;                     o[4] = sigm(a1[0]) * lo16(tv.z); o[5] = sigm(a1[1]) * hi16(tv.z); o[6] = sigm(a1[2]) * lo16(tv.w); o[7] = sigm(a1[3]) * hi16(tv.w);
;                     if (ACC) { o[0] += lo16(pv.x); o[1] += hi16(pv.x); o[2] += lo16(pv.y); o[3] += hi16(pv.y); o[4] += lo16(pv.z); o[5] += hi16(pv.z); o[6] += lo16(pv.w); o[7] += hi16(pv.w); }
;                     u32x4 w; w.x = cvt_pk_bf16(o[0], o[1]); w.y = cvt_pk_bf16(o[2], o[3]); w.z = cvt_pk_bf16(o[4], o[5]); w.w = cvt_pk_bf16(o[6], o[7]);
;                     *(u32x4*)(M + off) = w; } }
	v_mul_f32_e32 v81, 0xbfb8aa3b, v81
	v_exp_f32_e32 v80, v80
	v_exp_f32_e32 v81, v81
	v_add_f32_e32 v86, 1.0, v86
	v_add_f32_e32 v87, 1.0, v87
	v_rcp_f32_e32 v86, v86
	v_rcp_f32_e32 v87, v87
	v_add_f32_e32 v80, 1.0, v80
	v_add_f32_e32 v81, 1.0, v81
	v_rcp_f32_e32 v80, v80
	v_rcp_f32_e32 v81, v81
	v_pk_mul_f32 v[84:85], v[84:85], v[98:99] op_sel_hi:[1,0]
	v_pk_mul_f32 v[82:83], v[82:83], v[98:99] op_sel_hi:[1,0]
	v_mul_f32_e32 v84, 0xbfb8aa3b, v84
	v_mul_f32_e32 v85, 0xbfb8aa3b, v85
	v_exp_f32_e32 v84, v84
	v_exp_f32_e32 v85, v85
	v_add_f32_e32 v84, 1.0, v84
	v_add_f32_e32 v85, 1.0, v85
	v_rcp_f32_e32 v84, v84
	v_rcp_f32_e32 v85, v85
	v_lshlrev_b32_e32 v92, 16, v88
	v_and_b32_e32 v93, 0xffff0000, v88
	v_lshlrev_b32_e32 v88, 16, v89
	v_and_b32_e32 v89, 0xffff0000, v89
	v_pk_mul_f32 v[86:87], v[86:87], v[88:89]
	v_lshlrev_b32_e32 v88, 16, v90
	v_and_b32_e32 v89, 0xffff0000, v90
	v_pk_mul_f32 v[88:89], v[80:81], v[88:89]
	v_mul_f32_e32 v80, 0xbfb8aa3b, v82
	v_mul_f32_e32 v81, 0xbfb8aa3b, v83
	v_exp_f32_e32 v80, v80
	v_exp_f32_e32 v81, v81
	v_lshlrev_b32_e32 v82, 16, v91
	v_and_b32_e32 v83, 0xffff0000, v91
	v_add_f32_e32 v80, 1.0, v80
	v_add_f32_e32 v81, 1.0, v81
	v_rcp_f32_e32 v80, v80
	v_rcp_f32_e32 v81, v81
	v_pk_mul_f32 v[84:85], v[84:85], v[92:93]
	v_pk_mul_f32 v[90:91], v[80:81], v[82:83]
	v_cvt_pk_bf16_f32 v80, v84, v85
	v_cvt_pk_bf16_f32 v81, v86, v87
	v_cvt_pk_bf16_f32 v82, v88, v89
	v_cvt_pk_bf16_f32 v83, v90, v91
	global_store_dwordx4 v[96:97], v[80:83], off offset:256
	s_nop 1
	v_mov_b32_e32 v82, v182
	s_nop 0
	v_or_b32_e32 v80, 48, v162
	v_ashrrev_i32_e32 v81, 31, v80
	v_lshlrev_b64 v[80:81], 11, v[80:81]
	v_lshl_add_u64 v[80:81], s[0:1], 0, v[80:81]
	v_lshl_add_u64 v[80:81], v[80:81], 0, v[164:165]
	s_nop 1
	v_mov_b32_e32 v84, v216
	v_mov_b32_e32 v85, v217
	v_mov_b32_e32 v86, v218
	v_mov_b32_e32 v87, v219
	v_fmamk_f32 v82, v82, 0x3a800000, v187
	v_cmp_gt_f32_e32 vcc, s67, v82
	v_mul_f32_e32 v83, 0x4b800000, v82
	v_lshlrev_b32_e32 v88, 16, v84
	v_cndmask_b32_e32 v82, v82, v83, vcc
	v_rsq_f32_e32 v82, v82
	v_and_b32_e32 v89, 0xffff0000, v84
	v_lshlrev_b32_e32 v84, 16, v85
	v_and_b32_e32 v85, 0xffff0000, v85
	v_mul_f32_e32 v83, 0x45800000, v82
	v_cndmask_b32_e32 v82, v82, v83, vcc
	v_pk_mul_f32 v[78:79], v[78:79], v[82:83] op_sel_hi:[1,0]
	v_pk_mul_f32 v[72:73], v[72:73], v[82:83] op_sel_hi:[1,0]
	v_mul_f32_e32 v78, 0xbfb8aa3b, v78
	v_mul_f32_e32 v79, 0xbfb8aa3b, v79
	v_exp_f32_e32 v78, v78
	v_exp_f32_e32 v79, v79
	v_mul_f32_e32 v72, 0xbfb8aa3b, v72
	v_mul_f32_e32 v73, 0xbfb8aa3b, v73
	v_exp_f32_e32 v72, v72
	v_exp_f32_e32 v73, v73
	v_add_f32_e32 v78, 1.0, v78
	v_add_f32_e32 v79, 1.0, v79
	v_rcp_f32_e32 v78, v78
	v_rcp_f32_e32 v79, v79
	v_add_f32_e32 v72, 1.0, v72
	v_add_f32_e32 v73, 1.0, v73
	v_rcp_f32_e32 v72, v72
	v_rcp_f32_e32 v73, v73
	v_pk_mul_f32 v[76:77], v[76:77], v[82:83] op_sel_hi:[1,0]
	v_pk_mul_f32 v[74:75], v[74:75], v[82:83] op_sel_hi:[1,0]
	v_pk_mul_f32 v[78:79], v[78:79], v[84:85]
	v_lshlrev_b32_e32 v84, 16, v86
	v_and_b32_e32 v85, 0xffff0000, v86
	v_mul_f32_e32 v76, 0xbfb8aa3b, v76
	v_mul_f32_e32 v77, 0xbfb8aa3b, v77
	v_pk_mul_f32 v[84:85], v[72:73], v[84:85]
	v_mul_f32_e32 v72, 0xbfb8aa3b, v74
	v_mul_f32_e32 v73, 0xbfb8aa3b, v75
	v_exp_f32_e32 v76, v76
	v_exp_f32_e32 v77, v77
	v_exp_f32_e32 v72, v72
	v_exp_f32_e32 v73, v73
	v_add_f32_e32 v76, 1.0, v76
	v_add_f32_e32 v77, 1.0, v77
	v_add_f32_e32 v72, 1.0, v72
	v_add_f32_e32 v73, 1.0, v73
	v_rcp_f32_e32 v76, v76
	v_rcp_f32_e32 v77, v77
	v_rcp_f32_e32 v72, v72
	v_rcp_f32_e32 v73, v73
	v_lshlrev_b32_e32 v74, 16, v87
	v_and_b32_e32 v75, 0xffff0000, v87
	v_pk_mul_f32 v[76:77], v[76:77], v[88:89]
	v_pk_mul_f32 v[86:87], v[72:73], v[74:75]
	v_cvt_pk_bf16_f32 v72, v76, v77
	v_cvt_pk_bf16_f32 v73, v78, v79
	v_cvt_pk_bf16_f32 v74, v84, v85
	v_cvt_pk_bf16_f32 v75, v86, v87
	global_store_dwordx4 v[80:81], v[72:75], off
	s_nop 1
	v_mov_b32_e32 v72, v220
	v_mov_b32_e32 v73, v221
	v_mov_b32_e32 v74, v222
	v_mov_b32_e32 v75, v223
	v_pk_mul_f32 v[70:71], v[70:71], v[82:83] op_sel_hi:[1,0]
	v_pk_mul_f32 v[64:65], v[64:65], v[82:83] op_sel_hi:[1,0]
	v_mul_f32_e32 v70, 0xbfb8aa3b, v70
	v_mul_f32_e32 v71, 0xbfb8aa3b, v71
	v_exp_f32_e32 v70, v70
	v_exp_f32_e32 v71, v71
	v_mul_f32_e32 v64, 0xbfb8aa3b, v64
	v_mul_f32_e32 v65, 0xbfb8aa3b, v65
	v_exp_f32_e32 v64, v64
	v_exp_f32_e32 v65, v65
	v_add_f32_e32 v70, 1.0, v70
	v_add_f32_e32 v71, 1.0, v71
	v_rcp_f32_e32 v70, v70
	v_rcp_f32_e32 v71, v71
	v_add_f32_e32 v64, 1.0, v64
	v_add_f32_e32 v65, 1.0, v65
	v_rcp_f32_e32 v64, v64
	v_rcp_f32_e32 v65, v65
	v_pk_mul_f32 v[68:69], v[68:69], v[82:83] op_sel_hi:[1,0]
	v_pk_mul_f32 v[66:67], v[66:67], v[82:83] op_sel_hi:[1,0]
	v_mul_f32_e32 v68, 0xbfb8aa3b, v68
	v_mul_f32_e32 v69, 0xbfb8aa3b, v69
	v_exp_f32_e32 v68, v68
	v_exp_f32_e32 v69, v69
	v_add_f32_e32 v68, 1.0, v68
	v_add_f32_e32 v69, 1.0, v69
	v_rcp_f32_e32 v68, v68
	v_rcp_f32_e32 v69, v69
	v_lshlrev_b32_e32 v76, 16, v72
	v_and_b32_e32 v77, 0xffff0000, v72
	v_lshlrev_b32_e32 v72, 16, v73
	v_and_b32_e32 v73, 0xffff0000, v73
	v_pk_mul_f32 v[70:71], v[70:71], v[72:73]
	v_lshlrev_b32_e32 v72, 16, v74
	v_and_b32_e32 v73, 0xffff0000, v74
	v_pk_mul_f32 v[72:73], v[64:65], v[72:73]
	v_mul_f32_e32 v64, 0xbfb8aa3b, v66
	v_mul_f32_e32 v65, 0xbfb8aa3b, v67
	v_exp_f32_e32 v64, v64
	v_exp_f32_e32 v65, v65
	v_lshlrev_b32_e32 v66, 16, v75
	v_and_b32_e32 v67, 0xffff0000, v75
	v_add_f32_e32 v64, 1.0, v64
	v_add_f32_e32 v65, 1.0, v65
	v_rcp_f32_e32 v64, v64
	v_rcp_f32_e32 v65, v65
	v_pk_mul_f32 v[68:69], v[68:69], v[76:77]
	v_pk_mul_f32 v[74:75], v[64:65], v[66:67]
	v_cvt_pk_bf16_f32 v64, v68, v69
	v_cvt_pk_bf16_f32 v65, v70, v71
	v_cvt_pk_bf16_f32 v66, v72, v73
; __device__ __forceinline__ unsigned cvt_pk_bf16(float lo, float hi) { const f32x2_cv v = {lo, hi}; const bf16x2_cv b = __builtin_convertvector(v, bf16x2_cv); return __builtin_bit_cast(unsigned, b); }
; __device__ __forceinline__ float sigm(float x) { return __builtin_amdgcn_rcpf(1.0f + __expf(-x)); }
; __device__ __forceinline__ float lo16(unsigned w) { return __uint_as_float(w << 16); }
; __device__ __forceinline__ float hi16(unsigned w) { return __uint_as_float(w & 0xffff0000u); }
; __device__ __forceinline__ float rstd_of(const float* rowss, int row) { return rsqrtf(rowss[row] * (1.0f / 1024.0f) + 1e-6f); }
;     __device__ __forceinline__ void operator()(const f32x4 (&acc)[2][2][4][2], const pg8::Unit& u, int wr, int wc, int fr, int fq) const {
;     ...
;             for (int m = 0; m < 4; ++m) {
;                 const int row = row0 + ai * 128 + m * 16;
;                 const float s = rstd_of(rowss, row);
; #pragma unroll
;                 for (int bj = 0; bj < 2; ++bj) {
;                     const size_t off = (size_t)row * 1024 + col0 + bj * 128;
;                     const u32x4 tv = *(const u32x4*)(Tm + off);
;                     u32x4 pv = (u32x4){0u, 0u, 0u, 0u};
;                     if (ACC) pv = *(const u32x4*)(M + off);
;                     const f32x4 a0 = acc[ai][bj][m][0] * s, a1 = acc[ai][bj][m][1] * s;
;                     float o[8];
;                     o[0] = sigm(a0[0]) * lo16(tv.x); o[1] = sigm(a0[1]) * hi16(tv.x); o[2] = sigm(a0[2]) * lo16(tv.y); o[3] = sigm(a0[3]) * hi16(tv.y);
;                     o[4] = sigm(a1[0]) * lo16(tv.z); o[5] = sigm(a1[1]) * hi16(tv.z); o[6] = sigm(a1[2]) * lo16(tv.w); o[7] = sigm(a1[3]) * hi16(tv.w);
;                     if (ACC) { o[0] += lo16(pv.x); o[1] += hi16(pv.x); o[2] += lo16(pv.y); o[3] += hi16(pv.y); o[4] += lo16(pv.z); o[5] += hi16(pv.z); o[6] += lo16(pv.w); o[7] += hi16(pv.w); }
;                     u32x4 w; w.x = cvt_pk_bf16(o[0], o[1]); w.y = cvt_pk_bf16(o[2], o[3]); w.z = cvt_pk_bf16(o[4], o[5]); w.w = cvt_pk_bf16(o[6], o[7]);
;                     *(u32x4*)(M + off) = w; } }
	v_cvt_pk_bf16_f32 v67, v74, v75
	global_store_dwordx4 v[80:81], v[64:67], off offset:256
	s_nop 1
	v_mov_b32_e32 v64, v183
	v_fmamk_f32 v64, v64, 0x3a800000, v187
	v_cmp_gt_f32_e32 vcc, s67, v64
	v_mul_f32_e32 v65, 0x4b800000, v64
	s_nop 0
	v_cndmask_b32_e32 v64, v64, v65, vcc
	v_rsq_f32_e32 v64, v64
	s_nop 0
	v_mul_f32_e32 v65, 0x45800000, v64
	v_cndmask_b32_e32 v66, v64, v65, vcc
	v_add_co_u32_e32 v72, vcc, s2, v158
	v_pk_mul_f32 v[62:63], v[62:63], v[66:67] op_sel_hi:[1,0]
	s_nop 0
	v_addc_co_u32_e32 v73, vcc, 0, v159, vcc
	s_nop 1
	v_mov_b32_e32 v68, v224
	v_mov_b32_e32 v69, v225
	v_mov_b32_e32 v70, v226
	v_mov_b32_e32 v71, v227
	v_pk_mul_f32 v[56:57], v[56:57], v[66:67] op_sel_hi:[1,0]
	v_mul_f32_e32 v62, 0xbfb8aa3b, v62
	v_mul_f32_e32 v63, 0xbfb8aa3b, v63
	v_exp_f32_e32 v62, v62
	v_exp_f32_e32 v63, v63
	v_mul_f32_e32 v56, 0xbfb8aa3b, v56
	v_mul_f32_e32 v57, 0xbfb8aa3b, v57
	v_exp_f32_e32 v56, v56
	v_exp_f32_e32 v57, v57
	v_add_f32_e32 v62, 1.0, v62
	v_add_f32_e32 v63, 1.0, v63
	v_rcp_f32_e32 v62, v62
	v_rcp_f32_e32 v63, v63
	v_add_f32_e32 v56, 1.0, v56
	v_add_f32_e32 v57, 1.0, v57
	v_rcp_f32_e32 v56, v56
	v_rcp_f32_e32 v57, v57
	v_pk_mul_f32 v[60:61], v[60:61], v[66:67] op_sel_hi:[1,0]
	v_pk_mul_f32 v[58:59], v[58:59], v[66:67] op_sel_hi:[1,0]
	v_mul_f32_e32 v60, 0xbfb8aa3b, v60
	v_mul_f32_e32 v61, 0xbfb8aa3b, v61
	v_exp_f32_e32 v60, v60
	v_exp_f32_e32 v61, v61
	v_lshl_add_u64 v[64:65], v[158:159], 0, s[4:5]
	v_pk_mul_f32 v[54:55], v[54:55], v[66:67] op_sel_hi:[1,0]
	v_add_f32_e32 v60, 1.0, v60
	v_add_f32_e32 v61, 1.0, v61
	v_rcp_f32_e32 v60, v60
	v_rcp_f32_e32 v61, v61
	v_pk_mul_f32 v[48:49], v[48:49], v[66:67] op_sel_hi:[1,0]
	v_mul_f32_e32 v54, 0xbfb8aa3b, v54
	v_mul_f32_e32 v55, 0xbfb8aa3b, v55
	v_exp_f32_e32 v54, v54
	v_exp_f32_e32 v55, v55
	v_mul_f32_e32 v48, 0xbfb8aa3b, v48
	v_mul_f32_e32 v49, 0xbfb8aa3b, v49
	v_exp_f32_e32 v48, v48
	v_exp_f32_e32 v49, v49
	v_add_f32_e32 v54, 1.0, v54
	v_add_f32_e32 v55, 1.0, v55
	v_rcp_f32_e32 v54, v54
	v_rcp_f32_e32 v55, v55
	v_add_f32_e32 v48, 1.0, v48
	v_add_f32_e32 v49, 1.0, v49
	v_rcp_f32_e32 v48, v48
	v_rcp_f32_e32 v49, v49
	v_pk_mul_f32 v[52:53], v[52:53], v[66:67] op_sel_hi:[1,0]
	v_pk_mul_f32 v[50:51], v[50:51], v[66:67] op_sel_hi:[1,0]
	v_mul_f32_e32 v52, 0xbfb8aa3b, v52
	v_mul_f32_e32 v53, 0xbfb8aa3b, v53
	v_exp_f32_e32 v52, v52
	v_exp_f32_e32 v53, v53
	s_mov_b32 s2, 0x48000
	s_mov_b64 s[4:5], 0x48000
	v_add_f32_e32 v52, 1.0, v52
	v_add_f32_e32 v53, 1.0, v53
	v_rcp_f32_e32 v52, v52
	v_rcp_f32_e32 v53, v53
	v_lshlrev_b32_e32 v74, 16, v68
	v_and_b32_e32 v75, 0xffff0000, v68
	v_lshlrev_b32_e32 v68, 16, v69
	v_and_b32_e32 v69, 0xffff0000, v69
	v_pk_mul_f32 v[62:63], v[62:63], v[68:69]
	v_lshlrev_b32_e32 v68, 16, v70
	v_and_b32_e32 v69, 0xffff0000, v70
	v_pk_mul_f32 v[68:69], v[56:57], v[68:69]
	v_mul_f32_e32 v56, 0xbfb8aa3b, v58
	v_mul_f32_e32 v57, 0xbfb8aa3b, v59
	v_exp_f32_e32 v56, v56
	v_exp_f32_e32 v57, v57
	v_lshlrev_b32_e32 v58, 16, v71
	v_and_b32_e32 v59, 0xffff0000, v71
	v_add_f32_e32 v56, 1.0, v56
	v_add_f32_e32 v57, 1.0, v57
	v_rcp_f32_e32 v56, v56
	v_rcp_f32_e32 v57, v57
	v_pk_mul_f32 v[60:61], v[60:61], v[74:75]
	v_pk_mul_f32 v[70:71], v[56:57], v[58:59]
	v_cvt_pk_bf16_f32 v56, v60, v61
	v_cvt_pk_bf16_f32 v57, v62, v63
	v_cvt_pk_bf16_f32 v58, v68, v69
	v_cvt_pk_bf16_f32 v59, v70, v71
	global_store_dwordx4 v[72:73], v[56:59], off
	s_nop 1
	v_mov_b32_e32 v56, v228
	v_mov_b32_e32 v57, v229
	v_mov_b32_e32 v58, v230
	v_mov_b32_e32 v59, v231
	v_lshlrev_b32_e32 v60, 16, v56
	v_and_b32_e32 v61, 0xffff0000, v56
	v_lshlrev_b32_e32 v56, 16, v57
	v_and_b32_e32 v57, 0xffff0000, v57
	v_pk_mul_f32 v[54:55], v[54:55], v[56:57]
	v_lshlrev_b32_e32 v56, 16, v58
	v_and_b32_e32 v57, 0xffff0000, v58
	v_pk_mul_f32 v[56:57], v[48:49], v[56:57]
	v_mul_f32_e32 v48, 0xbfb8aa3b, v50
	v_mul_f32_e32 v49, 0xbfb8aa3b, v51
	v_exp_f32_e32 v48, v48
	v_exp_f32_e32 v49, v49
	v_lshlrev_b32_e32 v50, 16, v59
	v_and_b32_e32 v51, 0xffff0000, v59
	v_add_f32_e32 v48, 1.0, v48
	v_add_f32_e32 v49, 1.0, v49
	v_rcp_f32_e32 v48, v48
	v_rcp_f32_e32 v49, v49
	v_pk_mul_f32 v[52:53], v[52:53], v[60:61]
	v_pk_mul_f32 v[58:59], v[48:49], v[50:51]
	v_cvt_pk_bf16_f32 v48, v52, v53
	v_cvt_pk_bf16_f32 v49, v54, v55
	v_cvt_pk_bf16_f32 v50, v56, v57
	v_cvt_pk_bf16_f32 v51, v58, v59
	global_store_dwordx4 v[64:65], v[48:51], off offset:256
	s_nop 1
	v_mov_b32_e32 v48, v240
	v_fmamk_f32 v48, v48, 0x3a800000, v187
	v_cmp_gt_f32_e32 vcc, s67, v48
	v_mul_f32_e32 v49, 0x4b800000, v48
	s_nop 0
	v_cndmask_b32_e32 v48, v48, v49, vcc
	v_rsq_f32_e32 v48, v48
	s_nop 0
	v_mul_f32_e32 v49, 0x45800000, v48
	v_cndmask_b32_e32 v50, v48, v49, vcc
	v_add_co_u32_e32 v56, vcc, s2, v158
	v_pk_mul_f32 v[46:47], v[46:47], v[50:51] op_sel_hi:[1,0]
	s_nop 0
	v_addc_co_u32_e32 v57, vcc, 0, v159, vcc
	s_nop 1
	v_mov_b32_e32 v52, v232
	v_mov_b32_e32 v53, v233
	v_mov_b32_e32 v54, v234
	v_mov_b32_e32 v55, v235
	v_pk_mul_f32 v[40:41], v[40:41], v[50:51] op_sel_hi:[1,0]
	v_mul_f32_e32 v46, 0xbfb8aa3b, v46
	v_mul_f32_e32 v47, 0xbfb8aa3b, v47
	v_exp_f32_e32 v46, v46
	v_exp_f32_e32 v47, v47
	v_mul_f32_e32 v40, 0xbfb8aa3b, v40
	v_mul_f32_e32 v41, 0xbfb8aa3b, v41
	v_exp_f32_e32 v40, v40
	v_exp_f32_e32 v41, v41
	v_add_f32_e32 v46, 1.0, v46
	v_add_f32_e32 v47, 1.0, v47
	v_rcp_f32_e32 v46, v46
	v_rcp_f32_e32 v47, v47
	v_add_f32_e32 v40, 1.0, v40
	v_add_f32_e32 v41, 1.0, v41
	v_rcp_f32_e32 v40, v40
	v_rcp_f32_e32 v41, v41
	v_pk_mul_f32 v[44:45], v[44:45], v[50:51] op_sel_hi:[1,0]
	v_pk_mul_f32 v[42:43], v[42:43], v[50:51] op_sel_hi:[1,0]
	v_mul_f32_e32 v44, 0xbfb8aa3b, v44
	v_mul_f32_e32 v45, 0xbfb8aa3b, v45
	v_exp_f32_e32 v44, v44
	v_exp_f32_e32 v45, v45
; __device__ __forceinline__ unsigned cvt_pk_bf16(float lo, float hi) { const f32x2_cv v = {lo, hi}; const bf16x2_cv b = __builtin_convertvector(v, bf16x2_cv); return __builtin_bit_cast(unsigned, b); }
; __device__ __forceinline__ float sigm(float x) { return __builtin_amdgcn_rcpf(1.0f + __expf(-x)); }
; __device__ __forceinline__ float lo16(unsigned w) { return __uint_as_float(w << 16); }
; __device__ __forceinline__ float hi16(unsigned w) { return __uint_as_float(w & 0xffff0000u); }
; __device__ __forceinline__ float rstd_of(const float* rowss, int row) { return rsqrtf(rowss[row] * (1.0f / 1024.0f) + 1e-6f); }
;     __device__ __forceinline__ void operator()(const f32x4 (&acc)[2][2][4][2], const pg8::Unit& u, int wr, int wc, int fr, int fq) const {
;     ...
;             for (int m = 0; m < 4; ++m) {
;                 const int row = row0 + ai * 128 + m * 16;
;                 const float s = rstd_of(rowss, row);
; #pragma unroll
;                 for (int bj = 0; bj < 2; ++bj) {
;                     const size_t off = (size_t)row * 1024 + col0 + bj * 128;
;                     const u32x4 tv = *(const u32x4*)(Tm + off);
;                     u32x4 pv = (u32x4){0u, 0u, 0u, 0u};
;                     if (ACC) pv = *(const u32x4*)(M + off);
;                     const f32x4 a0 = acc[ai][bj][m][0] * s, a1 = acc[ai][bj][m][1] * s;
;                     float o[8];
;                     o[0] = sigm(a0[0]) * lo16(tv.x); o[1] = sigm(a0[1]) * hi16(tv.x); o[2] = sigm(a0[2]) * lo16(tv.y); o[3] = sigm(a0[3]) * hi16(tv.y);
;                     o[4] = sigm(a1[0]) * lo16(tv.z); o[5] = sigm(a1[1]) * hi16(tv.z); o[6] = sigm(a1[2]) * lo16(tv.w); o[7] = sigm(a1[3]) * hi16(tv.w);
;                     if (ACC) { o[0] += lo16(pv.x); o[1] += hi16(pv.x); o[2] += lo16(pv.y); o[3] += hi16(pv.y); o[4] += lo16(pv.z); o[5] += hi16(pv.z); o[6] += lo16(pv.w); o[7] += hi16(pv.w); }
;                     u32x4 w; w.x = cvt_pk_bf16(o[0], o[1]); w.y = cvt_pk_bf16(o[2], o[3]); w.z = cvt_pk_bf16(o[4], o[5]); w.w = cvt_pk_bf16(o[6], o[7]);
;                     *(u32x4*)(M + off) = w; } }
	v_lshl_add_u64 v[48:49], v[158:159], 0, s[4:5]
	v_pk_mul_f32 v[38:39], v[38:39], v[50:51] op_sel_hi:[1,0]
	v_add_f32_e32 v44, 1.0, v44
	v_add_f32_e32 v45, 1.0, v45
	v_rcp_f32_e32 v44, v44
	v_rcp_f32_e32 v45, v45
	v_pk_mul_f32 v[32:33], v[32:33], v[50:51] op_sel_hi:[1,0]
	v_mul_f32_e32 v38, 0xbfb8aa3b, v38
	v_mul_f32_e32 v39, 0xbfb8aa3b, v39
	v_exp_f32_e32 v38, v38
	v_exp_f32_e32 v39, v39
	v_mul_f32_e32 v32, 0xbfb8aa3b, v32
	v_mul_f32_e32 v33, 0xbfb8aa3b, v33
	v_exp_f32_e32 v32, v32
	v_exp_f32_e32 v33, v33
	v_add_f32_e32 v38, 1.0, v38
	v_add_f32_e32 v39, 1.0, v39
	v_rcp_f32_e32 v38, v38
	v_rcp_f32_e32 v39, v39
	v_add_f32_e32 v32, 1.0, v32
	v_add_f32_e32 v33, 1.0, v33
	v_rcp_f32_e32 v32, v32
	v_rcp_f32_e32 v33, v33
	v_pk_mul_f32 v[36:37], v[36:37], v[50:51] op_sel_hi:[1,0]
	v_pk_mul_f32 v[34:35], v[34:35], v[50:51] op_sel_hi:[1,0]
	v_mul_f32_e32 v36, 0xbfb8aa3b, v36
	v_mul_f32_e32 v37, 0xbfb8aa3b, v37
	v_exp_f32_e32 v36, v36
	v_exp_f32_e32 v37, v37
	s_mov_b32 s2, 0x50000
	s_mov_b64 s[4:5], 0x50000
	v_add_f32_e32 v36, 1.0, v36
	v_add_f32_e32 v37, 1.0, v37
	v_rcp_f32_e32 v36, v36
	v_rcp_f32_e32 v37, v37
	v_lshlrev_b32_e32 v58, 16, v52
	v_and_b32_e32 v59, 0xffff0000, v52
	v_lshlrev_b32_e32 v52, 16, v53
	v_and_b32_e32 v53, 0xffff0000, v53
	v_pk_mul_f32 v[46:47], v[46:47], v[52:53]
	v_lshlrev_b32_e32 v52, 16, v54
	v_and_b32_e32 v53, 0xffff0000, v54
	v_pk_mul_f32 v[52:53], v[40:41], v[52:53]
	v_mul_f32_e32 v40, 0xbfb8aa3b, v42
	v_mul_f32_e32 v41, 0xbfb8aa3b, v43
	v_exp_f32_e32 v40, v40
	v_exp_f32_e32 v41, v41
	v_lshlrev_b32_e32 v42, 16, v55
	v_and_b32_e32 v43, 0xffff0000, v55
	v_add_f32_e32 v40, 1.0, v40
	v_add_f32_e32 v41, 1.0, v41
	v_rcp_f32_e32 v40, v40
	v_rcp_f32_e32 v41, v41
	v_pk_mul_f32 v[44:45], v[44:45], v[58:59]
	v_pk_mul_f32 v[54:55], v[40:41], v[42:43]
	v_cvt_pk_bf16_f32 v40, v44, v45
	v_cvt_pk_bf16_f32 v41, v46, v47
	v_cvt_pk_bf16_f32 v42, v52, v53
	v_cvt_pk_bf16_f32 v43, v54, v55
	global_store_dwordx4 v[56:57], v[40:43], off
	s_nop 1
	v_mov_b32_e32 v40, v236
	v_mov_b32_e32 v41, v237
	v_mov_b32_e32 v42, v238
	v_mov_b32_e32 v43, v239
	v_lshlrev_b32_e32 v44, 16, v40
	v_and_b32_e32 v45, 0xffff0000, v40
	v_lshlrev_b32_e32 v40, 16, v41
	v_and_b32_e32 v41, 0xffff0000, v41
	v_pk_mul_f32 v[38:39], v[38:39], v[40:41]
	v_lshlrev_b32_e32 v40, 16, v42
	v_and_b32_e32 v41, 0xffff0000, v42
	v_pk_mul_f32 v[40:41], v[32:33], v[40:41]
	v_mul_f32_e32 v32, 0xbfb8aa3b, v34
	v_mul_f32_e32 v33, 0xbfb8aa3b, v35
	v_exp_f32_e32 v32, v32
	v_exp_f32_e32 v33, v33
	v_lshlrev_b32_e32 v34, 16, v43
	v_and_b32_e32 v35, 0xffff0000, v43
	v_add_f32_e32 v32, 1.0, v32
	v_add_f32_e32 v33, 1.0, v33
	v_rcp_f32_e32 v32, v32
	v_rcp_f32_e32 v33, v33
	v_pk_mul_f32 v[36:37], v[36:37], v[44:45]
	v_pk_mul_f32 v[42:43], v[32:33], v[34:35]
	v_cvt_pk_bf16_f32 v32, v36, v37
	v_cvt_pk_bf16_f32 v33, v38, v39
	v_cvt_pk_bf16_f32 v34, v40, v41
	v_cvt_pk_bf16_f32 v35, v42, v43
	global_store_dwordx4 v[48:49], v[32:35], off offset:256
	s_nop 1
	v_mov_b32_e32 v32, v241
	v_fmamk_f32 v32, v32, 0x3a800000, v187
	v_cmp_gt_f32_e32 vcc, s67, v32
	v_mul_f32_e32 v33, 0x4b800000, v32
	s_nop 0
	v_cndmask_b32_e32 v32, v32, v33, vcc
	v_rsq_f32_e32 v32, v32
	s_nop 0
	v_mul_f32_e32 v33, 0x45800000, v32
	v_cndmask_b32_e32 v34, v32, v33, vcc
	v_add_co_u32_e32 v40, vcc, s2, v158
	v_pk_mul_f32 v[30:31], v[30:31], v[34:35] op_sel_hi:[1,0]
	s_nop 0
	v_addc_co_u32_e32 v41, vcc, 0, v159, vcc
	s_nop 1
	v_mov_b32_e32 v36, v244
	v_mov_b32_e32 v37, v245
	v_mov_b32_e32 v38, v246
	v_mov_b32_e32 v39, v247
	v_pk_mul_f32 v[24:25], v[24:25], v[34:35] op_sel_hi:[1,0]
	v_mul_f32_e32 v30, 0xbfb8aa3b, v30
	v_mul_f32_e32 v31, 0xbfb8aa3b, v31
	v_exp_f32_e32 v30, v30
	v_exp_f32_e32 v31, v31
	v_mul_f32_e32 v24, 0xbfb8aa3b, v24
	v_mul_f32_e32 v25, 0xbfb8aa3b, v25
	v_exp_f32_e32 v24, v24
	v_exp_f32_e32 v25, v25
	v_add_f32_e32 v30, 1.0, v30
	v_add_f32_e32 v31, 1.0, v31
	v_rcp_f32_e32 v30, v30
	v_rcp_f32_e32 v31, v31
	v_add_f32_e32 v24, 1.0, v24
	v_add_f32_e32 v25, 1.0, v25
	v_rcp_f32_e32 v24, v24
	v_rcp_f32_e32 v25, v25
	v_pk_mul_f32 v[28:29], v[28:29], v[34:35] op_sel_hi:[1,0]
	v_pk_mul_f32 v[26:27], v[26:27], v[34:35] op_sel_hi:[1,0]
	v_mul_f32_e32 v28, 0xbfb8aa3b, v28
	v_mul_f32_e32 v29, 0xbfb8aa3b, v29
	v_exp_f32_e32 v28, v28
	v_exp_f32_e32 v29, v29
	v_lshl_add_u64 v[32:33], v[158:159], 0, s[4:5]
	v_pk_mul_f32 v[22:23], v[22:23], v[34:35] op_sel_hi:[1,0]
	v_add_f32_e32 v28, 1.0, v28
	v_add_f32_e32 v29, 1.0, v29
	v_rcp_f32_e32 v28, v28
	v_rcp_f32_e32 v29, v29
	v_pk_mul_f32 v[16:17], v[16:17], v[34:35] op_sel_hi:[1,0]
	v_mul_f32_e32 v22, 0xbfb8aa3b, v22
	v_mul_f32_e32 v23, 0xbfb8aa3b, v23
	v_exp_f32_e32 v22, v22
	v_exp_f32_e32 v23, v23
	v_mul_f32_e32 v16, 0xbfb8aa3b, v16
	v_mul_f32_e32 v17, 0xbfb8aa3b, v17
	v_exp_f32_e32 v16, v16
	v_exp_f32_e32 v17, v17
	v_add_f32_e32 v22, 1.0, v22
	v_add_f32_e32 v23, 1.0, v23
	v_rcp_f32_e32 v22, v22
	v_rcp_f32_e32 v23, v23
	v_add_f32_e32 v16, 1.0, v16
	v_add_f32_e32 v17, 1.0, v17
	v_rcp_f32_e32 v16, v16
	v_rcp_f32_e32 v17, v17
	v_pk_mul_f32 v[20:21], v[20:21], v[34:35] op_sel_hi:[1,0]
	v_pk_mul_f32 v[18:19], v[18:19], v[34:35] op_sel_hi:[1,0]
	v_mul_f32_e32 v20, 0xbfb8aa3b, v20
	v_mul_f32_e32 v21, 0xbfb8aa3b, v21
	v_exp_f32_e32 v20, v20
	v_exp_f32_e32 v21, v21
	s_mov_b32 s2, 0x58000
	s_mov_b64 s[4:5], 0x58000
	v_add_f32_e32 v20, 1.0, v20
	v_add_f32_e32 v21, 1.0, v21
	v_rcp_f32_e32 v20, v20
	v_rcp_f32_e32 v21, v21
	v_lshlrev_b32_e32 v42, 16, v36
	v_and_b32_e32 v43, 0xffff0000, v36
	v_lshlrev_b32_e32 v36, 16, v37
	v_and_b32_e32 v37, 0xffff0000, v37
	v_pk_mul_f32 v[30:31], v[30:31], v[36:37]
	v_lshlrev_b32_e32 v36, 16, v38
	v_and_b32_e32 v37, 0xffff0000, v38
	v_pk_mul_f32 v[36:37], v[24:25], v[36:37]
; __device__ __forceinline__ unsigned cvt_pk_bf16(float lo, float hi) { const f32x2_cv v = {lo, hi}; const bf16x2_cv b = __builtin_convertvector(v, bf16x2_cv); return __builtin_bit_cast(unsigned, b); }
; template <class Epi, class Sched, bool STAMP = false>
; __device__ __forceinline__ void gemm_phase(PG8_LAS unsigned char* lds, const Gemm g, const Sched& S, const Epi& E, unsigned long long* stamps) {
;     ...
;         if constexpr (!Epi::AFTER_DRAIN) { E(acc, cur, wr, wc, fr, fq); S.done(cur); }
;         if (!has_next) break;
; #pragma unroll
;         for (int a = 0; a < 2; ++a)
; #pragma unroll
;             for (int b = 0; b < 2; ++b)
; #pragma unroll
;                 for (int m = 0; m < 4; ++m)
; #pragma unroll
;                     for (int n = 0; n < 2; ++n) acc[a][b][m][n] = (f32x4){0.f, 0.f, 0.f, 0.f};
;         cur = nxt; cA = nA; cB = nB; ++ui;
;     }
;     PG8_WAIT_V(0);
;     if (wr == 0) PG8_BAR;
;     PG8_BAR;
;     __device__ __forceinline__ void operator()(const f32x4 (&acc)[2][2][4][2], const pg8::Unit& u, int wr, int wc, int fr, int fq) const {
;     ...
;             for (int m = 0; m < 4; ++m) {
;                 const int row = row0 + ai * 128 + m * 16;
;                 const float s = rstd_of(rowss, row);
; #pragma unroll
;                 for (int bj = 0; bj < 2; ++bj) {
;                     const size_t off = (size_t)row * 1024 + col0 + bj * 128;
;                     const u32x4 tv = *(const u32x4*)(Tm + off);
;                     u32x4 pv = (u32x4){0u, 0u, 0u, 0u};
;                     if (ACC) pv = *(const u32x4*)(M + off);
;                     const f32x4 a0 = acc[ai][bj][m][0] * s, a1 = acc[ai][bj][m][1] * s;
;                     float o[8];
;                     o[0] = sigm(a0[0]) * lo16(tv.x); o[1] = sigm(a0[1]) * hi16(tv.x); o[2] = sigm(a0[2]) * lo16(tv.y); o[3] = sigm(a0[3]) * hi16(tv.y);
;                     o[4] = sigm(a1[0]) * lo16(tv.z); o[5] = sigm(a1[1]) * hi16(tv.z); o[6] = sigm(a1[2]) * lo16(tv.w); o[7] = sigm(a1[3]) * hi16(tv.w);
;                     if (ACC) { o[0] += lo16(pv.x); o[1] += hi16(pv.x); o[2] += lo16(pv.y); o[3] += hi16(pv.y); o[4] += lo16(pv.z); o[5] += hi16(pv.z); o[6] += lo16(pv.w); o[7] += hi16(pv.w); }
;                     u32x4 w; w.x = cvt_pk_bf16(o[0], o[1]); w.y = cvt_pk_bf16(o[2], o[3]); w.z = cvt_pk_bf16(o[4], o[5]); w.w = cvt_pk_bf16(o[6], o[7]);
;                     *(u32x4*)(M + off) = w; } }
	v_mul_f32_e32 v24, 0xbfb8aa3b, v26
	v_mul_f32_e32 v25, 0xbfb8aa3b, v27
	v_exp_f32_e32 v24, v24
	v_exp_f32_e32 v25, v25
	v_lshlrev_b32_e32 v26, 16, v39
	v_and_b32_e32 v27, 0xffff0000, v39
	v_add_f32_e32 v24, 1.0, v24
	v_add_f32_e32 v25, 1.0, v25
	v_rcp_f32_e32 v24, v24
	v_rcp_f32_e32 v25, v25
	v_pk_mul_f32 v[28:29], v[28:29], v[42:43]
	v_pk_mul_f32 v[38:39], v[24:25], v[26:27]
	v_cvt_pk_bf16_f32 v24, v28, v29
	v_cvt_pk_bf16_f32 v25, v30, v31
	v_cvt_pk_bf16_f32 v26, v36, v37
	v_cvt_pk_bf16_f32 v27, v38, v39
	global_store_dwordx4 v[40:41], v[24:27], off
	s_nop 1
	v_mov_b32_e32 v24, v248
	v_mov_b32_e32 v25, v249
	v_mov_b32_e32 v26, v250
	v_mov_b32_e32 v27, v251
	v_lshlrev_b32_e32 v28, 16, v24
	v_and_b32_e32 v29, 0xffff0000, v24
	v_lshlrev_b32_e32 v24, 16, v25
	v_and_b32_e32 v25, 0xffff0000, v25
	v_pk_mul_f32 v[22:23], v[22:23], v[24:25]
	v_lshlrev_b32_e32 v24, 16, v26
	v_and_b32_e32 v25, 0xffff0000, v26
	v_pk_mul_f32 v[24:25], v[16:17], v[24:25]
	v_mul_f32_e32 v16, 0xbfb8aa3b, v18
	v_mul_f32_e32 v17, 0xbfb8aa3b, v19
	v_exp_f32_e32 v16, v16
	v_exp_f32_e32 v17, v17
	v_lshlrev_b32_e32 v18, 16, v27
	v_and_b32_e32 v19, 0xffff0000, v27
	v_add_f32_e32 v16, 1.0, v16
	v_add_f32_e32 v17, 1.0, v17
	v_rcp_f32_e32 v16, v16
	v_rcp_f32_e32 v17, v17
	v_pk_mul_f32 v[20:21], v[20:21], v[28:29]
	v_pk_mul_f32 v[26:27], v[16:17], v[18:19]
	v_cvt_pk_bf16_f32 v16, v20, v21
	v_cvt_pk_bf16_f32 v17, v22, v23
	v_cvt_pk_bf16_f32 v18, v24, v25
	v_cvt_pk_bf16_f32 v19, v26, v27
	global_store_dwordx4 v[32:33], v[16:19], off offset:256
	s_nop 1
	v_mov_b32_e32 v16, v169
	v_fmamk_f32 v16, v16, 0x3a800000, v187
	v_cmp_gt_f32_e32 vcc, s67, v16
	v_mul_f32_e32 v17, 0x4b800000, v16
	s_nop 0
	v_cndmask_b32_e32 v16, v16, v17, vcc
	v_rsq_f32_e32 v16, v16
	s_nop 0
	v_mul_f32_e32 v17, 0x45800000, v16
	v_cndmask_b32_e32 v18, v16, v17, vcc
	v_add_co_u32_e32 v24, vcc, s2, v158
	v_pk_mul_f32 v[14:15], v[14:15], v[18:19] op_sel_hi:[1,0]
	s_nop 0
	v_addc_co_u32_e32 v25, vcc, 0, v159, vcc
	s_nop 1
	v_mov_b32_e32 v20, v176
	v_mov_b32_e32 v21, v177
	v_mov_b32_e32 v22, v178
	v_mov_b32_e32 v23, v179
	v_pk_mul_f32 v[8:9], v[8:9], v[18:19] op_sel_hi:[1,0]
	v_mul_f32_e32 v14, 0xbfb8aa3b, v14
	v_mul_f32_e32 v15, 0xbfb8aa3b, v15
	v_exp_f32_e32 v14, v14
	v_exp_f32_e32 v15, v15
	v_mul_f32_e32 v8, 0xbfb8aa3b, v8
	v_mul_f32_e32 v9, 0xbfb8aa3b, v9
	v_exp_f32_e32 v8, v8
	v_exp_f32_e32 v9, v9
	v_add_f32_e32 v14, 1.0, v14
	v_add_f32_e32 v15, 1.0, v15
	v_rcp_f32_e32 v14, v14
	v_rcp_f32_e32 v15, v15
	v_add_f32_e32 v8, 1.0, v8
	v_add_f32_e32 v9, 1.0, v9
	v_rcp_f32_e32 v8, v8
	v_rcp_f32_e32 v9, v9
	v_pk_mul_f32 v[12:13], v[12:13], v[18:19] op_sel_hi:[1,0]
	v_pk_mul_f32 v[10:11], v[10:11], v[18:19] op_sel_hi:[1,0]
	v_mul_f32_e32 v12, 0xbfb8aa3b, v12
	v_mul_f32_e32 v13, 0xbfb8aa3b, v13
	v_exp_f32_e32 v12, v12
	v_exp_f32_e32 v13, v13
	v_lshl_add_u64 v[16:17], v[158:159], 0, s[4:5]
	v_pk_mul_f32 v[6:7], v[6:7], v[18:19] op_sel_hi:[1,0]
	v_add_f32_e32 v12, 1.0, v12
	v_add_f32_e32 v13, 1.0, v13
	v_rcp_f32_e32 v12, v12
	v_rcp_f32_e32 v13, v13
	v_pk_mul_f32 v[0:1], v[0:1], v[18:19] op_sel_hi:[1,0]
	v_mul_f32_e32 v6, 0xbfb8aa3b, v6
	v_mul_f32_e32 v7, 0xbfb8aa3b, v7
	v_exp_f32_e32 v6, v6
	v_exp_f32_e32 v7, v7
	v_mul_f32_e32 v0, 0xbfb8aa3b, v0
	v_mul_f32_e32 v1, 0xbfb8aa3b, v1
	v_exp_f32_e32 v0, v0
	v_exp_f32_e32 v1, v1
	v_add_f32_e32 v6, 1.0, v6
	v_add_f32_e32 v7, 1.0, v7
	v_rcp_f32_e32 v6, v6
	v_rcp_f32_e32 v7, v7
	v_add_f32_e32 v0, 1.0, v0
	v_add_f32_e32 v1, 1.0, v1
	v_rcp_f32_e32 v0, v0
	v_rcp_f32_e32 v1, v1
	v_pk_mul_f32 v[4:5], v[4:5], v[18:19] op_sel_hi:[1,0]
	v_pk_mul_f32 v[2:3], v[2:3], v[18:19] op_sel_hi:[1,0]
	v_mul_f32_e32 v4, 0xbfb8aa3b, v4
	v_mul_f32_e32 v5, 0xbfb8aa3b, v5
	v_exp_f32_e32 v4, v4
	v_exp_f32_e32 v5, v5
	s_and_b64 vcc, exec, s[38:39]
	s_mov_b32 s2, s30
	v_add_f32_e32 v4, 1.0, v4
	v_add_f32_e32 v5, 1.0, v5
	v_rcp_f32_e32 v4, v4
	v_rcp_f32_e32 v5, v5
	s_mov_b64 s[4:5], s[48:49]
	v_lshlrev_b32_e32 v26, 16, v20
	v_and_b32_e32 v27, 0xffff0000, v20
	v_lshlrev_b32_e32 v20, 16, v21
	v_and_b32_e32 v21, 0xffff0000, v21
	v_pk_mul_f32 v[14:15], v[14:15], v[20:21]
	v_lshlrev_b32_e32 v20, 16, v22
	v_and_b32_e32 v21, 0xffff0000, v22
	v_pk_mul_f32 v[20:21], v[8:9], v[20:21]
	v_mul_f32_e32 v8, 0xbfb8aa3b, v10
	v_mul_f32_e32 v9, 0xbfb8aa3b, v11
	v_exp_f32_e32 v8, v8
	v_exp_f32_e32 v9, v9
	v_lshlrev_b32_e32 v10, 16, v23
	v_and_b32_e32 v11, 0xffff0000, v23
	v_add_f32_e32 v8, 1.0, v8
	v_add_f32_e32 v9, 1.0, v9
	v_rcp_f32_e32 v8, v8
	v_rcp_f32_e32 v9, v9
	v_pk_mul_f32 v[12:13], v[12:13], v[26:27]
	v_pk_mul_f32 v[22:23], v[8:9], v[10:11]
	v_cvt_pk_bf16_f32 v8, v12, v13
	v_cvt_pk_bf16_f32 v9, v14, v15
	v_cvt_pk_bf16_f32 v10, v20, v21
	v_cvt_pk_bf16_f32 v11, v22, v23
	global_store_dwordx4 v[24:25], v[8:11], off
	s_nop 1
	v_mov_b32_e32 v8, v252
	v_mov_b32_e32 v9, v253
	v_mov_b32_e32 v10, v254
	v_mov_b32_e32 v11, v255
	v_lshlrev_b32_e32 v12, 16, v8
	v_and_b32_e32 v13, 0xffff0000, v8
	v_lshlrev_b32_e32 v8, 16, v9
	v_and_b32_e32 v9, 0xffff0000, v9
	v_pk_mul_f32 v[6:7], v[6:7], v[8:9]
	v_lshlrev_b32_e32 v8, 16, v10
	v_and_b32_e32 v9, 0xffff0000, v10
	v_pk_mul_f32 v[8:9], v[0:1], v[8:9]
	v_mul_f32_e32 v0, 0xbfb8aa3b, v2
	v_mul_f32_e32 v1, 0xbfb8aa3b, v3
	v_exp_f32_e32 v0, v0
	v_exp_f32_e32 v1, v1
	v_lshlrev_b32_e32 v2, 16, v11
	v_and_b32_e32 v3, 0xffff0000, v11
	v_add_f32_e32 v0, 1.0, v0
	v_add_f32_e32 v1, 1.0, v1
	v_rcp_f32_e32 v0, v0
	v_rcp_f32_e32 v1, v1
	v_pk_mul_f32 v[4:5], v[4:5], v[12:13]
	v_pk_mul_f32 v[10:11], v[0:1], v[2:3]
	v_cvt_pk_bf16_f32 v0, v4, v5
	v_cvt_pk_bf16_f32 v1, v6, v7
	v_cvt_pk_bf16_f32 v2, v8, v9
	v_cvt_pk_bf16_f32 v3, v10, v11
	global_store_dwordx4 v[16:17], v[0:3], off offset:256
	s_cbranch_vccz .LBB0_306
	s_waitcnt vmcnt(0)
	s_cmpk_gt_u32 s36, 0xff
	s_cbranch_scc1 .LBB0_317
	s_barrier

; #define PG8_STAGE(bufoff, gbase, voff) do { _Pragma("unroll") for (int _i = 0; _i < 2; ++_i) \
;         __builtin_amdgcn_global_load_lds((const unsigned*)((const char*)(gbase) + (voff)[_i]), (PG8_LAS unsigned*)(lds + (bufoff) + ldsw + _i * 8192), 16, 0, 0); } while (0)
; #define PG8_LDA(dst, b, h) do { _Pragma("unroll") for (int m = 0; m < 4; ++m) _Pragma("unroll") for (int k = 0; k < 2; ++k) dst[m][k] = *(const PG8_LAS bf16x8*)(lds + PG8_SA(b, h) + aoff + m * 2048 + k * 1024); } while (0)
; #define PG8_LDB(dst, b, h) do { _Pragma("unroll") for (int n = 0; n < 2; ++n) _Pragma("unroll") for (int k = 0; k < 2; ++k) dst[n][k] = *(const PG8_LAS bf16x8*)(lds + PG8_SB(b, h) + boff + n * 2048 + k * 1024); } while (0)
; #define PG8_MMA(ai, bj, At, Bt) do { __builtin_amdgcn_s_setprio(1); _Pragma("unroll") for (int m = 0; m < 4; ++m) _Pragma("unroll") for (int n = 0; n < 2; ++n) _Pragma("unroll") for (int k = 0; k < 2; ++k) \
;         acc[ai][bj][m][n] = __builtin_amdgcn_mfma_f32_16x16x32_bf16(Bt[n][k], At[m][k], acc[ai][bj][m][n], 0, 0, 0); __builtin_amdgcn_s_setprio(0); } while (0)
; #define PG8_WAIT_L(n) asm volatile("s_waitcnt lgkmcnt(" #n ")" ::: "memory")
; #define PG8_BAR __builtin_amdgcn_s_barrier()
; #define PG8_SCHED __builtin_amdgcn_sched_barrier(0)
; template <class Epi, class Sched, bool STAMP = false>
; __device__ __forceinline__ void gemm_phase(PG8_LAS unsigned char* lds, const Gemm g, const Sched& S, const Epi& E, unsigned long long* stamps) {
;     ...
;             PG8_LDB(B0, 0, 0); PG8_SCHED; PG8_LDA(At, 0, 0); PG8_STAGE(PG8_SA(1, 1), a1 + hstep, voffA);
;             PG8_WAIT_L(8); PG8_BAR; PG8_WAIT_L(0); PG8_MMA(0, 0, At, B0); PG8_BAR; PG8_SCHED;
;             PG8_LDB(B1, 0, 1); PG8_STAGE(PG8_SB(0, 0), b2, voffB);
;             PG8_BAR; PG8_WAIT_L(0); PG8_MMA(0, 1, At, B1); PG8_BAR;
;             PG8_LDA(At, 0, 1); PG8_STAGE(PG8_SA(0, 0), a2, voffA);
;             PG8_BAR; PG8_WAIT_L(0); PG8_MMA(1, 0, At, B0); PG8_BAR; PG8_SCHED;
.LBB0_353:
	s_add_u32 s14, s56, 0xfffc0080
	s_addc_u32 s15, s57, -1
	s_add_i32 s16, 0, 0x10000
	v_add_u32_e32 v166, s16, v167
	ds_read_b128 v[158:161], v166
	ds_read_b128 v[162:165], v166 offset:1024
	ds_read_b128 v[172:175], v166 offset:2048
	ds_read_b128 v[176:179], v166 offset:3072
	s_cmp_eq_u32 vcc_lo, 12
	s_cselect_b32 s61, s13, s15
	s_cselect_b32 s60, s47, s14
	s_cselect_b32 s59, s27, s77
	s_cselect_b32 s58, s53, s76
	v_lshl_add_u64 v[168:169], s[56:57], 0, v[154:155]
	s_add_i32 m0, s89, 0xc000
	ds_read_b128 v[180:183], v171
	ds_read_b128 v[192:195], v171 offset:1024
	ds_read_b128 v[196:199], v171 offset:2048
	ds_read_b128 v[200:203], v171 offset:3072
	ds_read_b128 v[204:207], v171 offset:4096
	ds_read_b128 v[208:211], v171 offset:5120
	ds_read_b128 v[212:215], v171 offset:6144
	ds_read_b128 v[216:219], v171 offset:7168
	global_load_lds_dwordx4 v[168:169], off
	v_lshl_add_u64 v[168:169], s[56:57], 0, v[156:157]
	s_add_i32 m0, s89, 0xe000
	s_nop 0
	global_load_lds_dwordx4 v[168:169], off
	s_waitcnt lgkmcnt(8)
	s_barrier
	s_waitcnt lgkmcnt(0)
	s_setprio 1
	s_waitcnt lgkmcnt(0)
	v_mfma_f32_16x16x32_bf16 v[124:127], v[158:161], v[180:183], v[124:127]
	v_mfma_f32_16x16x32_bf16 v[120:123], v[172:175], v[180:183], v[120:123]
	v_mfma_f32_16x16x32_bf16 v[108:111], v[158:161], v[196:199], v[108:111]
	v_mfma_f32_16x16x32_bf16 v[104:107], v[172:175], v[196:199], v[104:107]
	v_mfma_f32_16x16x32_bf16 v[92:95], v[158:161], v[204:207], v[92:95]
	v_mfma_f32_16x16x32_bf16 v[88:91], v[172:175], v[204:207], v[88:91]
	v_mfma_f32_16x16x32_bf16 v[76:79], v[158:161], v[212:215], v[76:79]
	v_mfma_f32_16x16x32_bf16 v[72:75], v[172:175], v[212:215], v[72:75]
	v_mfma_f32_16x16x32_bf16 v[124:127], v[162:165], v[192:195], v[124:127]
	v_mfma_f32_16x16x32_bf16 v[120:123], v[176:179], v[192:195], v[120:123]
	v_mfma_f32_16x16x32_bf16 v[108:111], v[162:165], v[200:203], v[108:111]
	v_mfma_f32_16x16x32_bf16 v[104:107], v[176:179], v[200:203], v[104:107]
	v_mfma_f32_16x16x32_bf16 v[92:95], v[162:165], v[208:211], v[92:95]
	v_mfma_f32_16x16x32_bf16 v[88:91], v[176:179], v[208:211], v[88:91]
	v_mfma_f32_16x16x32_bf16 v[76:79], v[162:165], v[216:219], v[76:79]
	v_mfma_f32_16x16x32_bf16 v[72:75], v[176:179], v[216:219], v[72:75]
	s_setprio 0
	s_barrier
	s_add_i32 s17, 0, 0x14000
	s_add_i32 s14, s16, s88
	v_add_u32_e32 v166, s17, v167
	v_lshl_add_u64 v[168:169], s[58:59], 0, v[128:129]
	s_mov_b32 m0, s14
	ds_read_b128 v[220:223], v166
	ds_read_b128 v[224:227], v166 offset:1024
	ds_read_b128 v[228:231], v166 offset:2048
	ds_read_b128 v[232:235], v166 offset:3072
	global_load_lds_dwordx4 v[168:169], off
	v_lshl_add_u64 v[236:237], s[58:59], 0, v[152:153]
	s_add_i32 m0, s14, 0x2000
	s_nop 0
	global_load_lds_dwordx4 v[236:237], off
	s_barrier
	s_waitcnt lgkmcnt(0)
	s_setprio 1
	s_waitcnt lgkmcnt(0)
	v_mfma_f32_16x16x32_bf16 v[116:119], v[220:223], v[180:183], v[116:119]
	v_mfma_f32_16x16x32_bf16 v[112:115], v[228:231], v[180:183], v[112:115]
	v_mfma_f32_16x16x32_bf16 v[100:103], v[220:223], v[196:199], v[100:103]
	v_mfma_f32_16x16x32_bf16 v[96:99], v[228:231], v[196:199], v[96:99]
	v_mfma_f32_16x16x32_bf16 v[84:87], v[220:223], v[204:207], v[84:87]
	v_mfma_f32_16x16x32_bf16 v[80:83], v[228:231], v[204:207], v[80:83]
	v_mfma_f32_16x16x32_bf16 v[68:71], v[220:223], v[212:215], v[68:71]
	v_mfma_f32_16x16x32_bf16 v[64:67], v[228:231], v[212:215], v[64:67]
	v_mfma_f32_16x16x32_bf16 v[116:119], v[224:227], v[192:195], v[116:119]
	v_mfma_f32_16x16x32_bf16 v[112:115], v[232:235], v[192:195], v[112:115]
	v_mfma_f32_16x16x32_bf16 v[100:103], v[224:227], v[200:203], v[100:103]
	v_mfma_f32_16x16x32_bf16 v[96:99], v[232:235], v[200:203], v[96:99]
	v_mfma_f32_16x16x32_bf16 v[84:87], v[224:227], v[208:211], v[84:87]
	v_mfma_f32_16x16x32_bf16 v[80:83], v[232:235], v[208:211], v[80:83]
	v_mfma_f32_16x16x32_bf16 v[68:71], v[224:227], v[216:219], v[68:71]
	v_mfma_f32_16x16x32_bf16 v[64:67], v[232:235], v[216:219], v[64:67]
	s_setprio 0
	s_mov_b32 m0, s89
	v_lshl_add_u64 v[238:239], s[60:61], 0, v[148:149]
	s_barrier
	ds_read_b128 v[180:183], v171 offset:16384
	ds_read_b128 v[192:195], v171 offset:17408
	ds_read_b128 v[196:199], v171 offset:18432
	ds_read_b128 v[200:203], v171 offset:19456
	ds_read_b128 v[204:207], v171 offset:20480
	ds_read_b128 v[208:211], v171 offset:21504
	ds_read_b128 v[212:215], v171 offset:22528
	ds_read_b128 v[216:219], v171 offset:23552
	global_load_lds_dwordx4 v[238:239], off
	v_lshl_add_u64 v[240:241], s[60:61], 0, v[150:151]
	s_mov_b32 m0, s96
	s_nop 0
	global_load_lds_dwordx4 v[240:241], off
	s_barrier
	s_waitcnt lgkmcnt(0)
	s_setprio 1
	s_waitcnt lgkmcnt(0)
	v_mfma_f32_16x16x32_bf16 v[60:63], v[158:161], v[180:183], v[60:63]
	v_mfma_f32_16x16x32_bf16 v[56:59], v[172:175], v[180:183], v[56:59]
	v_mfma_f32_16x16x32_bf16 v[44:47], v[158:161], v[196:199], v[44:47]
	v_mfma_f32_16x16x32_bf16 v[40:43], v[172:175], v[196:199], v[40:43]
	v_mfma_f32_16x16x32_bf16 v[28:31], v[158:161], v[204:207], v[28:31]
	v_mfma_f32_16x16x32_bf16 v[24:27], v[172:175], v[204:207], v[24:27]
	v_mfma_f32_16x16x32_bf16 v[12:15], v[158:161], v[212:215], v[12:15]
	v_mfma_f32_16x16x32_bf16 v[8:11], v[172:175], v[212:215], v[8:11]
	v_mfma_f32_16x16x32_bf16 v[60:63], v[162:165], v[192:195], v[60:63]
	v_mfma_f32_16x16x32_bf16 v[56:59], v[176:179], v[192:195], v[56:59]
	v_mfma_f32_16x16x32_bf16 v[44:47], v[162:165], v[200:203], v[44:47]
	v_mfma_f32_16x16x32_bf16 v[40:43], v[176:179], v[200:203], v[40:43]
	v_mfma_f32_16x16x32_bf16 v[28:31], v[162:165], v[208:211], v[28:31]
	v_mfma_f32_16x16x32_bf16 v[24:27], v[176:179], v[208:211], v[24:27]
	v_mfma_f32_16x16x32_bf16 v[12:15], v[162:165], v[216:219], v[12:15]
	v_mfma_f32_16x16x32_bf16 v[8:11], v[176:179], v[216:219], v[8:11]
	s_setprio 0
	s_barrier
; #define PG8_STAGE(bufoff, gbase, voff) do { _Pragma("unroll") for (int _i = 0; _i < 2; ++_i) \
;         __builtin_amdgcn_global_load_lds((const unsigned*)((const char*)(gbase) + (voff)[_i]), (PG8_LAS unsigned*)(lds + (bufoff) + ldsw + _i * 8192), 16, 0, 0); } while (0)
; #define PG8_LDA(dst, b, h) do { _Pragma("unroll") for (int m = 0; m < 4; ++m) _Pragma("unroll") for (int k = 0; k < 2; ++k) dst[m][k] = *(const PG8_LAS bf16x8*)(lds + PG8_SA(b, h) + aoff + m * 2048 + k * 1024); } while (0)
; #define PG8_LDB(dst, b, h) do { _Pragma("unroll") for (int n = 0; n < 2; ++n) _Pragma("unroll") for (int k = 0; k < 2; ++k) dst[n][k] = *(const PG8_LAS bf16x8*)(lds + PG8_SB(b, h) + boff + n * 2048 + k * 1024); } while (0)
; #define PG8_MMA(ai, bj, At, Bt) do { __builtin_amdgcn_s_setprio(1); _Pragma("unroll") for (int m = 0; m < 4; ++m) _Pragma("unroll") for (int n = 0; n < 2; ++n) _Pragma("unroll") for (int k = 0; k < 2; ++k) \
;         acc[ai][bj][m][n] = __builtin_amdgcn_mfma_f32_16x16x32_bf16(Bt[n][k], At[m][k], acc[ai][bj][m][n], 0, 0, 0); __builtin_amdgcn_s_setprio(0); } while (0)
; #define PG8_WAIT_V(n) asm volatile("s_waitcnt vmcnt(" #n ")" ::: "memory")
; #define PG8_WAIT_L(n) asm volatile("s_waitcnt lgkmcnt(" #n ")" ::: "memory")
; #define PG8_BAR __builtin_amdgcn_s_barrier()
; #define PG8_SCHED __builtin_amdgcn_sched_barrier(0)
; template <class Epi, class Sched, bool STAMP = false>
; __device__ __forceinline__ void gemm_phase(PG8_LAS unsigned char* lds, const Gemm g, const Sched& S, const Epi& E, unsigned long long* stamps) {
;     ...
;             PG8_STAGE(PG8_SB(0, 1), b2 + hstep, voffB);
;             PG8_WAIT_V(6); PG8_BAR; PG8_MMA(1, 1, At, B1); PG8_BAR;
;             PG8_LDB(B0, 1, 0); PG8_SCHED; PG8_LDA(At, 1, 0); PG8_STAGE(PG8_SA(0, 1), a2 + hstep, voffA);
;             PG8_WAIT_L(8); PG8_BAR; PG8_WAIT_L(0); PG8_MMA(0, 0, At, B0); PG8_BAR; PG8_SCHED;
;             PG8_LDB(B1, 1, 1); PG8_STAGE(PG8_SB(1, 0), b3, voffB);
;             PG8_BAR; PG8_WAIT_L(0); PG8_MMA(0, 1, At, B1); PG8_BAR;
;             PG8_LDA(At, 1, 1); PG8_STAGE(PG8_SA(1, 0), a3, voffA);
;             PG8_BAR; PG8_WAIT_L(0); PG8_MMA(1, 0, At, B0); PG8_BAR; PG8_SCHED;
	s_add_u32 s14, s58, 0x40000
	s_addc_u32 s15, s59, 0
	s_add_i32 s16, s17, s88
	v_lshl_add_u64 v[158:159], s[14:15], 0, v[128:129]
	s_mov_b32 m0, s16
	s_nop 0
	global_load_lds_dwordx4 v[158:159], off
	v_lshl_add_u64 v[158:159], s[14:15], 0, v[152:153]
	s_add_i32 m0, s16, 0x2000
	s_nop 0
	global_load_lds_dwordx4 v[158:159], off
	s_waitcnt vmcnt(6)
	s_barrier
	s_setprio 1
	v_mfma_f32_16x16x32_bf16 v[52:55], v[220:223], v[180:183], v[52:55]
	v_mfma_f32_16x16x32_bf16 v[48:51], v[228:231], v[180:183], v[48:51]
	v_mfma_f32_16x16x32_bf16 v[36:39], v[220:223], v[196:199], v[36:39]
	v_mfma_f32_16x16x32_bf16 v[32:35], v[228:231], v[196:199], v[32:35]
	v_mfma_f32_16x16x32_bf16 v[20:23], v[220:223], v[204:207], v[20:23]
	v_mfma_f32_16x16x32_bf16 v[16:19], v[228:231], v[204:207], v[16:19]
	v_mfma_f32_16x16x32_bf16 v[4:7], v[220:223], v[212:215], v[4:7]
	v_mfma_f32_16x16x32_bf16 v[0:3], v[228:231], v[212:215], v[0:3]
	v_mfma_f32_16x16x32_bf16 v[52:55], v[224:227], v[192:195], v[52:55]
	v_mfma_f32_16x16x32_bf16 v[48:51], v[232:235], v[192:195], v[48:51]
	v_mfma_f32_16x16x32_bf16 v[36:39], v[224:227], v[200:203], v[36:39]
	v_mfma_f32_16x16x32_bf16 v[32:35], v[232:235], v[200:203], v[32:35]
	v_mfma_f32_16x16x32_bf16 v[20:23], v[224:227], v[208:211], v[20:23]
	v_mfma_f32_16x16x32_bf16 v[16:19], v[232:235], v[208:211], v[16:19]
	v_mfma_f32_16x16x32_bf16 v[4:7], v[224:227], v[216:219], v[4:7]
	v_mfma_f32_16x16x32_bf16 v[0:3], v[232:235], v[216:219], v[0:3]
	s_setprio 0
	s_add_i32 s16, 0, 0x18000
	v_add_u32_e32 v166, s16, v167
	s_barrier
	ds_read_b128 v[158:161], v166
	ds_read_b128 v[162:165], v166 offset:1024
	ds_read_b128 v[172:175], v166 offset:2048
	ds_read_b128 v[176:179], v166 offset:3072
	s_add_u32 s14, s60, 0x40000
	s_addc_u32 s15, s61, 0
	s_mov_b32 m0, s97
	v_lshl_add_u64 v[220:221], s[14:15], 0, v[148:149]
	ds_read_b128 v[180:183], v171 offset:32768
	ds_read_b128 v[192:195], v171 offset:33792
	ds_read_b128 v[196:199], v171 offset:34816
	ds_read_b128 v[200:203], v171 offset:35840
	ds_read_b128 v[204:207], v171 offset:36864
	ds_read_b128 v[208:211], v171 offset:37888
	ds_read_b128 v[212:215], v171 offset:38912
	ds_read_b128 v[216:219], v171 offset:39936
	global_load_lds_dwordx4 v[220:221], off
	v_lshl_add_u64 v[220:221], s[14:15], 0, v[150:151]
	s_mov_b32 m0, s64
	s_nop 0
	global_load_lds_dwordx4 v[220:221], off
	s_waitcnt lgkmcnt(8)
	s_barrier
	s_waitcnt lgkmcnt(0)
	s_setprio 1
	s_waitcnt lgkmcnt(0)
	v_mfma_f32_16x16x32_bf16 v[124:127], v[158:161], v[180:183], v[124:127]
	v_mfma_f32_16x16x32_bf16 v[120:123], v[172:175], v[180:183], v[120:123]
	v_mfma_f32_16x16x32_bf16 v[108:111], v[158:161], v[196:199], v[108:111]
	v_mfma_f32_16x16x32_bf16 v[104:107], v[172:175], v[196:199], v[104:107]
	v_mfma_f32_16x16x32_bf16 v[92:95], v[158:161], v[204:207], v[92:95]
	v_mfma_f32_16x16x32_bf16 v[88:91], v[172:175], v[204:207], v[88:91]
	v_mfma_f32_16x16x32_bf16 v[76:79], v[158:161], v[212:215], v[76:79]
	v_mfma_f32_16x16x32_bf16 v[72:75], v[172:175], v[212:215], v[72:75]
	v_mfma_f32_16x16x32_bf16 v[124:127], v[162:165], v[192:195], v[124:127]
	v_mfma_f32_16x16x32_bf16 v[120:123], v[176:179], v[192:195], v[120:123]
	v_mfma_f32_16x16x32_bf16 v[108:111], v[162:165], v[200:203], v[108:111]
	v_mfma_f32_16x16x32_bf16 v[104:107], v[176:179], v[200:203], v[104:107]
	v_mfma_f32_16x16x32_bf16 v[92:95], v[162:165], v[208:211], v[92:95]
	v_mfma_f32_16x16x32_bf16 v[88:91], v[176:179], v[208:211], v[88:91]
	v_mfma_f32_16x16x32_bf16 v[76:79], v[162:165], v[216:219], v[76:79]
	v_mfma_f32_16x16x32_bf16 v[72:75], v[176:179], v[216:219], v[72:75]
	s_setprio 0
	s_barrier
	s_add_i32 s17, 0, 0x1c000
	s_add_i32 s14, s16, s88
	v_add_u32_e32 v166, s17, v167
	v_lshl_add_u64 v[168:169], v[168:169], 0, s[18:19]
	s_mov_b32 m0, s14
	ds_read_b128 v[220:223], v166
	ds_read_b128 v[224:227], v166 offset:1024
	ds_read_b128 v[228:231], v166 offset:2048
	ds_read_b128 v[232:235], v166 offset:3072
	global_load_lds_dwordx4 v[168:169], off
	v_lshl_add_u64 v[168:169], v[236:237], 0, s[18:19]
	s_add_i32 m0, s14, 0x2000
	s_nop 0
	global_load_lds_dwordx4 v[168:169], off
	s_barrier
	s_waitcnt lgkmcnt(0)
	s_setprio 1
	s_waitcnt lgkmcnt(0)
	v_mfma_f32_16x16x32_bf16 v[116:119], v[220:223], v[180:183], v[116:119]
	v_mfma_f32_16x16x32_bf16 v[112:115], v[228:231], v[180:183], v[112:115]
	v_mfma_f32_16x16x32_bf16 v[100:103], v[220:223], v[196:199], v[100:103]
	v_mfma_f32_16x16x32_bf16 v[96:99], v[228:231], v[196:199], v[96:99]
	v_mfma_f32_16x16x32_bf16 v[84:87], v[220:223], v[204:207], v[84:87]
	v_mfma_f32_16x16x32_bf16 v[80:83], v[228:231], v[204:207], v[80:83]
	v_mfma_f32_16x16x32_bf16 v[68:71], v[220:223], v[212:215], v[68:71]
	v_mfma_f32_16x16x32_bf16 v[64:67], v[228:231], v[212:215], v[64:67]
	v_mfma_f32_16x16x32_bf16 v[116:119], v[224:227], v[192:195], v[116:119]
	v_mfma_f32_16x16x32_bf16 v[112:115], v[232:235], v[192:195], v[112:115]
	v_mfma_f32_16x16x32_bf16 v[100:103], v[224:227], v[200:203], v[100:103]
	v_mfma_f32_16x16x32_bf16 v[96:99], v[232:235], v[200:203], v[96:99]
	v_mfma_f32_16x16x32_bf16 v[84:87], v[224:227], v[208:211], v[84:87]
	v_mfma_f32_16x16x32_bf16 v[80:83], v[232:235], v[208:211], v[80:83]
	v_mfma_f32_16x16x32_bf16 v[68:71], v[224:227], v[216:219], v[68:71]
	v_mfma_f32_16x16x32_bf16 v[64:67], v[232:235], v[216:219], v[64:67]
	s_setprio 0
	s_mov_b32 m0, s62
	v_lshl_add_u64 v[168:169], v[238:239], 0, s[18:19]
	s_barrier
	ds_read_b128 v[180:183], v171 offset:49152
	ds_read_b128 v[192:195], v171 offset:50176
	ds_read_b128 v[196:199], v171 offset:51200
	ds_read_b128 v[200:203], v171 offset:52224
	ds_read_b128 v[204:207], v171 offset:53248
	ds_read_b128 v[208:211], v171 offset:54272
	ds_read_b128 v[212:215], v171 offset:55296
	ds_read_b128 v[216:219], v171 offset:56320
	global_load_lds_dwordx4 v[168:169], off
	v_lshl_add_u64 v[168:169], v[240:241], 0, s[18:19]
	s_mov_b32 m0, s63
	s_nop 0
	global_load_lds_dwordx4 v[168:169], off
	s_barrier
; __device__ __forceinline__ unsigned cvt_pk_bf16(float lo, float hi) { const f32x2_cv v = {lo, hi}; const bf16x2_cv b = __builtin_convertvector(v, bf16x2_cv); return __builtin_bit_cast(unsigned, b); }
; #define PG8_STAGE(bufoff, gbase, voff) do { _Pragma("unroll") for (int _i = 0; _i < 2; ++_i) \
;         __builtin_amdgcn_global_load_lds((const unsigned*)((const char*)(gbase) + (voff)[_i]), (PG8_LAS unsigned*)(lds + (bufoff) + ldsw + _i * 8192), 16, 0, 0); } while (0)
; #define PG8_BAR __builtin_amdgcn_s_barrier()
; template <class Epi, class Sched, bool STAMP = false>
; __device__ __forceinline__ void gemm_phase(PG8_LAS unsigned char* lds, const Gemm g, const Sched& S, const Epi& E, unsigned long long* stamps) {
;     ...
;             PG8_BAR; PG8_WAIT_L(0); PG8_MMA(1, 0, At, B0); PG8_BAR; PG8_SCHED;
;             PG8_STAGE(PG8_SB(1, 1), b3 + hstep, voffB);
;             PG8_WAIT_V(6); PG8_BAR; PG8_MMA(1, 1, At, B1); PG8_BAR;
;     __device__ __forceinline__ void operator()(const f32x4 (&acc)[2][2][4][2], const pg8::Unit& u, int wr, int wc, int fr, int fq) const {
;     ...
;             for (int m = 0; m < 4; ++m) {
;                 const int row = row0 + ai * 128 + m * 16;
;                 const float s = rstd_of(rowss, row);
; #pragma unroll
;                 for (int bj = 0; bj < 2; ++bj) {
;                     const size_t off = (size_t)row * 1024 + col0 + bj * 128;
;                     const u32x4 tv = *(const u32x4*)(Tm + off);
;                     u32x4 pv = (u32x4){0u, 0u, 0u, 0u};
;                     if (ACC) pv = *(const u32x4*)(M + off);
;                     const f32x4 a0 = acc[ai][bj][m][0] * s, a1 = acc[ai][bj][m][1] * s;
;                     float o[8];
;                     o[0] = sigm(a0[0]) * lo16(tv.x); o[1] = sigm(a0[1]) * hi16(tv.x); o[2] = sigm(a0[2]) * lo16(tv.y); o[3] = sigm(a0[3]) * hi16(tv.y);
;                     o[4] = sigm(a1[0]) * lo16(tv.z); o[5] = sigm(a1[1]) * hi16(tv.z); o[6] = sigm(a1[2]) * lo16(tv.w); o[7] = sigm(a1[3]) * hi16(tv.w);
;                     if (ACC) { o[0] += lo16(pv.x); o[1] += hi16(pv.x); o[2] += lo16(pv.y); o[3] += hi16(pv.y); o[4] += lo16(pv.z); o[5] += hi16(pv.z); o[6] += lo16(pv.w); o[7] += hi16(pv.w); }
;                     u32x4 w; w.x = cvt_pk_bf16(o[0], o[1]); w.y = cvt_pk_bf16(o[2], o[3]); w.z = cvt_pk_bf16(o[4], o[5]); w.w = cvt_pk_bf16(o[6], o[7]);
;                     *(u32x4*)(M + off) = w; } }
	s_waitcnt lgkmcnt(0)
	s_setprio 1
	s_waitcnt lgkmcnt(0)
	v_mfma_f32_16x16x32_bf16 v[60:63], v[158:161], v[180:183], v[60:63]
	v_mfma_f32_16x16x32_bf16 v[56:59], v[172:175], v[180:183], v[56:59]
	v_mfma_f32_16x16x32_bf16 v[44:47], v[158:161], v[196:199], v[44:47]
	v_mfma_f32_16x16x32_bf16 v[40:43], v[172:175], v[196:199], v[40:43]
	v_mfma_f32_16x16x32_bf16 v[28:31], v[158:161], v[204:207], v[28:31]
	v_mfma_f32_16x16x32_bf16 v[24:27], v[172:175], v[204:207], v[24:27]
	v_mfma_f32_16x16x32_bf16 v[12:15], v[158:161], v[212:215], v[12:15]
	v_mfma_f32_16x16x32_bf16 v[8:11], v[172:175], v[212:215], v[8:11]
	v_mfma_f32_16x16x32_bf16 v[60:63], v[162:165], v[192:195], v[60:63]
	v_mfma_f32_16x16x32_bf16 v[56:59], v[176:179], v[192:195], v[56:59]
	v_mfma_f32_16x16x32_bf16 v[44:47], v[162:165], v[200:203], v[44:47]
	v_mfma_f32_16x16x32_bf16 v[40:43], v[176:179], v[200:203], v[40:43]
	v_mfma_f32_16x16x32_bf16 v[28:31], v[162:165], v[208:211], v[28:31]
	v_mfma_f32_16x16x32_bf16 v[24:27], v[176:179], v[208:211], v[24:27]
	v_mfma_f32_16x16x32_bf16 v[12:15], v[162:165], v[216:219], v[12:15]
	v_mfma_f32_16x16x32_bf16 v[8:11], v[176:179], v[216:219], v[8:11]
	s_setprio 0
	s_barrier
	s_add_u32 s14, s58, 0x40080
	s_addc_u32 s15, s59, 0
	s_add_i32 s16, s17, s88
	v_lshl_add_u64 v[158:159], s[14:15], 0, v[128:129]
	s_mov_b32 m0, s16
	s_nop 0
	global_load_lds_dwordx4 v[158:159], off
	v_lshl_add_u64 v[158:159], s[14:15], 0, v[152:153]
	s_add_i32 m0, s16, 0x2000
	s_nop 0
	global_load_lds_dwordx4 v[158:159], off
	s_waitcnt vmcnt(6)
	s_barrier
	s_setprio 1
	v_mfma_f32_16x16x32_bf16 v[52:55], v[220:223], v[180:183], v[52:55]
	v_mfma_f32_16x16x32_bf16 v[48:51], v[228:231], v[180:183], v[48:51]
	v_mfma_f32_16x16x32_bf16 v[36:39], v[220:223], v[196:199], v[36:39]
	v_mfma_f32_16x16x32_bf16 v[32:35], v[228:231], v[196:199], v[32:35]
	v_mfma_f32_16x16x32_bf16 v[20:23], v[220:223], v[204:207], v[20:23]
	v_mfma_f32_16x16x32_bf16 v[16:19], v[228:231], v[204:207], v[16:19]
	v_mfma_f32_16x16x32_bf16 v[4:7], v[220:223], v[212:215], v[4:7]
	v_mfma_f32_16x16x32_bf16 v[0:3], v[228:231], v[212:215], v[0:3]
	v_mfma_f32_16x16x32_bf16 v[52:55], v[224:227], v[192:195], v[52:55]
	v_mfma_f32_16x16x32_bf16 v[48:51], v[232:235], v[192:195], v[48:51]
	v_mfma_f32_16x16x32_bf16 v[36:39], v[224:227], v[200:203], v[36:39]
	v_mfma_f32_16x16x32_bf16 v[32:35], v[232:235], v[200:203], v[32:35]
	v_mfma_f32_16x16x32_bf16 v[20:23], v[224:227], v[208:211], v[20:23]
	v_mfma_f32_16x16x32_bf16 v[16:19], v[232:235], v[208:211], v[16:19]
	v_mfma_f32_16x16x32_bf16 v[4:7], v[224:227], v[216:219], v[4:7]
	v_mfma_f32_16x16x32_bf16 v[0:3], v[232:235], v[216:219], v[0:3]
	s_setprio 0
	s_add_i32 vcc_lo, vcc_lo, 2
	s_add_u32 s56, s56, 0x100
	s_addc_u32 s57, s57, 0
	s_add_u32 s76, s76, 0x100
	s_addc_u32 s77, s77, 0
	s_cmp_gt_u32 vcc_lo, 13
	s_barrier
	s_cbranch_scc0 .LBB0_353
	v_lshl_add_u32 v164, s2, 8, v139
	v_ashrrev_i32_e32 v165, 31, v164
	v_lshl_add_u64 v[160:161], v[164:165], 2, s[40:41]
	global_load_dword v158, v[160:161], off
	v_lshl_or_b32 v162, s3, 8, v170
	v_ashrrev_i32_e32 v163, 31, v162
	s_mov_b64 s[2:3], 0x40000
	s_mov_b64 s[58:59], s[36:37]
	s_mov_b64 s[56:57], s[4:5]
	s_waitcnt vmcnt(0)
	v_fmamk_f32 v158, v158, 0x3a800000, v187
	v_cmp_gt_f32_e32 vcc, s67, v158
	v_mul_f32_e32 v159, 0x4b800000, v158
	s_nop 0
	v_cndmask_b32_e32 v158, v158, v159, vcc
	v_rsq_f32_e32 v158, v158
	s_nop 0
	v_mul_f32_e32 v159, 0x45800000, v158
	v_cndmask_b32_e32 v166, v158, v159, vcc
	v_lshlrev_b64 v[158:159], 10, v[164:165]
	v_lshl_add_u64 v[158:159], v[158:159], 0, v[162:163]
	v_lshlrev_b64 v[158:159], 1, v[158:159]
	v_lshl_add_u64 v[168:169], s[30:31], 0, v[158:159]
	v_mov_b32_e32 v249, v158
	v_mov_b32_e32 v250, v249
	global_load_dwordx4 v[192:195], v250, s[30:31]
	global_load_dwordx4 v[196:199], v250, s[0:1]
	global_load_dwordx4 v[200:203], v250, s[30:31] offset:256
	global_load_dwordx4 v[204:207], v250, s[0:1] offset:256
	v_add_u32_e32 v250, 0x8000, v249
	global_load_dwordx4 v[208:211], v250, s[30:31]
	global_load_dwordx4 v[212:215], v250, s[0:1]
	global_load_dwordx4 v[216:219], v250, s[30:31] offset:256
	global_load_dwordx4 v[220:223], v250, s[0:1] offset:256
	v_add_u32_e32 v250, 0x10000, v249
	global_load_dwordx4 v[224:227], v250, s[30:31]
	global_load_dwordx4 v[228:231], v250, s[0:1]
	global_load_dwordx4 v[232:235], v250, s[30:31] offset:256
	global_load_dwordx4 v[236:239], v250, s[0:1] offset:256
	global_load_dword v240, v[160:161], off offset:64
	global_load_dword v241, v[160:161], off offset:128
	global_load_dword v244, v[160:161], off offset:192
	global_load_dword v245, v[160:161], off offset:512
	global_load_dword v246, v[160:161], off offset:576
	global_load_dword v247, v[160:161], off offset:640
	global_load_dword v248, v[160:161], off offset:704
	v_lshl_add_u64 v[168:169], s[0:1], 0, v[158:159]
	v_pk_mul_f32 v[126:127], v[126:127], v[166:167] op_sel_hi:[1,0]
	v_pk_mul_f32 v[120:121], v[120:121], v[166:167] op_sel_hi:[1,0]
	v_mul_f32_e32 v126, 0xbfb8aa3b, v126
	v_mul_f32_e32 v127, 0xbfb8aa3b, v127
	v_pk_mul_f32 v[124:125], v[124:125], v[166:167] op_sel_hi:[1,0]
	v_pk_mul_f32 v[122:123], v[122:123], v[166:167] op_sel_hi:[1,0]
	v_exp_f32_e32 v126, v126
	v_exp_f32_e32 v127, v127
	v_mul_f32_e32 v120, 0xbfb8aa3b, v120
	v_mul_f32_e32 v121, 0xbfb8aa3b, v121
	v_mul_f32_e32 v124, 0xbfb8aa3b, v124
	v_mul_f32_e32 v125, 0xbfb8aa3b, v125
	v_exp_f32_e32 v120, v120
	v_exp_f32_e32 v121, v121
	v_mul_f32_e32 v122, 0xbfb8aa3b, v122
	v_mul_f32_e32 v123, 0xbfb8aa3b, v123
	v_exp_f32_e32 v124, v124
	v_exp_f32_e32 v125, v125
	v_exp_f32_e32 v122, v122
	v_exp_f32_e32 v123, v123
	v_add_f32_e32 v126, 1.0, v126
	v_add_f32_e32 v127, 1.0, v127
	v_rcp_f32_e32 v126, v126
	v_rcp_f32_e32 v127, v127
	v_add_f32_e32 v120, 1.0, v120
	v_add_f32_e32 v121, 1.0, v121
	v_add_f32_e32 v124, 1.0, v124
	v_add_f32_e32 v125, 1.0, v125
	v_rcp_f32_e32 v120, v120
	v_rcp_f32_e32 v121, v121
	v_add_f32_e32 v122, 1.0, v122
	v_add_f32_e32 v123, 1.0, v123
	v_rcp_f32_e32 v124, v124
	v_rcp_f32_e32 v125, v125
	v_rcp_f32_e32 v122, v122
	v_rcp_f32_e32 v123, v123
	v_pk_mul_f32 v[116:117], v[116:117], v[166:167] op_sel_hi:[1,0]
	v_pk_mul_f32 v[114:115], v[114:115], v[166:167] op_sel_hi:[1,0]
	s_waitcnt vmcnt(0)
; __device__ __forceinline__ unsigned cvt_pk_bf16(float lo, float hi) { const f32x2_cv v = {lo, hi}; const bf16x2_cv b = __builtin_convertvector(v, bf16x2_cv); return __builtin_bit_cast(unsigned, b); }
; __device__ __forceinline__ float sigm(float x) { return __builtin_amdgcn_rcpf(1.0f + __expf(-x)); }
; __device__ __forceinline__ float lo16(unsigned w) { return __uint_as_float(w << 16); }
; __device__ __forceinline__ float hi16(unsigned w) { return __uint_as_float(w & 0xffff0000u); }
; __device__ __forceinline__ float rstd_of(const float* rowss, int row) { return rsqrtf(rowss[row] * (1.0f / 1024.0f) + 1e-6f); }
;     __device__ __forceinline__ void operator()(const f32x4 (&acc)[2][2][4][2], const pg8::Unit& u, int wr, int wc, int fr, int fq) const {
;     ...
;             for (int m = 0; m < 4; ++m) {
;                 const int row = row0 + ai * 128 + m * 16;
;                 const float s = rstd_of(rowss, row);
; #pragma unroll
;                 for (int bj = 0; bj < 2; ++bj) {
;                     const size_t off = (size_t)row * 1024 + col0 + bj * 128;
;                     const u32x4 tv = *(const u32x4*)(Tm + off);
;                     u32x4 pv = (u32x4){0u, 0u, 0u, 0u};
;                     if (ACC) pv = *(const u32x4*)(M + off);
;                     const f32x4 a0 = acc[ai][bj][m][0] * s, a1 = acc[ai][bj][m][1] * s;
;                     float o[8];
;                     o[0] = sigm(a0[0]) * lo16(tv.x); o[1] = sigm(a0[1]) * hi16(tv.x); o[2] = sigm(a0[2]) * lo16(tv.y); o[3] = sigm(a0[3]) * hi16(tv.y);
;                     o[4] = sigm(a1[0]) * lo16(tv.z); o[5] = sigm(a1[1]) * hi16(tv.z); o[6] = sigm(a1[2]) * lo16(tv.w); o[7] = sigm(a1[3]) * hi16(tv.w);
;                     if (ACC) { o[0] += lo16(pv.x); o[1] += hi16(pv.x); o[2] += lo16(pv.y); o[3] += hi16(pv.y); o[4] += lo16(pv.z); o[5] += hi16(pv.z); o[6] += lo16(pv.w); o[7] += hi16(pv.w); }
;                     u32x4 w; w.x = cvt_pk_bf16(o[0], o[1]); w.y = cvt_pk_bf16(o[2], o[3]); w.z = cvt_pk_bf16(o[4], o[5]); w.w = cvt_pk_bf16(o[6], o[7]);
;                     *(u32x4*)(M + off) = w; } }
	v_mov_b32_e32 v172, v192
	v_mov_b32_e32 v173, v193
	v_mov_b32_e32 v174, v194
	v_mov_b32_e32 v175, v195
	v_mov_b32_e32 v176, v196
	v_mov_b32_e32 v177, v197
	v_mov_b32_e32 v178, v198
	v_mov_b32_e32 v179, v199
	v_lshlrev_b32_e32 v180, 16, v172
	v_and_b32_e32 v181, 0xffff0000, v172
	v_lshlrev_b32_e32 v182, 16, v176
	v_and_b32_e32 v183, 0xffff0000, v176
	v_lshlrev_b32_e32 v172, 16, v173
	v_and_b32_e32 v173, 0xffff0000, v173
	v_lshlrev_b32_e32 v176, 16, v177
	v_and_b32_e32 v177, 0xffff0000, v177
	v_pk_fma_f32 v[126:127], v[126:127], v[172:173], v[176:177]
	v_lshlrev_b32_e32 v172, 16, v174
	v_and_b32_e32 v173, 0xffff0000, v174
	v_lshlrev_b32_e32 v176, 16, v178
	v_and_b32_e32 v177, 0xffff0000, v178
	v_pk_fma_f32 v[172:173], v[120:121], v[172:173], v[176:177]
	v_lshlrev_b32_e32 v120, 16, v175
	v_and_b32_e32 v121, 0xffff0000, v175
	v_lshlrev_b32_e32 v174, 16, v179
	v_and_b32_e32 v175, 0xffff0000, v179
	v_pk_fma_f32 v[124:125], v[124:125], v[180:181], v[182:183]
	v_pk_fma_f32 v[174:175], v[122:123], v[120:121], v[174:175]
	v_cvt_pk_bf16_f32 v120, v124, v125
	v_cvt_pk_bf16_f32 v121, v126, v127
	v_cvt_pk_bf16_f32 v122, v172, v173
	v_cvt_pk_bf16_f32 v123, v174, v175
	v_or_b32_e32 v124, 0x100, v158
	v_mov_b32_e32 v125, v159
	global_store_dwordx4 v[168:169], v[120:123], off
	v_lshl_add_u64 v[168:169], s[0:1], 0, v[124:125]
	v_pk_mul_f32 v[172:173], v[118:119], v[166:167] op_sel_hi:[1,0]
	v_lshl_add_u64 v[120:121], s[30:31], 0, v[124:125]
	s_nop 1
	v_mov_b32_e32 v120, v200
	v_mov_b32_e32 v121, v201
	v_mov_b32_e32 v122, v202
	v_mov_b32_e32 v123, v203
	v_pk_mul_f32 v[118:119], v[112:113], v[166:167] op_sel_hi:[1,0]
	s_nop 1
	v_mov_b32_e32 v124, v204
	v_mov_b32_e32 v125, v205
	v_mov_b32_e32 v126, v206
	v_mov_b32_e32 v127, v207
	v_add_u32_e32 v250, 0x18000, v249
	global_load_dwordx4 v[192:195], v250, s[30:31]
	global_load_dwordx4 v[196:199], v250, s[0:1]
	global_load_dwordx4 v[200:203], v250, s[30:31] offset:256
	global_load_dwordx4 v[204:207], v250, s[0:1] offset:256
	v_mul_f32_e32 v112, 0xbfb8aa3b, v116
	v_mul_f32_e32 v113, 0xbfb8aa3b, v117
	v_mul_f32_e32 v116, 0xbfb8aa3b, v172
	v_mul_f32_e32 v117, 0xbfb8aa3b, v173
	v_exp_f32_e32 v116, v116
	v_exp_f32_e32 v117, v117
	v_mul_f32_e32 v118, 0xbfb8aa3b, v118
	v_mul_f32_e32 v119, 0xbfb8aa3b, v119
	v_exp_f32_e32 v118, v118
	v_exp_f32_e32 v119, v119
	v_mul_f32_e32 v114, 0xbfb8aa3b, v114
	v_mul_f32_e32 v115, 0xbfb8aa3b, v115
	v_exp_f32_e32 v112, v112
	v_exp_f32_e32 v113, v113
	v_exp_f32_e32 v114, v114
	v_exp_f32_e32 v115, v115
	v_add_f32_e32 v116, 1.0, v116
	v_add_f32_e32 v117, 1.0, v117
	v_rcp_f32_e32 v116, v116
	v_rcp_f32_e32 v117, v117
	v_add_f32_e32 v118, 1.0, v118
	v_add_f32_e32 v119, 1.0, v119
	v_add_f32_e32 v112, 1.0, v112
	v_add_f32_e32 v113, 1.0, v113
	v_rcp_f32_e32 v118, v118
	v_rcp_f32_e32 v119, v119
	v_add_f32_e32 v114, 1.0, v114
	v_add_f32_e32 v115, 1.0, v115
	v_rcp_f32_e32 v112, v112
	v_rcp_f32_e32 v113, v113
	v_rcp_f32_e32 v114, v114
	v_rcp_f32_e32 v115, v115
	v_lshlrev_b32_e32 v172, 16, v120
	v_and_b32_e32 v173, 0xffff0000, v120
	v_lshlrev_b32_e32 v174, 16, v124
	v_and_b32_e32 v175, 0xffff0000, v124
	v_lshlrev_b32_e32 v120, 16, v121
	v_and_b32_e32 v121, 0xffff0000, v121
	v_lshlrev_b32_e32 v124, 16, v125
	v_and_b32_e32 v125, 0xffff0000, v125
	v_pk_fma_f32 v[116:117], v[116:117], v[120:121], v[124:125]
	v_lshlrev_b32_e32 v120, 16, v122
	v_and_b32_e32 v121, 0xffff0000, v122
	v_lshlrev_b32_e32 v124, 16, v126
	v_and_b32_e32 v125, 0xffff0000, v126
	v_pk_fma_f32 v[118:119], v[118:119], v[120:121], v[124:125]
	v_lshlrev_b32_e32 v120, 16, v123
	v_and_b32_e32 v121, 0xffff0000, v123
	v_lshlrev_b32_e32 v122, 16, v127
	v_and_b32_e32 v123, 0xffff0000, v127
	v_pk_fma_f32 v[112:113], v[112:113], v[172:173], v[174:175]
	v_pk_fma_f32 v[120:121], v[114:115], v[120:121], v[122:123]
	v_cvt_pk_bf16_f32 v112, v112, v113
	v_cvt_pk_bf16_f32 v113, v116, v117
	v_cvt_pk_bf16_f32 v114, v118, v119
	v_cvt_pk_bf16_f32 v115, v120, v121
	global_store_dwordx4 v[168:169], v[112:115], off
	s_nop 1
	v_mov_b32_e32 v112, v240
	s_nop 0
	v_or_b32_e32 v114, 16, v164
	v_ashrrev_i32_e32 v115, 31, v114
	v_lshlrev_b64 v[114:115], 10, v[114:115]
	v_lshl_add_u64 v[114:115], v[114:115], 0, v[162:163]
	v_lshlrev_b64 v[114:115], 1, v[114:115]
	v_lshl_add_u64 v[116:117], s[30:31], 0, v[114:115]
	v_lshl_add_u64 v[124:125], s[0:1], 0, v[114:115]
	s_nop 1
	v_mov_b32_e32 v116, v208
	v_mov_b32_e32 v117, v209
	v_mov_b32_e32 v118, v210
	v_mov_b32_e32 v119, v211
	v_or_b32_e32 v114, 0x100, v114
	s_nop 1
	v_mov_b32_e32 v120, v212
	v_mov_b32_e32 v121, v213
	v_mov_b32_e32 v122, v214
	v_mov_b32_e32 v123, v215
	v_fmamk_f32 v112, v112, 0x3a800000, v187
	v_cmp_gt_f32_e32 vcc, s67, v112
	v_mul_f32_e32 v113, 0x4b800000, v112
	v_lshlrev_b32_e32 v126, 16, v116
	v_cndmask_b32_e32 v112, v112, v113, vcc
	v_rsq_f32_e32 v112, v112
	v_and_b32_e32 v127, 0xffff0000, v116
	v_lshlrev_b32_e32 v168, 16, v120
	v_and_b32_e32 v169, 0xffff0000, v120
	v_mul_f32_e32 v113, 0x45800000, v112
	v_cndmask_b32_e32 v112, v112, v113, vcc
	v_pk_mul_f32 v[110:111], v[110:111], v[112:113] op_sel_hi:[1,0]
	v_pk_mul_f32 v[104:105], v[104:105], v[112:113] op_sel_hi:[1,0]
	v_mul_f32_e32 v110, 0xbfb8aa3b, v110
	v_mul_f32_e32 v111, 0xbfb8aa3b, v111
	v_pk_mul_f32 v[108:109], v[108:109], v[112:113] op_sel_hi:[1,0]
	v_pk_mul_f32 v[106:107], v[106:107], v[112:113] op_sel_hi:[1,0]
	v_exp_f32_e32 v110, v110
	v_exp_f32_e32 v111, v111
	v_mul_f32_e32 v104, 0xbfb8aa3b, v104
	v_mul_f32_e32 v105, 0xbfb8aa3b, v105
	v_mul_f32_e32 v108, 0xbfb8aa3b, v108
	v_mul_f32_e32 v109, 0xbfb8aa3b, v109
	v_exp_f32_e32 v104, v104
	v_exp_f32_e32 v105, v105
	v_mul_f32_e32 v106, 0xbfb8aa3b, v106
	v_mul_f32_e32 v107, 0xbfb8aa3b, v107
; __device__ __forceinline__ unsigned cvt_pk_bf16(float lo, float hi) { const f32x2_cv v = {lo, hi}; const bf16x2_cv b = __builtin_convertvector(v, bf16x2_cv); return __builtin_bit_cast(unsigned, b); }
; __device__ __forceinline__ float sigm(float x) { return __builtin_amdgcn_rcpf(1.0f + __expf(-x)); }
; __device__ __forceinline__ float lo16(unsigned w) { return __uint_as_float(w << 16); }
; __device__ __forceinline__ float hi16(unsigned w) { return __uint_as_float(w & 0xffff0000u); }
; __device__ __forceinline__ float rstd_of(const float* rowss, int row) { return rsqrtf(rowss[row] * (1.0f / 1024.0f) + 1e-6f); }
;     __device__ __forceinline__ void operator()(const f32x4 (&acc)[2][2][4][2], const pg8::Unit& u, int wr, int wc, int fr, int fq) const {
;     ...
;             for (int m = 0; m < 4; ++m) {
;                 const int row = row0 + ai * 128 + m * 16;
;                 const float s = rstd_of(rowss, row);
; #pragma unroll
;                 for (int bj = 0; bj < 2; ++bj) {
;                     const size_t off = (size_t)row * 1024 + col0 + bj * 128;
;                     const u32x4 tv = *(const u32x4*)(Tm + off);
;                     u32x4 pv = (u32x4){0u, 0u, 0u, 0u};
;                     if (ACC) pv = *(const u32x4*)(M + off);
;                     const f32x4 a0 = acc[ai][bj][m][0] * s, a1 = acc[ai][bj][m][1] * s;
;                     float o[8];
;                     o[0] = sigm(a0[0]) * lo16(tv.x); o[1] = sigm(a0[1]) * hi16(tv.x); o[2] = sigm(a0[2]) * lo16(tv.y); o[3] = sigm(a0[3]) * hi16(tv.y);
;                     o[4] = sigm(a1[0]) * lo16(tv.z); o[5] = sigm(a1[1]) * hi16(tv.z); o[6] = sigm(a1[2]) * lo16(tv.w); o[7] = sigm(a1[3]) * hi16(tv.w);
;                     if (ACC) { o[0] += lo16(pv.x); o[1] += hi16(pv.x); o[2] += lo16(pv.y); o[3] += hi16(pv.y); o[4] += lo16(pv.z); o[5] += hi16(pv.z); o[6] += lo16(pv.w); o[7] += hi16(pv.w); }
;                     u32x4 w; w.x = cvt_pk_bf16(o[0], o[1]); w.y = cvt_pk_bf16(o[2], o[3]); w.z = cvt_pk_bf16(o[4], o[5]); w.w = cvt_pk_bf16(o[6], o[7]);
;                     *(u32x4*)(M + off) = w; } }
	v_exp_f32_e32 v108, v108
	v_exp_f32_e32 v109, v109
	v_exp_f32_e32 v106, v106
	v_exp_f32_e32 v107, v107
	v_add_f32_e32 v110, 1.0, v110
	v_add_f32_e32 v111, 1.0, v111
	v_rcp_f32_e32 v110, v110
	v_rcp_f32_e32 v111, v111
	v_add_f32_e32 v104, 1.0, v104
	v_add_f32_e32 v105, 1.0, v105
	v_add_f32_e32 v108, 1.0, v108
	v_add_f32_e32 v109, 1.0, v109
	v_rcp_f32_e32 v104, v104
	v_rcp_f32_e32 v105, v105
	v_add_f32_e32 v106, 1.0, v106
	v_add_f32_e32 v107, 1.0, v107
	v_rcp_f32_e32 v108, v108
	v_rcp_f32_e32 v109, v109
	v_rcp_f32_e32 v106, v106
	v_rcp_f32_e32 v107, v107
	v_lshlrev_b32_e32 v116, 16, v117
	v_and_b32_e32 v117, 0xffff0000, v117
	v_lshlrev_b32_e32 v120, 16, v121
	v_and_b32_e32 v121, 0xffff0000, v121
	v_pk_fma_f32 v[110:111], v[110:111], v[116:117], v[120:121]
	v_lshlrev_b32_e32 v116, 16, v118
	v_and_b32_e32 v117, 0xffff0000, v118
	v_lshlrev_b32_e32 v120, 16, v122
	v_and_b32_e32 v121, 0xffff0000, v122
	v_pk_fma_f32 v[116:117], v[104:105], v[116:117], v[120:121]
	v_lshlrev_b32_e32 v104, 16, v119
	v_and_b32_e32 v105, 0xffff0000, v119
	v_lshlrev_b32_e32 v118, 16, v123
	v_and_b32_e32 v119, 0xffff0000, v123
	v_pk_fma_f32 v[108:109], v[108:109], v[126:127], v[168:169]
	v_pk_fma_f32 v[118:119], v[106:107], v[104:105], v[118:119]
	v_cvt_pk_bf16_f32 v104, v108, v109
	v_cvt_pk_bf16_f32 v105, v110, v111
	v_cvt_pk_bf16_f32 v106, v116, v117
	v_cvt_pk_bf16_f32 v107, v118, v119
	global_store_dwordx4 v[124:125], v[104:107], off
	v_pk_mul_f32 v[102:103], v[102:103], v[112:113] op_sel_hi:[1,0]
	v_pk_mul_f32 v[96:97], v[96:97], v[112:113] op_sel_hi:[1,0]
	v_lshl_add_u64 v[104:105], s[30:31], 0, v[114:115]
	v_lshl_add_u64 v[114:115], s[0:1], 0, v[114:115]
	s_nop 1
	v_mov_b32_e32 v104, v216
	v_mov_b32_e32 v105, v217
	v_mov_b32_e32 v106, v218
	v_mov_b32_e32 v107, v219
	v_mul_f32_e32 v102, 0xbfb8aa3b, v102
	s_nop 1
	v_mov_b32_e32 v108, v220
	v_mov_b32_e32 v109, v221
	v_mov_b32_e32 v110, v222
	v_mov_b32_e32 v111, v223
	v_add_u32_e32 v250, 0x40000, v249
	global_load_dwordx4 v[208:211], v250, s[30:31]
	global_load_dwordx4 v[212:215], v250, s[0:1]
	global_load_dwordx4 v[216:219], v250, s[30:31] offset:256
	global_load_dwordx4 v[220:223], v250, s[0:1] offset:256
	v_mul_f32_e32 v103, 0xbfb8aa3b, v103
	v_pk_mul_f32 v[100:101], v[100:101], v[112:113] op_sel_hi:[1,0]
	v_pk_mul_f32 v[98:99], v[98:99], v[112:113] op_sel_hi:[1,0]
	v_exp_f32_e32 v102, v102
	v_exp_f32_e32 v103, v103
	v_mul_f32_e32 v96, 0xbfb8aa3b, v96
	v_mul_f32_e32 v97, 0xbfb8aa3b, v97
	v_mul_f32_e32 v100, 0xbfb8aa3b, v100
	v_mul_f32_e32 v101, 0xbfb8aa3b, v101
	v_exp_f32_e32 v96, v96
	v_exp_f32_e32 v97, v97
	v_mul_f32_e32 v98, 0xbfb8aa3b, v98
	v_mul_f32_e32 v99, 0xbfb8aa3b, v99
	v_exp_f32_e32 v100, v100
	v_exp_f32_e32 v101, v101
	v_exp_f32_e32 v98, v98
	v_exp_f32_e32 v99, v99
	v_add_f32_e32 v102, 1.0, v102
	v_add_f32_e32 v103, 1.0, v103
	v_rcp_f32_e32 v102, v102
	v_rcp_f32_e32 v103, v103
	v_add_f32_e32 v96, 1.0, v96
	v_add_f32_e32 v97, 1.0, v97
	v_add_f32_e32 v100, 1.0, v100
	v_add_f32_e32 v101, 1.0, v101
	v_rcp_f32_e32 v96, v96
	v_rcp_f32_e32 v97, v97
	v_add_f32_e32 v98, 1.0, v98
	v_add_f32_e32 v99, 1.0, v99
	v_rcp_f32_e32 v100, v100
	v_rcp_f32_e32 v101, v101
	v_rcp_f32_e32 v98, v98
	v_rcp_f32_e32 v99, v99
	v_lshlrev_b32_e32 v112, 16, v104
	v_and_b32_e32 v113, 0xffff0000, v104
	v_lshlrev_b32_e32 v116, 16, v108
	v_and_b32_e32 v117, 0xffff0000, v108
	v_lshlrev_b32_e32 v104, 16, v105
	v_and_b32_e32 v105, 0xffff0000, v105
	v_lshlrev_b32_e32 v108, 16, v109
	v_and_b32_e32 v109, 0xffff0000, v109
	v_pk_fma_f32 v[102:103], v[102:103], v[104:105], v[108:109]
	v_lshlrev_b32_e32 v104, 16, v106
	v_and_b32_e32 v105, 0xffff0000, v106
	v_lshlrev_b32_e32 v108, 16, v110
	v_and_b32_e32 v109, 0xffff0000, v110
	v_pk_fma_f32 v[104:105], v[96:97], v[104:105], v[108:109]
	v_lshlrev_b32_e32 v96, 16, v107
	v_and_b32_e32 v97, 0xffff0000, v107
	v_lshlrev_b32_e32 v106, 16, v111
	v_and_b32_e32 v107, 0xffff0000, v111
	v_pk_fma_f32 v[100:101], v[100:101], v[112:113], v[116:117]
	v_pk_fma_f32 v[106:107], v[98:99], v[96:97], v[106:107]
	v_cvt_pk_bf16_f32 v96, v100, v101
	v_cvt_pk_bf16_f32 v97, v102, v103
	v_cvt_pk_bf16_f32 v98, v104, v105
	v_cvt_pk_bf16_f32 v99, v106, v107
	global_store_dwordx4 v[114:115], v[96:99], off
	s_nop 1
	v_mov_b32_e32 v96, v241
	s_nop 0
	v_or_b32_e32 v98, 32, v164
	v_ashrrev_i32_e32 v99, 31, v98
	v_lshlrev_b64 v[98:99], 10, v[98:99]
	v_lshl_add_u64 v[98:99], v[98:99], 0, v[162:163]
	v_lshlrev_b64 v[98:99], 1, v[98:99]
	v_lshl_add_u64 v[100:101], s[30:31], 0, v[98:99]
	v_lshl_add_u64 v[108:109], s[0:1], 0, v[98:99]
	s_nop 1
	v_mov_b32_e32 v100, v224
	v_mov_b32_e32 v101, v225
	v_mov_b32_e32 v102, v226
	v_mov_b32_e32 v103, v227
	v_or_b32_e32 v98, 0x100, v98
	s_nop 1
	v_mov_b32_e32 v104, v228
	v_mov_b32_e32 v105, v229
	v_mov_b32_e32 v106, v230
	v_mov_b32_e32 v107, v231
	v_fmamk_f32 v96, v96, 0x3a800000, v187
	v_cmp_gt_f32_e32 vcc, s67, v96
	v_mul_f32_e32 v97, 0x4b800000, v96
	v_lshlrev_b32_e32 v110, 16, v100
	v_cndmask_b32_e32 v96, v96, v97, vcc
	v_rsq_f32_e32 v96, v96
	v_and_b32_e32 v111, 0xffff0000, v100
	v_lshlrev_b32_e32 v112, 16, v104
	v_and_b32_e32 v113, 0xffff0000, v104
	v_mul_f32_e32 v97, 0x45800000, v96
	v_cndmask_b32_e32 v96, v96, v97, vcc
	v_pk_mul_f32 v[94:95], v[94:95], v[96:97] op_sel_hi:[1,0]
	v_pk_mul_f32 v[88:89], v[88:89], v[96:97] op_sel_hi:[1,0]
	v_mul_f32_e32 v94, 0xbfb8aa3b, v94
	v_mul_f32_e32 v95, 0xbfb8aa3b, v95
	v_pk_mul_f32 v[92:93], v[92:93], v[96:97] op_sel_hi:[1,0]
	v_pk_mul_f32 v[90:91], v[90:91], v[96:97] op_sel_hi:[1,0]
	v_exp_f32_e32 v94, v94
	v_exp_f32_e32 v95, v95
	v_mul_f32_e32 v88, 0xbfb8aa3b, v88
	v_mul_f32_e32 v89, 0xbfb8aa3b, v89
	v_mul_f32_e32 v92, 0xbfb8aa3b, v92
; __device__ __forceinline__ unsigned cvt_pk_bf16(float lo, float hi) { const f32x2_cv v = {lo, hi}; const bf16x2_cv b = __builtin_convertvector(v, bf16x2_cv); return __builtin_bit_cast(unsigned, b); }
; __device__ __forceinline__ float sigm(float x) { return __builtin_amdgcn_rcpf(1.0f + __expf(-x)); }
; __device__ __forceinline__ float lo16(unsigned w) { return __uint_as_float(w << 16); }
; __device__ __forceinline__ float hi16(unsigned w) { return __uint_as_float(w & 0xffff0000u); }
; __device__ __forceinline__ float rstd_of(const float* rowss, int row) { return rsqrtf(rowss[row] * (1.0f / 1024.0f) + 1e-6f); }
;     __device__ __forceinline__ void operator()(const f32x4 (&acc)[2][2][4][2], const pg8::Unit& u, int wr, int wc, int fr, int fq) const {
;     ...
;             for (int m = 0; m < 4; ++m) {
;                 const int row = row0 + ai * 128 + m * 16;
;                 const float s = rstd_of(rowss, row);
; #pragma unroll
;                 for (int bj = 0; bj < 2; ++bj) {
;                     const size_t off = (size_t)row * 1024 + col0 + bj * 128;
;                     const u32x4 tv = *(const u32x4*)(Tm + off);
;                     u32x4 pv = (u32x4){0u, 0u, 0u, 0u};
;                     if (ACC) pv = *(const u32x4*)(M + off);
;                     const f32x4 a0 = acc[ai][bj][m][0] * s, a1 = acc[ai][bj][m][1] * s;
;                     float o[8];
;                     o[0] = sigm(a0[0]) * lo16(tv.x); o[1] = sigm(a0[1]) * hi16(tv.x); o[2] = sigm(a0[2]) * lo16(tv.y); o[3] = sigm(a0[3]) * hi16(tv.y);
;                     o[4] = sigm(a1[0]) * lo16(tv.z); o[5] = sigm(a1[1]) * hi16(tv.z); o[6] = sigm(a1[2]) * lo16(tv.w); o[7] = sigm(a1[3]) * hi16(tv.w);
;                     if (ACC) { o[0] += lo16(pv.x); o[1] += hi16(pv.x); o[2] += lo16(pv.y); o[3] += hi16(pv.y); o[4] += lo16(pv.z); o[5] += hi16(pv.z); o[6] += lo16(pv.w); o[7] += hi16(pv.w); }
;                     u32x4 w; w.x = cvt_pk_bf16(o[0], o[1]); w.y = cvt_pk_bf16(o[2], o[3]); w.z = cvt_pk_bf16(o[4], o[5]); w.w = cvt_pk_bf16(o[6], o[7]);
;                     *(u32x4*)(M + off) = w; } }
	v_mul_f32_e32 v93, 0xbfb8aa3b, v93
	v_exp_f32_e32 v88, v88
	v_exp_f32_e32 v89, v89
	v_mul_f32_e32 v90, 0xbfb8aa3b, v90
	v_mul_f32_e32 v91, 0xbfb8aa3b, v91
	v_exp_f32_e32 v92, v92
	v_exp_f32_e32 v93, v93
	v_exp_f32_e32 v90, v90
	v_exp_f32_e32 v91, v91
	v_add_f32_e32 v94, 1.0, v94
	v_add_f32_e32 v95, 1.0, v95
	v_rcp_f32_e32 v94, v94
	v_rcp_f32_e32 v95, v95
	v_add_f32_e32 v88, 1.0, v88
	v_add_f32_e32 v89, 1.0, v89
	v_add_f32_e32 v92, 1.0, v92
	v_add_f32_e32 v93, 1.0, v93
	v_rcp_f32_e32 v88, v88
	v_rcp_f32_e32 v89, v89
	v_add_f32_e32 v90, 1.0, v90
	v_add_f32_e32 v91, 1.0, v91
	v_rcp_f32_e32 v92, v92
	v_rcp_f32_e32 v93, v93
	v_rcp_f32_e32 v90, v90
	v_rcp_f32_e32 v91, v91
	v_lshlrev_b32_e32 v100, 16, v101
	v_and_b32_e32 v101, 0xffff0000, v101
	v_lshlrev_b32_e32 v104, 16, v105
	v_and_b32_e32 v105, 0xffff0000, v105
	v_pk_fma_f32 v[94:95], v[94:95], v[100:101], v[104:105]
	v_lshlrev_b32_e32 v100, 16, v102
	v_and_b32_e32 v101, 0xffff0000, v102
	v_lshlrev_b32_e32 v104, 16, v106
	v_and_b32_e32 v105, 0xffff0000, v106
	v_pk_fma_f32 v[100:101], v[88:89], v[100:101], v[104:105]
	v_lshlrev_b32_e32 v88, 16, v103
	v_and_b32_e32 v89, 0xffff0000, v103
	v_lshlrev_b32_e32 v102, 16, v107
	v_and_b32_e32 v103, 0xffff0000, v107
	v_pk_fma_f32 v[92:93], v[92:93], v[110:111], v[112:113]
	v_pk_fma_f32 v[102:103], v[90:91], v[88:89], v[102:103]
	v_cvt_pk_bf16_f32 v88, v92, v93
	v_cvt_pk_bf16_f32 v89, v94, v95
	v_cvt_pk_bf16_f32 v90, v100, v101
	v_cvt_pk_bf16_f32 v91, v102, v103
	global_store_dwordx4 v[108:109], v[88:91], off
	v_pk_mul_f32 v[86:87], v[86:87], v[96:97] op_sel_hi:[1,0]
	v_pk_mul_f32 v[80:81], v[80:81], v[96:97] op_sel_hi:[1,0]
	v_lshl_add_u64 v[88:89], s[30:31], 0, v[98:99]
	v_lshl_add_u64 v[98:99], s[0:1], 0, v[98:99]
	s_nop 1
	v_mov_b32_e32 v92, v232
	v_mov_b32_e32 v93, v233
	v_mov_b32_e32 v94, v234
	v_mov_b32_e32 v95, v235
	v_mul_f32_e32 v86, 0xbfb8aa3b, v86
	s_nop 1
	v_mov_b32_e32 v88, v236
	v_mov_b32_e32 v89, v237
	v_mov_b32_e32 v90, v238
	v_mov_b32_e32 v91, v239
	v_add_u32_e32 v250, 0x48000, v249
	global_load_dwordx4 v[224:227], v250, s[30:31]
	global_load_dwordx4 v[228:231], v250, s[0:1]
	global_load_dwordx4 v[232:235], v250, s[30:31] offset:256
	global_load_dwordx4 v[236:239], v250, s[0:1] offset:256
	v_mul_f32_e32 v87, 0xbfb8aa3b, v87
	v_pk_mul_f32 v[84:85], v[84:85], v[96:97] op_sel_hi:[1,0]
	v_pk_mul_f32 v[82:83], v[82:83], v[96:97] op_sel_hi:[1,0]
	v_exp_f32_e32 v86, v86
	v_exp_f32_e32 v87, v87
	v_mul_f32_e32 v80, 0xbfb8aa3b, v80
	v_mul_f32_e32 v81, 0xbfb8aa3b, v81
	v_mul_f32_e32 v84, 0xbfb8aa3b, v84
	v_mul_f32_e32 v85, 0xbfb8aa3b, v85
	v_exp_f32_e32 v80, v80
	v_exp_f32_e32 v81, v81
	v_mul_f32_e32 v82, 0xbfb8aa3b, v82
	v_mul_f32_e32 v83, 0xbfb8aa3b, v83
	v_exp_f32_e32 v84, v84
	v_exp_f32_e32 v85, v85
	v_exp_f32_e32 v82, v82
	v_exp_f32_e32 v83, v83
	v_add_f32_e32 v86, 1.0, v86
	v_add_f32_e32 v87, 1.0, v87
	v_rcp_f32_e32 v86, v86
	v_rcp_f32_e32 v87, v87
	v_add_f32_e32 v80, 1.0, v80
	v_add_f32_e32 v81, 1.0, v81
	v_add_f32_e32 v84, 1.0, v84
	v_add_f32_e32 v85, 1.0, v85
	v_rcp_f32_e32 v80, v80
	v_rcp_f32_e32 v81, v81
	v_add_f32_e32 v82, 1.0, v82
	v_add_f32_e32 v83, 1.0, v83
	v_rcp_f32_e32 v84, v84
	v_rcp_f32_e32 v85, v85
	v_rcp_f32_e32 v82, v82
	v_rcp_f32_e32 v83, v83
	v_lshlrev_b32_e32 v96, 16, v92
	v_and_b32_e32 v97, 0xffff0000, v92
	v_lshlrev_b32_e32 v100, 16, v88
	v_and_b32_e32 v101, 0xffff0000, v88
	v_lshlrev_b32_e32 v92, 16, v93
	v_and_b32_e32 v93, 0xffff0000, v93
	v_lshlrev_b32_e32 v88, 16, v89
	v_and_b32_e32 v89, 0xffff0000, v89
	v_pk_fma_f32 v[86:87], v[86:87], v[92:93], v[88:89]
	v_lshlrev_b32_e32 v88, 16, v94
	v_and_b32_e32 v89, 0xffff0000, v94
	v_lshlrev_b32_e32 v92, 16, v90
	v_and_b32_e32 v93, 0xffff0000, v90
	v_pk_fma_f32 v[88:89], v[80:81], v[88:89], v[92:93]
	v_lshlrev_b32_e32 v80, 16, v95
	v_and_b32_e32 v81, 0xffff0000, v95
	v_lshlrev_b32_e32 v90, 16, v91
	v_and_b32_e32 v91, 0xffff0000, v91
	v_pk_fma_f32 v[84:85], v[84:85], v[96:97], v[100:101]
	v_pk_fma_f32 v[90:91], v[82:83], v[80:81], v[90:91]
	v_cvt_pk_bf16_f32 v80, v84, v85
	v_cvt_pk_bf16_f32 v81, v86, v87
	v_cvt_pk_bf16_f32 v82, v88, v89
	v_cvt_pk_bf16_f32 v83, v90, v91
	global_store_dwordx4 v[98:99], v[80:83], off
	s_nop 1
	v_mov_b32_e32 v80, v244
	s_nop 0
	v_or_b32_e32 v82, 48, v164
	v_ashrrev_i32_e32 v83, 31, v82
	v_lshlrev_b64 v[82:83], 10, v[82:83]
	v_lshl_add_u64 v[82:83], v[82:83], 0, v[162:163]
	v_lshlrev_b64 v[82:83], 1, v[82:83]
	v_lshl_add_u64 v[84:85], s[30:31], 0, v[82:83]
	v_lshl_add_u64 v[92:93], s[0:1], 0, v[82:83]
	s_waitcnt vmcnt(13)
; __device__ __forceinline__ unsigned cvt_pk_bf16(float lo, float hi) { const f32x2_cv v = {lo, hi}; const bf16x2_cv b = __builtin_convertvector(v, bf16x2_cv); return __builtin_bit_cast(unsigned, b); }
; __device__ __forceinline__ float sigm(float x) { return __builtin_amdgcn_rcpf(1.0f + __expf(-x)); }
; __device__ __forceinline__ float lo16(unsigned w) { return __uint_as_float(w << 16); }
; __device__ __forceinline__ float hi16(unsigned w) { return __uint_as_float(w & 0xffff0000u); }
; __device__ __forceinline__ float rstd_of(const float* rowss, int row) { return rsqrtf(rowss[row] * (1.0f / 1024.0f) + 1e-6f); }
;     __device__ __forceinline__ void operator()(const f32x4 (&acc)[2][2][4][2], const pg8::Unit& u, int wr, int wc, int fr, int fq) const {
;     ...
;             for (int m = 0; m < 4; ++m) {
;                 const int row = row0 + ai * 128 + m * 16;
;                 const float s = rstd_of(rowss, row);
; #pragma unroll
;                 for (int bj = 0; bj < 2; ++bj) {
;                     const size_t off = (size_t)row * 1024 + col0 + bj * 128;
;                     const u32x4 tv = *(const u32x4*)(Tm + off);
;                     u32x4 pv = (u32x4){0u, 0u, 0u, 0u};
;                     if (ACC) pv = *(const u32x4*)(M + off);
;                     const f32x4 a0 = acc[ai][bj][m][0] * s, a1 = acc[ai][bj][m][1] * s;
;                     float o[8];
;                     o[0] = sigm(a0[0]) * lo16(tv.x); o[1] = sigm(a0[1]) * hi16(tv.x); o[2] = sigm(a0[2]) * lo16(tv.y); o[3] = sigm(a0[3]) * hi16(tv.y);
;                     o[4] = sigm(a1[0]) * lo16(tv.z); o[5] = sigm(a1[1]) * hi16(tv.z); o[6] = sigm(a1[2]) * lo16(tv.w); o[7] = sigm(a1[3]) * hi16(tv.w);
;                     if (ACC) { o[0] += lo16(pv.x); o[1] += hi16(pv.x); o[2] += lo16(pv.y); o[3] += hi16(pv.y); o[4] += lo16(pv.z); o[5] += hi16(pv.z); o[6] += lo16(pv.w); o[7] += hi16(pv.w); }
;                     u32x4 w; w.x = cvt_pk_bf16(o[0], o[1]); w.y = cvt_pk_bf16(o[2], o[3]); w.z = cvt_pk_bf16(o[4], o[5]); w.w = cvt_pk_bf16(o[6], o[7]);
;                     *(u32x4*)(M + off) = w; } }
	s_nop 1
	v_mov_b32_e32 v84, v192
	v_mov_b32_e32 v85, v193
	v_mov_b32_e32 v86, v194
	v_mov_b32_e32 v87, v195
	v_or_b32_e32 v82, 0x100, v82
	s_nop 1
	v_mov_b32_e32 v88, v196
	v_mov_b32_e32 v89, v197
	v_mov_b32_e32 v90, v198
	v_mov_b32_e32 v91, v199
	v_fmamk_f32 v80, v80, 0x3a800000, v187
	v_cmp_gt_f32_e32 vcc, s67, v80
	v_mul_f32_e32 v81, 0x4b800000, v80
	v_lshlrev_b32_e32 v94, 16, v84
	v_cndmask_b32_e32 v80, v80, v81, vcc
	v_rsq_f32_e32 v80, v80
	v_and_b32_e32 v95, 0xffff0000, v84
	v_lshlrev_b32_e32 v96, 16, v88
	v_and_b32_e32 v97, 0xffff0000, v88
	v_mul_f32_e32 v81, 0x45800000, v80
	v_cndmask_b32_e32 v80, v80, v81, vcc
	v_pk_mul_f32 v[78:79], v[78:79], v[80:81] op_sel_hi:[1,0]
	v_pk_mul_f32 v[72:73], v[72:73], v[80:81] op_sel_hi:[1,0]
	v_mul_f32_e32 v78, 0xbfb8aa3b, v78
	v_mul_f32_e32 v79, 0xbfb8aa3b, v79
	v_pk_mul_f32 v[76:77], v[76:77], v[80:81] op_sel_hi:[1,0]
	v_pk_mul_f32 v[74:75], v[74:75], v[80:81] op_sel_hi:[1,0]
	v_exp_f32_e32 v78, v78
	v_exp_f32_e32 v79, v79
	v_mul_f32_e32 v72, 0xbfb8aa3b, v72
	v_mul_f32_e32 v73, 0xbfb8aa3b, v73
	v_mul_f32_e32 v76, 0xbfb8aa3b, v76
	v_mul_f32_e32 v77, 0xbfb8aa3b, v77
	v_exp_f32_e32 v72, v72
	v_exp_f32_e32 v73, v73
	v_mul_f32_e32 v74, 0xbfb8aa3b, v74
	v_mul_f32_e32 v75, 0xbfb8aa3b, v75
	v_exp_f32_e32 v76, v76
	v_exp_f32_e32 v77, v77
	v_exp_f32_e32 v74, v74
	v_exp_f32_e32 v75, v75
	v_add_f32_e32 v78, 1.0, v78
	v_add_f32_e32 v79, 1.0, v79
	v_rcp_f32_e32 v78, v78
	v_rcp_f32_e32 v79, v79
	v_add_f32_e32 v72, 1.0, v72
	v_add_f32_e32 v73, 1.0, v73
	v_add_f32_e32 v76, 1.0, v76
	v_add_f32_e32 v77, 1.0, v77
	v_rcp_f32_e32 v72, v72
	v_rcp_f32_e32 v73, v73
	v_add_f32_e32 v74, 1.0, v74
	v_add_f32_e32 v75, 1.0, v75
	v_rcp_f32_e32 v76, v76
	v_rcp_f32_e32 v77, v77
	v_rcp_f32_e32 v74, v74
	v_rcp_f32_e32 v75, v75
	v_lshlrev_b32_e32 v84, 16, v85
	v_and_b32_e32 v85, 0xffff0000, v85
	v_lshlrev_b32_e32 v88, 16, v89
	v_and_b32_e32 v89, 0xffff0000, v89
	v_pk_fma_f32 v[78:79], v[78:79], v[84:85], v[88:89]
	v_lshlrev_b32_e32 v84, 16, v86
	v_and_b32_e32 v85, 0xffff0000, v86
	v_lshlrev_b32_e32 v88, 16, v90
	v_and_b32_e32 v89, 0xffff0000, v90
	v_pk_fma_f32 v[84:85], v[72:73], v[84:85], v[88:89]
	v_lshlrev_b32_e32 v72, 16, v87
	v_and_b32_e32 v73, 0xffff0000, v87
	v_lshlrev_b32_e32 v86, 16, v91
	v_and_b32_e32 v87, 0xffff0000, v91
	v_pk_fma_f32 v[76:77], v[76:77], v[94:95], v[96:97]
	v_pk_fma_f32 v[86:87], v[74:75], v[72:73], v[86:87]
	v_cvt_pk_bf16_f32 v72, v76, v77
	v_cvt_pk_bf16_f32 v73, v78, v79
	v_cvt_pk_bf16_f32 v74, v84, v85
	v_cvt_pk_bf16_f32 v75, v86, v87
	global_store_dwordx4 v[92:93], v[72:75], off
	v_pk_mul_f32 v[70:71], v[70:71], v[80:81] op_sel_hi:[1,0]
	v_pk_mul_f32 v[64:65], v[64:65], v[80:81] op_sel_hi:[1,0]
	v_lshl_add_u64 v[72:73], s[30:31], 0, v[82:83]
	v_lshl_add_u64 v[82:83], s[0:1], 0, v[82:83]
	s_nop 1
	v_mov_b32_e32 v76, v200
	v_mov_b32_e32 v77, v201
	v_mov_b32_e32 v78, v202
	v_mov_b32_e32 v79, v203
	v_mul_f32_e32 v70, 0xbfb8aa3b, v70
	s_nop 1
	v_mov_b32_e32 v72, v204
	v_mov_b32_e32 v73, v205
	v_mov_b32_e32 v74, v206
	v_mov_b32_e32 v75, v207
	v_add_u32_e32 v250, 0x50000, v249
	global_load_dwordx4 v[192:195], v250, s[30:31]
	global_load_dwordx4 v[196:199], v250, s[0:1]
	global_load_dwordx4 v[200:203], v250, s[30:31] offset:256
	global_load_dwordx4 v[204:207], v250, s[0:1] offset:256
	v_mul_f32_e32 v71, 0xbfb8aa3b, v71
	v_pk_mul_f32 v[68:69], v[68:69], v[80:81] op_sel_hi:[1,0]
	v_pk_mul_f32 v[66:67], v[66:67], v[80:81] op_sel_hi:[1,0]
	v_exp_f32_e32 v70, v70
	v_exp_f32_e32 v71, v71
	v_mul_f32_e32 v64, 0xbfb8aa3b, v64
	v_mul_f32_e32 v65, 0xbfb8aa3b, v65
	v_mul_f32_e32 v68, 0xbfb8aa3b, v68
	v_mul_f32_e32 v69, 0xbfb8aa3b, v69
	v_exp_f32_e32 v64, v64
	v_exp_f32_e32 v65, v65
	v_mul_f32_e32 v66, 0xbfb8aa3b, v66
	v_mul_f32_e32 v67, 0xbfb8aa3b, v67
	v_exp_f32_e32 v68, v68
	v_exp_f32_e32 v69, v69
	v_exp_f32_e32 v66, v66
	v_exp_f32_e32 v67, v67
	v_add_f32_e32 v70, 1.0, v70
	v_add_f32_e32 v71, 1.0, v71
	v_rcp_f32_e32 v70, v70
	v_rcp_f32_e32 v71, v71
	v_add_f32_e32 v64, 1.0, v64
	v_add_f32_e32 v65, 1.0, v65
	v_add_f32_e32 v68, 1.0, v68
	v_add_f32_e32 v69, 1.0, v69
	v_rcp_f32_e32 v64, v64
	v_rcp_f32_e32 v65, v65
	v_add_f32_e32 v66, 1.0, v66
	v_add_f32_e32 v67, 1.0, v67
	v_rcp_f32_e32 v68, v68
	v_rcp_f32_e32 v69, v69
	v_rcp_f32_e32 v66, v66
	v_rcp_f32_e32 v67, v67
	v_lshlrev_b32_e32 v80, 16, v76
	v_and_b32_e32 v81, 0xffff0000, v76
	v_lshlrev_b32_e32 v84, 16, v72
	v_and_b32_e32 v85, 0xffff0000, v72
	v_lshlrev_b32_e32 v76, 16, v77
	v_and_b32_e32 v77, 0xffff0000, v77
	v_lshlrev_b32_e32 v72, 16, v73
	v_and_b32_e32 v73, 0xffff0000, v73
	v_pk_fma_f32 v[70:71], v[70:71], v[76:77], v[72:73]
	v_lshlrev_b32_e32 v72, 16, v78
	v_and_b32_e32 v73, 0xffff0000, v78
	v_lshlrev_b32_e32 v76, 16, v74
	v_and_b32_e32 v77, 0xffff0000, v74
	v_pk_fma_f32 v[72:73], v[64:65], v[72:73], v[76:77]
	v_lshlrev_b32_e32 v64, 16, v79
	v_and_b32_e32 v65, 0xffff0000, v79
	v_lshlrev_b32_e32 v74, 16, v75
	v_and_b32_e32 v75, 0xffff0000, v75
	v_pk_fma_f32 v[68:69], v[68:69], v[80:81], v[84:85]
	v_pk_fma_f32 v[74:75], v[66:67], v[64:65], v[74:75]
	v_cvt_pk_bf16_f32 v64, v68, v69
	v_cvt_pk_bf16_f32 v65, v70, v71
	v_cvt_pk_bf16_f32 v66, v72, v73
	v_cvt_pk_bf16_f32 v67, v74, v75
	global_store_dwordx4 v[82:83], v[64:67], off
	s_nop 1
	v_mov_b32_e32 v64, v245
	v_lshl_add_u64 v[70:71], v[158:159], 0, s[2:3]
	v_lshl_add_u64 v[66:67], s[30:31], 0, v[70:71]
	v_lshl_add_u64 v[74:75], s[0:1], 0, v[70:71]
	s_waitcnt vmcnt(13)
; __device__ __forceinline__ unsigned cvt_pk_bf16(float lo, float hi) { const f32x2_cv v = {lo, hi}; const bf16x2_cv b = __builtin_convertvector(v, bf16x2_cv); return __builtin_bit_cast(unsigned, b); }
; __device__ __forceinline__ float sigm(float x) { return __builtin_amdgcn_rcpf(1.0f + __expf(-x)); }
; __device__ __forceinline__ float lo16(unsigned w) { return __uint_as_float(w << 16); }
; __device__ __forceinline__ float hi16(unsigned w) { return __uint_as_float(w & 0xffff0000u); }
; __device__ __forceinline__ float rstd_of(const float* rowss, int row) { return rsqrtf(rowss[row] * (1.0f / 1024.0f) + 1e-6f); }
;     __device__ __forceinline__ void operator()(const f32x4 (&acc)[2][2][4][2], const pg8::Unit& u, int wr, int wc, int fr, int fq) const {
;     ...
;             for (int m = 0; m < 4; ++m) {
;                 const int row = row0 + ai * 128 + m * 16;
;                 const float s = rstd_of(rowss, row);
; #pragma unroll
;                 for (int bj = 0; bj < 2; ++bj) {
;                     const size_t off = (size_t)row * 1024 + col0 + bj * 128;
;                     const u32x4 tv = *(const u32x4*)(Tm + off);
;                     u32x4 pv = (u32x4){0u, 0u, 0u, 0u};
;                     if (ACC) pv = *(const u32x4*)(M + off);
;                     const f32x4 a0 = acc[ai][bj][m][0] * s, a1 = acc[ai][bj][m][1] * s;
;                     float o[8];
;                     o[0] = sigm(a0[0]) * lo16(tv.x); o[1] = sigm(a0[1]) * hi16(tv.x); o[2] = sigm(a0[2]) * lo16(tv.y); o[3] = sigm(a0[3]) * hi16(tv.y);
;                     o[4] = sigm(a1[0]) * lo16(tv.z); o[5] = sigm(a1[1]) * hi16(tv.z); o[6] = sigm(a1[2]) * lo16(tv.w); o[7] = sigm(a1[3]) * hi16(tv.w);
;                     if (ACC) { o[0] += lo16(pv.x); o[1] += hi16(pv.x); o[2] += lo16(pv.y); o[3] += hi16(pv.y); o[4] += lo16(pv.z); o[5] += hi16(pv.z); o[6] += lo16(pv.w); o[7] += hi16(pv.w); }
;                     u32x4 w; w.x = cvt_pk_bf16(o[0], o[1]); w.y = cvt_pk_bf16(o[2], o[3]); w.z = cvt_pk_bf16(o[4], o[5]); w.w = cvt_pk_bf16(o[6], o[7]);
;                     *(u32x4*)(M + off) = w; } }
	s_nop 1
	v_mov_b32_e32 v66, v208
	v_mov_b32_e32 v67, v209
	v_mov_b32_e32 v68, v210
	v_mov_b32_e32 v69, v211
	s_mov_b64 s[2:3], 0x40100
	s_nop 1
	v_mov_b32_e32 v70, v212
	v_mov_b32_e32 v71, v213
	v_mov_b32_e32 v72, v214
	v_mov_b32_e32 v73, v215
	v_fmamk_f32 v64, v64, 0x3a800000, v187
	v_cmp_gt_f32_e32 vcc, s67, v64
	v_mul_f32_e32 v65, 0x4b800000, v64
	v_lshlrev_b32_e32 v76, 16, v66
	v_cndmask_b32_e32 v64, v64, v65, vcc
	v_rsq_f32_e32 v64, v64
	v_and_b32_e32 v77, 0xffff0000, v66
	v_lshlrev_b32_e32 v78, 16, v70
	v_and_b32_e32 v79, 0xffff0000, v70
	v_mul_f32_e32 v65, 0x45800000, v64
	v_cndmask_b32_e32 v64, v64, v65, vcc
	v_pk_mul_f32 v[62:63], v[62:63], v[64:65] op_sel_hi:[1,0]
	v_pk_mul_f32 v[56:57], v[56:57], v[64:65] op_sel_hi:[1,0]
	v_mul_f32_e32 v62, 0xbfb8aa3b, v62
	v_mul_f32_e32 v63, 0xbfb8aa3b, v63
	v_pk_mul_f32 v[60:61], v[60:61], v[64:65] op_sel_hi:[1,0]
	v_pk_mul_f32 v[58:59], v[58:59], v[64:65] op_sel_hi:[1,0]
	v_exp_f32_e32 v62, v62
	v_exp_f32_e32 v63, v63
	v_mul_f32_e32 v56, 0xbfb8aa3b, v56
	v_mul_f32_e32 v57, 0xbfb8aa3b, v57
	v_mul_f32_e32 v60, 0xbfb8aa3b, v60
	v_mul_f32_e32 v61, 0xbfb8aa3b, v61
	v_exp_f32_e32 v56, v56
	v_exp_f32_e32 v57, v57
	v_mul_f32_e32 v58, 0xbfb8aa3b, v58
	v_mul_f32_e32 v59, 0xbfb8aa3b, v59
	v_exp_f32_e32 v60, v60
	v_exp_f32_e32 v61, v61
	v_exp_f32_e32 v58, v58
	v_exp_f32_e32 v59, v59
	v_add_f32_e32 v62, 1.0, v62
	v_add_f32_e32 v63, 1.0, v63
	v_rcp_f32_e32 v62, v62
	v_rcp_f32_e32 v63, v63
	v_add_f32_e32 v56, 1.0, v56
	v_add_f32_e32 v57, 1.0, v57
	v_add_f32_e32 v60, 1.0, v60
	v_add_f32_e32 v61, 1.0, v61
	v_rcp_f32_e32 v56, v56
	v_rcp_f32_e32 v57, v57
	v_add_f32_e32 v58, 1.0, v58
	v_add_f32_e32 v59, 1.0, v59
	v_rcp_f32_e32 v60, v60
	v_rcp_f32_e32 v61, v61
	v_rcp_f32_e32 v58, v58
	v_rcp_f32_e32 v59, v59
	v_lshlrev_b32_e32 v66, 16, v67
	v_and_b32_e32 v67, 0xffff0000, v67
	v_lshlrev_b32_e32 v70, 16, v71
	v_and_b32_e32 v71, 0xffff0000, v71
	v_pk_fma_f32 v[62:63], v[62:63], v[66:67], v[70:71]
	v_lshlrev_b32_e32 v66, 16, v68
	v_and_b32_e32 v67, 0xffff0000, v68
	v_lshlrev_b32_e32 v70, 16, v72
	v_and_b32_e32 v71, 0xffff0000, v72
	v_pk_fma_f32 v[66:67], v[56:57], v[66:67], v[70:71]
	v_lshlrev_b32_e32 v56, 16, v69
	v_and_b32_e32 v57, 0xffff0000, v69
	v_lshlrev_b32_e32 v68, 16, v73
	v_and_b32_e32 v69, 0xffff0000, v73
	v_pk_fma_f32 v[60:61], v[60:61], v[76:77], v[78:79]
	v_pk_fma_f32 v[68:69], v[58:59], v[56:57], v[68:69]
	v_cvt_pk_bf16_f32 v56, v60, v61
	v_cvt_pk_bf16_f32 v57, v62, v63
	v_cvt_pk_bf16_f32 v58, v66, v67
	v_cvt_pk_bf16_f32 v59, v68, v69
	global_store_dwordx4 v[74:75], v[56:59], off
	v_pk_mul_f32 v[54:55], v[54:55], v[64:65] op_sel_hi:[1,0]
	v_pk_mul_f32 v[48:49], v[48:49], v[64:65] op_sel_hi:[1,0]
	v_lshl_add_u64 v[56:57], v[158:159], 0, s[2:3]
	v_lshl_add_u64 v[58:59], s[30:31], 0, v[56:57]
	v_lshl_add_u64 v[66:67], s[0:1], 0, v[56:57]
	s_nop 1
	v_mov_b32_e32 v60, v216
	v_mov_b32_e32 v61, v217
	v_mov_b32_e32 v62, v218
	v_mov_b32_e32 v63, v219
	v_mul_f32_e32 v54, 0xbfb8aa3b, v54
	s_nop 1
	v_mov_b32_e32 v56, v220
	v_mov_b32_e32 v57, v221
	v_mov_b32_e32 v58, v222
	v_mov_b32_e32 v59, v223
	v_add_u32_e32 v250, 0x58000, v249
	global_load_dwordx4 v[208:211], v250, s[30:31]
	global_load_dwordx4 v[212:215], v250, s[0:1]
	global_load_dwordx4 v[216:219], v250, s[30:31] offset:256
	global_load_dwordx4 v[220:223], v250, s[0:1] offset:256
	v_mul_f32_e32 v55, 0xbfb8aa3b, v55
	v_pk_mul_f32 v[52:53], v[52:53], v[64:65] op_sel_hi:[1,0]
	v_pk_mul_f32 v[50:51], v[50:51], v[64:65] op_sel_hi:[1,0]
	v_exp_f32_e32 v54, v54
	v_exp_f32_e32 v55, v55
	v_mul_f32_e32 v48, 0xbfb8aa3b, v48
	v_mul_f32_e32 v49, 0xbfb8aa3b, v49
	v_mul_f32_e32 v52, 0xbfb8aa3b, v52
	v_mul_f32_e32 v53, 0xbfb8aa3b, v53
	v_exp_f32_e32 v48, v48
	v_exp_f32_e32 v49, v49
	v_mul_f32_e32 v50, 0xbfb8aa3b, v50
	v_mul_f32_e32 v51, 0xbfb8aa3b, v51
	v_exp_f32_e32 v52, v52
	v_exp_f32_e32 v53, v53
	v_exp_f32_e32 v50, v50
	v_exp_f32_e32 v51, v51
	v_add_f32_e32 v54, 1.0, v54
	v_add_f32_e32 v55, 1.0, v55
	v_rcp_f32_e32 v54, v54
	v_rcp_f32_e32 v55, v55
	v_add_f32_e32 v48, 1.0, v48
	v_add_f32_e32 v49, 1.0, v49
	v_add_f32_e32 v52, 1.0, v52
	v_add_f32_e32 v53, 1.0, v53
	v_rcp_f32_e32 v48, v48
	v_rcp_f32_e32 v49, v49
	v_add_f32_e32 v50, 1.0, v50
	v_add_f32_e32 v51, 1.0, v51
	v_rcp_f32_e32 v52, v52
	v_rcp_f32_e32 v53, v53
	v_rcp_f32_e32 v50, v50
	v_rcp_f32_e32 v51, v51
	s_mov_b64 s[2:3], 0x48000
	v_lshlrev_b32_e32 v64, 16, v60
	v_and_b32_e32 v65, 0xffff0000, v60
	v_lshlrev_b32_e32 v68, 16, v56
	v_and_b32_e32 v69, 0xffff0000, v56
	v_lshlrev_b32_e32 v60, 16, v61
	v_and_b32_e32 v61, 0xffff0000, v61
	v_lshlrev_b32_e32 v56, 16, v57
	v_and_b32_e32 v57, 0xffff0000, v57
	v_pk_fma_f32 v[54:55], v[54:55], v[60:61], v[56:57]
	v_lshlrev_b32_e32 v56, 16, v62
	v_and_b32_e32 v57, 0xffff0000, v62
	v_lshlrev_b32_e32 v60, 16, v58
	v_and_b32_e32 v61, 0xffff0000, v58
	v_pk_fma_f32 v[56:57], v[48:49], v[56:57], v[60:61]
	v_lshlrev_b32_e32 v48, 16, v63
	v_and_b32_e32 v49, 0xffff0000, v63
	v_lshlrev_b32_e32 v58, 16, v59
	v_and_b32_e32 v59, 0xffff0000, v59
	v_pk_fma_f32 v[52:53], v[52:53], v[64:65], v[68:69]
	v_pk_fma_f32 v[58:59], v[50:51], v[48:49], v[58:59]
	v_cvt_pk_bf16_f32 v48, v52, v53
	v_cvt_pk_bf16_f32 v49, v54, v55
	v_cvt_pk_bf16_f32 v50, v56, v57
	v_cvt_pk_bf16_f32 v51, v58, v59
	global_store_dwordx4 v[66:67], v[48:51], off
	s_nop 1
	v_mov_b32_e32 v48, v246
	v_lshl_add_u64 v[54:55], v[158:159], 0, s[2:3]
	v_lshl_add_u64 v[50:51], s[30:31], 0, v[54:55]
	v_lshl_add_u64 v[58:59], s[0:1], 0, v[54:55]
	s_waitcnt vmcnt(13)
; __device__ __forceinline__ unsigned cvt_pk_bf16(float lo, float hi) { const f32x2_cv v = {lo, hi}; const bf16x2_cv b = __builtin_convertvector(v, bf16x2_cv); return __builtin_bit_cast(unsigned, b); }
; __device__ __forceinline__ float sigm(float x) { return __builtin_amdgcn_rcpf(1.0f + __expf(-x)); }
; __device__ __forceinline__ float lo16(unsigned w) { return __uint_as_float(w << 16); }
; __device__ __forceinline__ float hi16(unsigned w) { return __uint_as_float(w & 0xffff0000u); }
; __device__ __forceinline__ float rstd_of(const float* rowss, int row) { return rsqrtf(rowss[row] * (1.0f / 1024.0f) + 1e-6f); }
;     __device__ __forceinline__ void operator()(const f32x4 (&acc)[2][2][4][2], const pg8::Unit& u, int wr, int wc, int fr, int fq) const {
;     ...
;             for (int m = 0; m < 4; ++m) {
;                 const int row = row0 + ai * 128 + m * 16;
;                 const float s = rstd_of(rowss, row);
; #pragma unroll
;                 for (int bj = 0; bj < 2; ++bj) {
;                     const size_t off = (size_t)row * 1024 + col0 + bj * 128;
;                     const u32x4 tv = *(const u32x4*)(Tm + off);
;                     u32x4 pv = (u32x4){0u, 0u, 0u, 0u};
;                     if (ACC) pv = *(const u32x4*)(M + off);
;                     const f32x4 a0 = acc[ai][bj][m][0] * s, a1 = acc[ai][bj][m][1] * s;
;                     float o[8];
;                     o[0] = sigm(a0[0]) * lo16(tv.x); o[1] = sigm(a0[1]) * hi16(tv.x); o[2] = sigm(a0[2]) * lo16(tv.y); o[3] = sigm(a0[3]) * hi16(tv.y);
;                     o[4] = sigm(a1[0]) * lo16(tv.z); o[5] = sigm(a1[1]) * hi16(tv.z); o[6] = sigm(a1[2]) * lo16(tv.w); o[7] = sigm(a1[3]) * hi16(tv.w);
;                     if (ACC) { o[0] += lo16(pv.x); o[1] += hi16(pv.x); o[2] += lo16(pv.y); o[3] += hi16(pv.y); o[4] += lo16(pv.z); o[5] += hi16(pv.z); o[6] += lo16(pv.w); o[7] += hi16(pv.w); }
;                     u32x4 w; w.x = cvt_pk_bf16(o[0], o[1]); w.y = cvt_pk_bf16(o[2], o[3]); w.z = cvt_pk_bf16(o[4], o[5]); w.w = cvt_pk_bf16(o[6], o[7]);
;                     *(u32x4*)(M + off) = w; } }
	s_nop 1
	v_mov_b32_e32 v50, v224
	v_mov_b32_e32 v51, v225
	v_mov_b32_e32 v52, v226
	v_mov_b32_e32 v53, v227
	s_mov_b64 s[2:3], 0x48100
	s_nop 1
	v_mov_b32_e32 v54, v228
	v_mov_b32_e32 v55, v229
	v_mov_b32_e32 v56, v230
	v_mov_b32_e32 v57, v231
	v_fmamk_f32 v48, v48, 0x3a800000, v187
	v_cmp_gt_f32_e32 vcc, s67, v48
	v_mul_f32_e32 v49, 0x4b800000, v48
	v_lshlrev_b32_e32 v60, 16, v50
	v_cndmask_b32_e32 v48, v48, v49, vcc
	v_rsq_f32_e32 v48, v48
	v_and_b32_e32 v61, 0xffff0000, v50
	v_lshlrev_b32_e32 v62, 16, v54
	v_and_b32_e32 v63, 0xffff0000, v54
	v_mul_f32_e32 v49, 0x45800000, v48
	v_cndmask_b32_e32 v48, v48, v49, vcc
	v_pk_mul_f32 v[46:47], v[46:47], v[48:49] op_sel_hi:[1,0]
	v_pk_mul_f32 v[40:41], v[40:41], v[48:49] op_sel_hi:[1,0]
	v_mul_f32_e32 v46, 0xbfb8aa3b, v46
	v_mul_f32_e32 v47, 0xbfb8aa3b, v47
	v_pk_mul_f32 v[44:45], v[44:45], v[48:49] op_sel_hi:[1,0]
	v_pk_mul_f32 v[42:43], v[42:43], v[48:49] op_sel_hi:[1,0]
	v_exp_f32_e32 v46, v46
	v_exp_f32_e32 v47, v47
	v_mul_f32_e32 v40, 0xbfb8aa3b, v40
	v_mul_f32_e32 v41, 0xbfb8aa3b, v41
	v_mul_f32_e32 v44, 0xbfb8aa3b, v44
	v_mul_f32_e32 v45, 0xbfb8aa3b, v45
	v_exp_f32_e32 v40, v40
	v_exp_f32_e32 v41, v41
	v_mul_f32_e32 v42, 0xbfb8aa3b, v42
	v_mul_f32_e32 v43, 0xbfb8aa3b, v43
	v_exp_f32_e32 v44, v44
	v_exp_f32_e32 v45, v45
	v_exp_f32_e32 v42, v42
	v_exp_f32_e32 v43, v43
	v_add_f32_e32 v46, 1.0, v46
	v_add_f32_e32 v47, 1.0, v47
	v_rcp_f32_e32 v46, v46
	v_rcp_f32_e32 v47, v47
	v_add_f32_e32 v40, 1.0, v40
	v_add_f32_e32 v41, 1.0, v41
	v_add_f32_e32 v44, 1.0, v44
	v_add_f32_e32 v45, 1.0, v45
	v_rcp_f32_e32 v40, v40
	v_rcp_f32_e32 v41, v41
	v_add_f32_e32 v42, 1.0, v42
	v_add_f32_e32 v43, 1.0, v43
	v_rcp_f32_e32 v44, v44
	v_rcp_f32_e32 v45, v45
	v_rcp_f32_e32 v42, v42
	v_rcp_f32_e32 v43, v43
	v_lshlrev_b32_e32 v50, 16, v51
	v_and_b32_e32 v51, 0xffff0000, v51
	v_lshlrev_b32_e32 v54, 16, v55
	v_and_b32_e32 v55, 0xffff0000, v55
	v_pk_fma_f32 v[46:47], v[46:47], v[50:51], v[54:55]
	v_lshlrev_b32_e32 v50, 16, v52
	v_and_b32_e32 v51, 0xffff0000, v52
	v_lshlrev_b32_e32 v54, 16, v56
	v_and_b32_e32 v55, 0xffff0000, v56
	v_pk_fma_f32 v[50:51], v[40:41], v[50:51], v[54:55]
	v_lshlrev_b32_e32 v40, 16, v53
	v_and_b32_e32 v41, 0xffff0000, v53
	v_lshlrev_b32_e32 v52, 16, v57
	v_and_b32_e32 v53, 0xffff0000, v57
	v_pk_fma_f32 v[44:45], v[44:45], v[60:61], v[62:63]
	v_pk_fma_f32 v[52:53], v[42:43], v[40:41], v[52:53]
	v_cvt_pk_bf16_f32 v40, v44, v45
	v_cvt_pk_bf16_f32 v41, v46, v47
	v_cvt_pk_bf16_f32 v42, v50, v51
	v_cvt_pk_bf16_f32 v43, v52, v53
	global_store_dwordx4 v[58:59], v[40:43], off
	v_pk_mul_f32 v[38:39], v[38:39], v[48:49] op_sel_hi:[1,0]
	v_pk_mul_f32 v[32:33], v[32:33], v[48:49] op_sel_hi:[1,0]
	v_lshl_add_u64 v[40:41], v[158:159], 0, s[2:3]
	v_lshl_add_u64 v[42:43], s[30:31], 0, v[40:41]
	v_lshl_add_u64 v[50:51], s[0:1], 0, v[40:41]
	s_nop 1
	v_mov_b32_e32 v44, v232
	v_mov_b32_e32 v45, v233
	v_mov_b32_e32 v46, v234
	v_mov_b32_e32 v47, v235
	v_mul_f32_e32 v38, 0xbfb8aa3b, v38
	s_nop 1
	v_mov_b32_e32 v40, v236
	v_mov_b32_e32 v41, v237
	v_mov_b32_e32 v42, v238
	v_mov_b32_e32 v43, v239
	v_mul_f32_e32 v39, 0xbfb8aa3b, v39
	v_pk_mul_f32 v[36:37], v[36:37], v[48:49] op_sel_hi:[1,0]
	v_pk_mul_f32 v[34:35], v[34:35], v[48:49] op_sel_hi:[1,0]
	v_exp_f32_e32 v38, v38
	v_exp_f32_e32 v39, v39
	v_mul_f32_e32 v32, 0xbfb8aa3b, v32
	v_mul_f32_e32 v33, 0xbfb8aa3b, v33
	v_mul_f32_e32 v36, 0xbfb8aa3b, v36
	v_mul_f32_e32 v37, 0xbfb8aa3b, v37
	v_exp_f32_e32 v32, v32
	v_exp_f32_e32 v33, v33
	v_mul_f32_e32 v34, 0xbfb8aa3b, v34
	v_mul_f32_e32 v35, 0xbfb8aa3b, v35
	v_exp_f32_e32 v36, v36
	v_exp_f32_e32 v37, v37
	v_exp_f32_e32 v34, v34
	v_exp_f32_e32 v35, v35
	v_add_f32_e32 v38, 1.0, v38
	v_add_f32_e32 v39, 1.0, v39
	v_rcp_f32_e32 v38, v38
	v_rcp_f32_e32 v39, v39
	v_add_f32_e32 v32, 1.0, v32
	v_add_f32_e32 v33, 1.0, v33
	v_add_f32_e32 v36, 1.0, v36
	v_add_f32_e32 v37, 1.0, v37
	v_rcp_f32_e32 v32, v32
	v_rcp_f32_e32 v33, v33
	v_add_f32_e32 v34, 1.0, v34
	v_add_f32_e32 v35, 1.0, v35
	v_rcp_f32_e32 v36, v36
	v_rcp_f32_e32 v37, v37
	v_rcp_f32_e32 v34, v34
	v_rcp_f32_e32 v35, v35
	s_mov_b64 s[2:3], 0x50000
	v_lshlrev_b32_e32 v48, 16, v44
	v_and_b32_e32 v49, 0xffff0000, v44
	v_lshlrev_b32_e32 v52, 16, v40
	v_and_b32_e32 v53, 0xffff0000, v40
	v_lshlrev_b32_e32 v44, 16, v45
	v_and_b32_e32 v45, 0xffff0000, v45
	v_lshlrev_b32_e32 v40, 16, v41
	v_and_b32_e32 v41, 0xffff0000, v41
	v_pk_fma_f32 v[38:39], v[38:39], v[44:45], v[40:41]
	v_lshlrev_b32_e32 v40, 16, v46
	v_and_b32_e32 v41, 0xffff0000, v46
	v_lshlrev_b32_e32 v44, 16, v42
	v_and_b32_e32 v45, 0xffff0000, v42
	v_pk_fma_f32 v[40:41], v[32:33], v[40:41], v[44:45]
	v_lshlrev_b32_e32 v32, 16, v47
	v_and_b32_e32 v33, 0xffff0000, v47
	v_lshlrev_b32_e32 v42, 16, v43
	v_and_b32_e32 v43, 0xffff0000, v43
	v_pk_fma_f32 v[36:37], v[36:37], v[48:49], v[52:53]
	v_pk_fma_f32 v[42:43], v[34:35], v[32:33], v[42:43]
	v_cvt_pk_bf16_f32 v32, v36, v37
	v_cvt_pk_bf16_f32 v33, v38, v39
	v_cvt_pk_bf16_f32 v34, v40, v41
	v_cvt_pk_bf16_f32 v35, v42, v43
	global_store_dwordx4 v[50:51], v[32:35], off
	s_nop 1
	v_mov_b32_e32 v32, v247
	v_lshl_add_u64 v[38:39], v[158:159], 0, s[2:3]
	v_lshl_add_u64 v[34:35], s[30:31], 0, v[38:39]
	v_lshl_add_u64 v[42:43], s[0:1], 0, v[38:39]
	s_waitcnt vmcnt(9)
; __device__ __forceinline__ unsigned cvt_pk_bf16(float lo, float hi) { const f32x2_cv v = {lo, hi}; const bf16x2_cv b = __builtin_convertvector(v, bf16x2_cv); return __builtin_bit_cast(unsigned, b); }
; __device__ __forceinline__ float sigm(float x) { return __builtin_amdgcn_rcpf(1.0f + __expf(-x)); }
; __device__ __forceinline__ float lo16(unsigned w) { return __uint_as_float(w << 16); }
; __device__ __forceinline__ float hi16(unsigned w) { return __uint_as_float(w & 0xffff0000u); }
; __device__ __forceinline__ float rstd_of(const float* rowss, int row) { return rsqrtf(rowss[row] * (1.0f / 1024.0f) + 1e-6f); }
;     __device__ __forceinline__ void operator()(const f32x4 (&acc)[2][2][4][2], const pg8::Unit& u, int wr, int wc, int fr, int fq) const {
;     ...
;             for (int m = 0; m < 4; ++m) {
;                 const int row = row0 + ai * 128 + m * 16;
;                 const float s = rstd_of(rowss, row);
; #pragma unroll
;                 for (int bj = 0; bj < 2; ++bj) {
;                     const size_t off = (size_t)row * 1024 + col0 + bj * 128;
;                     const u32x4 tv = *(const u32x4*)(Tm + off);
;                     u32x4 pv = (u32x4){0u, 0u, 0u, 0u};
;                     if (ACC) pv = *(const u32x4*)(M + off);
;                     const f32x4 a0 = acc[ai][bj][m][0] * s, a1 = acc[ai][bj][m][1] * s;
;                     float o[8];
;                     o[0] = sigm(a0[0]) * lo16(tv.x); o[1] = sigm(a0[1]) * hi16(tv.x); o[2] = sigm(a0[2]) * lo16(tv.y); o[3] = sigm(a0[3]) * hi16(tv.y);
;                     o[4] = sigm(a1[0]) * lo16(tv.z); o[5] = sigm(a1[1]) * hi16(tv.z); o[6] = sigm(a1[2]) * lo16(tv.w); o[7] = sigm(a1[3]) * hi16(tv.w);
;                     if (ACC) { o[0] += lo16(pv.x); o[1] += hi16(pv.x); o[2] += lo16(pv.y); o[3] += hi16(pv.y); o[4] += lo16(pv.z); o[5] += hi16(pv.z); o[6] += lo16(pv.w); o[7] += hi16(pv.w); }
;                     u32x4 w; w.x = cvt_pk_bf16(o[0], o[1]); w.y = cvt_pk_bf16(o[2], o[3]); w.z = cvt_pk_bf16(o[4], o[5]); w.w = cvt_pk_bf16(o[6], o[7]);
;                     *(u32x4*)(M + off) = w; } }
	s_nop 1
	v_mov_b32_e32 v34, v192
	v_mov_b32_e32 v35, v193
	v_mov_b32_e32 v36, v194
	v_mov_b32_e32 v37, v195
	s_mov_b64 s[2:3], 0x50100
	s_nop 1
	v_mov_b32_e32 v38, v196
	v_mov_b32_e32 v39, v197
	v_mov_b32_e32 v40, v198
	v_mov_b32_e32 v41, v199
	v_fmamk_f32 v32, v32, 0x3a800000, v187
	v_cmp_gt_f32_e32 vcc, s67, v32
	v_mul_f32_e32 v33, 0x4b800000, v32
	v_lshlrev_b32_e32 v44, 16, v34
	v_cndmask_b32_e32 v32, v32, v33, vcc
	v_rsq_f32_e32 v32, v32
	v_and_b32_e32 v45, 0xffff0000, v34
	v_lshlrev_b32_e32 v46, 16, v38
	v_and_b32_e32 v47, 0xffff0000, v38
	v_mul_f32_e32 v33, 0x45800000, v32
	v_cndmask_b32_e32 v32, v32, v33, vcc
	v_pk_mul_f32 v[30:31], v[30:31], v[32:33] op_sel_hi:[1,0]
	v_pk_mul_f32 v[24:25], v[24:25], v[32:33] op_sel_hi:[1,0]
	v_mul_f32_e32 v30, 0xbfb8aa3b, v30
	v_mul_f32_e32 v31, 0xbfb8aa3b, v31
	v_pk_mul_f32 v[28:29], v[28:29], v[32:33] op_sel_hi:[1,0]
	v_pk_mul_f32 v[26:27], v[26:27], v[32:33] op_sel_hi:[1,0]
	v_exp_f32_e32 v30, v30
	v_exp_f32_e32 v31, v31
	v_mul_f32_e32 v24, 0xbfb8aa3b, v24
	v_mul_f32_e32 v25, 0xbfb8aa3b, v25
	v_mul_f32_e32 v28, 0xbfb8aa3b, v28
	v_mul_f32_e32 v29, 0xbfb8aa3b, v29
	v_exp_f32_e32 v24, v24
	v_exp_f32_e32 v25, v25
	v_mul_f32_e32 v26, 0xbfb8aa3b, v26
	v_mul_f32_e32 v27, 0xbfb8aa3b, v27
	v_exp_f32_e32 v28, v28
	v_exp_f32_e32 v29, v29
	v_exp_f32_e32 v26, v26
	v_exp_f32_e32 v27, v27
	v_add_f32_e32 v30, 1.0, v30
	v_add_f32_e32 v31, 1.0, v31
	v_rcp_f32_e32 v30, v30
	v_rcp_f32_e32 v31, v31
	v_add_f32_e32 v24, 1.0, v24
	v_add_f32_e32 v25, 1.0, v25
	v_add_f32_e32 v28, 1.0, v28
	v_add_f32_e32 v29, 1.0, v29
	v_rcp_f32_e32 v24, v24
	v_rcp_f32_e32 v25, v25
	v_add_f32_e32 v26, 1.0, v26
	v_add_f32_e32 v27, 1.0, v27
	v_rcp_f32_e32 v28, v28
	v_rcp_f32_e32 v29, v29
	v_rcp_f32_e32 v26, v26
	v_rcp_f32_e32 v27, v27
	v_lshlrev_b32_e32 v34, 16, v35
	v_and_b32_e32 v35, 0xffff0000, v35
	v_lshlrev_b32_e32 v38, 16, v39
	v_and_b32_e32 v39, 0xffff0000, v39
	v_pk_fma_f32 v[30:31], v[30:31], v[34:35], v[38:39]
	v_lshlrev_b32_e32 v34, 16, v36
	v_and_b32_e32 v35, 0xffff0000, v36
	v_lshlrev_b32_e32 v38, 16, v40
	v_and_b32_e32 v39, 0xffff0000, v40
	v_pk_fma_f32 v[34:35], v[24:25], v[34:35], v[38:39]
	v_lshlrev_b32_e32 v24, 16, v37
	v_and_b32_e32 v25, 0xffff0000, v37
	v_lshlrev_b32_e32 v36, 16, v41
	v_and_b32_e32 v37, 0xffff0000, v41
	v_pk_fma_f32 v[28:29], v[28:29], v[44:45], v[46:47]
	v_pk_fma_f32 v[36:37], v[26:27], v[24:25], v[36:37]
	v_cvt_pk_bf16_f32 v24, v28, v29
	v_cvt_pk_bf16_f32 v25, v30, v31
	v_cvt_pk_bf16_f32 v26, v34, v35
	v_cvt_pk_bf16_f32 v27, v36, v37
	global_store_dwordx4 v[42:43], v[24:27], off
	v_pk_mul_f32 v[22:23], v[22:23], v[32:33] op_sel_hi:[1,0]
	v_pk_mul_f32 v[16:17], v[16:17], v[32:33] op_sel_hi:[1,0]
	v_lshl_add_u64 v[24:25], v[158:159], 0, s[2:3]
	v_lshl_add_u64 v[26:27], s[30:31], 0, v[24:25]
	v_lshl_add_u64 v[34:35], s[0:1], 0, v[24:25]
	s_nop 1
	v_mov_b32_e32 v28, v200
	v_mov_b32_e32 v29, v201
	v_mov_b32_e32 v30, v202
	v_mov_b32_e32 v31, v203
	v_mul_f32_e32 v22, 0xbfb8aa3b, v22
	s_nop 1
	v_mov_b32_e32 v24, v204
	v_mov_b32_e32 v25, v205
	v_mov_b32_e32 v26, v206
	v_mov_b32_e32 v27, v207
	v_mul_f32_e32 v23, 0xbfb8aa3b, v23
	v_pk_mul_f32 v[20:21], v[20:21], v[32:33] op_sel_hi:[1,0]
	v_pk_mul_f32 v[18:19], v[18:19], v[32:33] op_sel_hi:[1,0]
	v_exp_f32_e32 v22, v22
	v_exp_f32_e32 v23, v23
	v_mul_f32_e32 v16, 0xbfb8aa3b, v16
	v_mul_f32_e32 v17, 0xbfb8aa3b, v17
	v_mul_f32_e32 v20, 0xbfb8aa3b, v20
	v_mul_f32_e32 v21, 0xbfb8aa3b, v21
	v_exp_f32_e32 v16, v16
	v_exp_f32_e32 v17, v17
	v_mul_f32_e32 v18, 0xbfb8aa3b, v18
	v_mul_f32_e32 v19, 0xbfb8aa3b, v19
	v_exp_f32_e32 v20, v20
	v_exp_f32_e32 v21, v21
	v_exp_f32_e32 v18, v18
	v_exp_f32_e32 v19, v19
	v_add_f32_e32 v22, 1.0, v22
	v_add_f32_e32 v23, 1.0, v23
	v_rcp_f32_e32 v22, v22
	v_rcp_f32_e32 v23, v23
	v_add_f32_e32 v16, 1.0, v16
	v_add_f32_e32 v17, 1.0, v17
	v_add_f32_e32 v20, 1.0, v20
	v_add_f32_e32 v21, 1.0, v21
	v_rcp_f32_e32 v16, v16
	v_rcp_f32_e32 v17, v17
	v_add_f32_e32 v18, 1.0, v18
	v_add_f32_e32 v19, 1.0, v19
	v_rcp_f32_e32 v20, v20
	v_rcp_f32_e32 v21, v21
	v_rcp_f32_e32 v18, v18
	v_rcp_f32_e32 v19, v19
	s_mov_b64 s[2:3], 0x58000
	v_lshlrev_b32_e32 v32, 16, v28
	v_and_b32_e32 v33, 0xffff0000, v28
	v_lshlrev_b32_e32 v36, 16, v24
	v_and_b32_e32 v37, 0xffff0000, v24
	v_lshlrev_b32_e32 v28, 16, v29
	v_and_b32_e32 v29, 0xffff0000, v29
	v_lshlrev_b32_e32 v24, 16, v25
	v_and_b32_e32 v25, 0xffff0000, v25
	v_pk_fma_f32 v[22:23], v[22:23], v[28:29], v[24:25]
	v_lshlrev_b32_e32 v24, 16, v30
	v_and_b32_e32 v25, 0xffff0000, v30
	v_lshlrev_b32_e32 v28, 16, v26
	v_and_b32_e32 v29, 0xffff0000, v26
	v_pk_fma_f32 v[24:25], v[16:17], v[24:25], v[28:29]
	v_lshlrev_b32_e32 v16, 16, v31
	v_and_b32_e32 v17, 0xffff0000, v31
	v_lshlrev_b32_e32 v26, 16, v27
	v_and_b32_e32 v27, 0xffff0000, v27
	v_pk_fma_f32 v[20:21], v[20:21], v[32:33], v[36:37]
	v_pk_fma_f32 v[26:27], v[18:19], v[16:17], v[26:27]
	v_cvt_pk_bf16_f32 v16, v20, v21
	v_cvt_pk_bf16_f32 v17, v22, v23
	v_cvt_pk_bf16_f32 v18, v24, v25
	v_cvt_pk_bf16_f32 v19, v26, v27
	global_store_dwordx4 v[34:35], v[16:19], off
	s_nop 1
	v_mov_b32_e32 v16, v248
	v_lshl_add_u64 v[22:23], v[158:159], 0, s[2:3]
	v_lshl_add_u64 v[18:19], s[30:31], 0, v[22:23]
	v_lshl_add_u64 v[26:27], s[0:1], 0, v[22:23]
	s_waitcnt vmcnt(5)
; __device__ __forceinline__ unsigned cvt_pk_bf16(float lo, float hi) { const f32x2_cv v = {lo, hi}; const bf16x2_cv b = __builtin_convertvector(v, bf16x2_cv); return __builtin_bit_cast(unsigned, b); }
; template <class Epi, class Sched, bool STAMP = false>
; __device__ __forceinline__ void gemm_phase(PG8_LAS unsigned char* lds, const Gemm g, const Sched& S, const Epi& E, unsigned long long* stamps) {
;     ...
;         if constexpr (!Epi::AFTER_DRAIN) { E(acc, cur, wr, wc, fr, fq); S.done(cur); }
;         if (!has_next) break;
; #pragma unroll
;         for (int a = 0; a < 2; ++a)
; #pragma unroll
;             for (int b = 0; b < 2; ++b)
; #pragma unroll
;                 for (int m = 0; m < 4; ++m)
; #pragma unroll
;                     for (int n = 0; n < 2; ++n) acc[a][b][m][n] = (f32x4){0.f, 0.f, 0.f, 0.f};
;         cur = nxt; cA = nA; cB = nB; ++ui;
;     }
;     PG8_WAIT_V(0);
;     if (wr == 0) PG8_BAR;
;     PG8_BAR;
;     __device__ __forceinline__ void operator()(const f32x4 (&acc)[2][2][4][2], const pg8::Unit& u, int wr, int wc, int fr, int fq) const {
;     ...
;             for (int m = 0; m < 4; ++m) {
;                 const int row = row0 + ai * 128 + m * 16;
;                 const float s = rstd_of(rowss, row);
; #pragma unroll
;                 for (int bj = 0; bj < 2; ++bj) {
;                     const size_t off = (size_t)row * 1024 + col0 + bj * 128;
;                     const u32x4 tv = *(const u32x4*)(Tm + off);
;                     u32x4 pv = (u32x4){0u, 0u, 0u, 0u};
;                     if (ACC) pv = *(const u32x4*)(M + off);
;                     const f32x4 a0 = acc[ai][bj][m][0] * s, a1 = acc[ai][bj][m][1] * s;
;                     float o[8];
;                     o[0] = sigm(a0[0]) * lo16(tv.x); o[1] = sigm(a0[1]) * hi16(tv.x); o[2] = sigm(a0[2]) * lo16(tv.y); o[3] = sigm(a0[3]) * hi16(tv.y);
;                     o[4] = sigm(a1[0]) * lo16(tv.z); o[5] = sigm(a1[1]) * hi16(tv.z); o[6] = sigm(a1[2]) * lo16(tv.w); o[7] = sigm(a1[3]) * hi16(tv.w);
;                     if (ACC) { o[0] += lo16(pv.x); o[1] += hi16(pv.x); o[2] += lo16(pv.y); o[3] += hi16(pv.y); o[4] += lo16(pv.z); o[5] += hi16(pv.z); o[6] += lo16(pv.w); o[7] += hi16(pv.w); }
;                     u32x4 w; w.x = cvt_pk_bf16(o[0], o[1]); w.y = cvt_pk_bf16(o[2], o[3]); w.z = cvt_pk_bf16(o[4], o[5]); w.w = cvt_pk_bf16(o[6], o[7]);
;                     *(u32x4*)(M + off) = w; } }
	s_nop 1
	v_mov_b32_e32 v18, v208
	v_mov_b32_e32 v19, v209
	v_mov_b32_e32 v20, v210
	v_mov_b32_e32 v21, v211
	s_mov_b64 s[2:3], 0x58100
	s_nop 1
	v_mov_b32_e32 v22, v212
	v_mov_b32_e32 v23, v213
	v_mov_b32_e32 v24, v214
	v_mov_b32_e32 v25, v215
	v_fmamk_f32 v16, v16, 0x3a800000, v187
	v_cmp_gt_f32_e32 vcc, s67, v16
	v_mul_f32_e32 v17, 0x4b800000, v16
	v_lshlrev_b32_e32 v28, 16, v18
	v_cndmask_b32_e32 v16, v16, v17, vcc
	v_rsq_f32_e32 v16, v16
	v_and_b32_e32 v29, 0xffff0000, v18
	v_lshlrev_b32_e32 v30, 16, v22
	v_and_b32_e32 v31, 0xffff0000, v22
	v_mul_f32_e32 v17, 0x45800000, v16
	v_cndmask_b32_e32 v16, v16, v17, vcc
	v_pk_mul_f32 v[14:15], v[14:15], v[16:17] op_sel_hi:[1,0]
	v_pk_mul_f32 v[8:9], v[8:9], v[16:17] op_sel_hi:[1,0]
	v_mul_f32_e32 v14, 0xbfb8aa3b, v14
	v_mul_f32_e32 v15, 0xbfb8aa3b, v15
	v_pk_mul_f32 v[12:13], v[12:13], v[16:17] op_sel_hi:[1,0]
	v_pk_mul_f32 v[10:11], v[10:11], v[16:17] op_sel_hi:[1,0]
	v_exp_f32_e32 v14, v14
	v_exp_f32_e32 v15, v15
	v_mul_f32_e32 v8, 0xbfb8aa3b, v8
	v_mul_f32_e32 v9, 0xbfb8aa3b, v9
	v_mul_f32_e32 v12, 0xbfb8aa3b, v12
	v_mul_f32_e32 v13, 0xbfb8aa3b, v13
	v_exp_f32_e32 v8, v8
	v_exp_f32_e32 v9, v9
	v_mul_f32_e32 v10, 0xbfb8aa3b, v10
	v_mul_f32_e32 v11, 0xbfb8aa3b, v11
	v_exp_f32_e32 v12, v12
	v_exp_f32_e32 v13, v13
	v_exp_f32_e32 v10, v10
	v_exp_f32_e32 v11, v11
	v_add_f32_e32 v14, 1.0, v14
	v_add_f32_e32 v15, 1.0, v15
	v_rcp_f32_e32 v14, v14
	v_rcp_f32_e32 v15, v15
	v_add_f32_e32 v8, 1.0, v8
	v_add_f32_e32 v9, 1.0, v9
	v_add_f32_e32 v12, 1.0, v12
	v_add_f32_e32 v13, 1.0, v13
	v_rcp_f32_e32 v8, v8
	v_rcp_f32_e32 v9, v9
	v_add_f32_e32 v10, 1.0, v10
	v_add_f32_e32 v11, 1.0, v11
	v_rcp_f32_e32 v12, v12
	v_rcp_f32_e32 v13, v13
	v_rcp_f32_e32 v10, v10
	v_rcp_f32_e32 v11, v11
	v_lshlrev_b32_e32 v18, 16, v19
	v_and_b32_e32 v19, 0xffff0000, v19
	v_lshlrev_b32_e32 v22, 16, v23
	v_and_b32_e32 v23, 0xffff0000, v23
	v_pk_fma_f32 v[14:15], v[14:15], v[18:19], v[22:23]
	v_lshlrev_b32_e32 v18, 16, v20
	v_and_b32_e32 v19, 0xffff0000, v20
	v_lshlrev_b32_e32 v22, 16, v24
	v_and_b32_e32 v23, 0xffff0000, v24
	v_pk_fma_f32 v[18:19], v[8:9], v[18:19], v[22:23]
	v_lshlrev_b32_e32 v8, 16, v21
	v_and_b32_e32 v9, 0xffff0000, v21
	v_lshlrev_b32_e32 v20, 16, v25
	v_and_b32_e32 v21, 0xffff0000, v25
	v_pk_fma_f32 v[12:13], v[12:13], v[28:29], v[30:31]
	v_pk_fma_f32 v[20:21], v[10:11], v[8:9], v[20:21]
	v_cvt_pk_bf16_f32 v8, v12, v13
	v_cvt_pk_bf16_f32 v9, v14, v15
	v_cvt_pk_bf16_f32 v10, v18, v19
	v_cvt_pk_bf16_f32 v11, v20, v21
	global_store_dwordx4 v[26:27], v[8:11], off
	v_pk_mul_f32 v[6:7], v[6:7], v[16:17] op_sel_hi:[1,0]
	v_pk_mul_f32 v[0:1], v[0:1], v[16:17] op_sel_hi:[1,0]
	v_lshl_add_u64 v[8:9], v[158:159], 0, s[2:3]
	v_lshl_add_u64 v[10:11], s[30:31], 0, v[8:9]
	v_lshl_add_u64 v[18:19], s[0:1], 0, v[8:9]
	s_nop 1
	v_mov_b32_e32 v12, v216
	v_mov_b32_e32 v13, v217
	v_mov_b32_e32 v14, v218
	v_mov_b32_e32 v15, v219
	v_mul_f32_e32 v6, 0xbfb8aa3b, v6
	s_nop 1
	v_mov_b32_e32 v8, v220
	v_mov_b32_e32 v9, v221
	v_mov_b32_e32 v10, v222
	v_mov_b32_e32 v11, v223
	v_mul_f32_e32 v7, 0xbfb8aa3b, v7
	v_pk_mul_f32 v[4:5], v[4:5], v[16:17] op_sel_hi:[1,0]
	v_pk_mul_f32 v[2:3], v[2:3], v[16:17] op_sel_hi:[1,0]
	v_exp_f32_e32 v6, v6
	v_exp_f32_e32 v7, v7
	v_mul_f32_e32 v0, 0xbfb8aa3b, v0
	v_mul_f32_e32 v1, 0xbfb8aa3b, v1
	v_mul_f32_e32 v4, 0xbfb8aa3b, v4
	v_mul_f32_e32 v5, 0xbfb8aa3b, v5
	v_exp_f32_e32 v0, v0
	v_exp_f32_e32 v1, v1
	v_mul_f32_e32 v2, 0xbfb8aa3b, v2
	v_mul_f32_e32 v3, 0xbfb8aa3b, v3
	v_exp_f32_e32 v4, v4
	v_exp_f32_e32 v5, v5
	v_exp_f32_e32 v2, v2
	v_exp_f32_e32 v3, v3
	v_add_f32_e32 v6, 1.0, v6
	v_add_f32_e32 v7, 1.0, v7
	v_rcp_f32_e32 v6, v6
	v_rcp_f32_e32 v7, v7
	v_add_f32_e32 v0, 1.0, v0
	v_add_f32_e32 v1, 1.0, v1
	v_add_f32_e32 v4, 1.0, v4
	v_add_f32_e32 v5, 1.0, v5
	v_rcp_f32_e32 v0, v0
	v_rcp_f32_e32 v1, v1
	v_add_f32_e32 v2, 1.0, v2
	v_add_f32_e32 v3, 1.0, v3
	v_rcp_f32_e32 v4, v4
	v_rcp_f32_e32 v5, v5
	v_rcp_f32_e32 v2, v2
	v_rcp_f32_e32 v3, v3
	s_and_b64 vcc, exec, s[38:39]
	s_mov_b32 s3, s26
	s_mov_b32 s2, s12
	v_lshlrev_b32_e32 v16, 16, v12
	v_and_b32_e32 v17, 0xffff0000, v12
	v_lshlrev_b32_e32 v20, 16, v8
	v_and_b32_e32 v21, 0xffff0000, v8
	v_lshlrev_b32_e32 v12, 16, v13
	v_and_b32_e32 v13, 0xffff0000, v13
	v_lshlrev_b32_e32 v8, 16, v9
	v_and_b32_e32 v9, 0xffff0000, v9
	v_pk_fma_f32 v[6:7], v[6:7], v[12:13], v[8:9]
	v_lshlrev_b32_e32 v8, 16, v14
	v_and_b32_e32 v9, 0xffff0000, v14
	v_lshlrev_b32_e32 v12, 16, v10
	v_and_b32_e32 v13, 0xffff0000, v10
	v_pk_fma_f32 v[8:9], v[0:1], v[8:9], v[12:13]
	v_lshlrev_b32_e32 v0, 16, v15
	v_and_b32_e32 v1, 0xffff0000, v15
	v_lshlrev_b32_e32 v10, 16, v11
	v_and_b32_e32 v11, 0xffff0000, v11
	v_pk_fma_f32 v[4:5], v[4:5], v[16:17], v[20:21]
	v_pk_fma_f32 v[10:11], v[2:3], v[0:1], v[10:11]
	v_cvt_pk_bf16_f32 v0, v4, v5
	v_cvt_pk_bf16_f32 v1, v6, v7
	v_cvt_pk_bf16_f32 v2, v8, v9
	v_cvt_pk_bf16_f32 v3, v10, v11
	global_store_dwordx4 v[18:19], v[0:3], off
	s_cbranch_vccz .LBB0_346
	s_waitcnt vmcnt(0)
	s_cmpk_gt_u32 s70, 0xff
	s_cbranch_scc1 .LBB0_357
	s_barrier

; __device__ __forceinline__ unsigned cvt_pk_bf16(float lo, float hi) { const f32x2_cv v = {lo, hi}; const bf16x2_cv b = __builtin_convertvector(v, bf16x2_cv); return __builtin_bit_cast(unsigned, b); }
; __device__ void phase_rwkv_fix(const Ctx& p, int l) {
;     ...
;                 for (int ks = 0; ks < 2; ++ks) { const float* sp = UC + (size_t)it * 4096 + (vt * 16 + fr) * 64 + ks * 32 + fq * 8; const float4 a = *(const float4*)sp, b4 = *(const float4*)(sp + 4);
;                     u32x4 w; w.x = cvt_pk_bf16(a.x, a.y); w.y = cvt_pk_bf16(a.z, a.w); w.z = cvt_pk_bf16(b4.x, b4.y); w.w = cvt_pk_bf16(b4.z, b4.w); X[vt][ks] = __builtin_bit_cast(bf16x8, w); }
.LBB0_558:
	v_lshl_add_u64 v[32:33], s[4:5], 2, v[76:77]
	s_mov_b64 s[4:5], 0x2000
	v_lshl_add_u64 v[34:35], v[32:33], 0, s[4:5]
	global_load_dwordx4 v[168:171], v[32:33], off
	global_load_dwordx4 v[172:175], v[32:33], off offset:16
	global_load_dwordx4 v[176:179], v[32:33], off offset:128
	global_load_dwordx4 v[180:183], v[32:33], off offset:144
	global_load_dwordx4 v[192:195], v[34:35], off offset:-4096
	global_load_dwordx4 v[196:199], v[34:35], off offset:-4080
	global_load_dwordx4 v[200:203], v[34:35], off offset:-3968
	global_load_dwordx4 v[204:207], v[34:35], off offset:-3952
	v_lshl_add_u64 v[32:33], v[32:33], 0, s[8:9]
	global_load_dwordx4 v[208:211], v[34:35], off
	global_load_dwordx4 v[212:215], v[34:35], off offset:16
	global_load_dwordx4 v[216:219], v[34:35], off offset:128
	global_load_dwordx4 v[220:223], v[34:35], off offset:144
	global_load_dwordx4 v[224:227], v[32:33], off
	global_load_dwordx4 v[228:231], v[32:33], off offset:16
	global_load_dwordx4 v[232:235], v[32:33], off offset:128
	global_load_dwordx4 v[236:239], v[32:33], off offset:144
	s_mov_b64 s[4:5], 0x3080
	s_waitcnt vmcnt(12)
	v_cvt_pk_bf16_f32 v0, v168, v169
	v_cvt_pk_bf16_f32 v1, v170, v171
	v_cvt_pk_bf16_f32 v2, v172, v173
	v_cvt_pk_bf16_f32 v3, v174, v175
	v_cvt_pk_bf16_f32 v4, v176, v177
	v_cvt_pk_bf16_f32 v5, v178, v179
	v_cvt_pk_bf16_f32 v6, v180, v181
	v_cvt_pk_bf16_f32 v7, v182, v183
	s_waitcnt vmcnt(8)
	v_cvt_pk_bf16_f32 v8, v192, v193
	v_cvt_pk_bf16_f32 v9, v194, v195
	v_cvt_pk_bf16_f32 v10, v196, v197
	v_cvt_pk_bf16_f32 v11, v198, v199
	v_cvt_pk_bf16_f32 v12, v200, v201
	v_cvt_pk_bf16_f32 v13, v202, v203
	v_cvt_pk_bf16_f32 v14, v204, v205
	v_cvt_pk_bf16_f32 v15, v206, v207
	s_waitcnt vmcnt(4)
	v_cvt_pk_bf16_f32 v16, v208, v209
	v_cvt_pk_bf16_f32 v17, v210, v211
	v_cvt_pk_bf16_f32 v18, v212, v213
	v_cvt_pk_bf16_f32 v19, v214, v215
	v_cvt_pk_bf16_f32 v20, v216, v217
	v_cvt_pk_bf16_f32 v21, v218, v219
	v_cvt_pk_bf16_f32 v22, v220, v221
	v_cvt_pk_bf16_f32 v23, v222, v223
	s_waitcnt vmcnt(0)
	v_cvt_pk_bf16_f32 v24, v224, v225
	v_cvt_pk_bf16_f32 v25, v226, v227
	v_cvt_pk_bf16_f32 v26, v228, v229
	v_cvt_pk_bf16_f32 v27, v230, v231
	v_cvt_pk_bf16_f32 v28, v232, v233
	v_cvt_pk_bf16_f32 v29, v234, v235
	v_cvt_pk_bf16_f32 v30, v236, v237
	v_cvt_pk_bf16_f32 v31, v238, v239

; #define PG8_STAGE(bufoff, gbase, voff) do { _Pragma("unroll") for (int _i = 0; _i < 2; ++_i) \
;         __builtin_amdgcn_global_load_lds((const unsigned*)((const char*)(gbase) + (voff)[_i]), (PG8_LAS unsigned*)(lds + (bufoff) + ldsw + _i * 8192), 16, 0, 0); } while (0)
; #define PG8_LDA(dst, b, h) do { _Pragma("unroll") for (int m = 0; m < 4; ++m) _Pragma("unroll") for (int k = 0; k < 2; ++k) dst[m][k] = *(const PG8_LAS bf16x8*)(lds + PG8_SA(b, h) + aoff + m * 2048 + k * 1024); } while (0)
; #define PG8_LDB(dst, b, h) do { _Pragma("unroll") for (int n = 0; n < 2; ++n) _Pragma("unroll") for (int k = 0; k < 2; ++k) dst[n][k] = *(const PG8_LAS bf16x8*)(lds + PG8_SB(b, h) + boff + n * 2048 + k * 1024); } while (0)
; #define PG8_MMA(ai, bj, At, Bt) do { __builtin_amdgcn_s_setprio(1); _Pragma("unroll") for (int m = 0; m < 4; ++m) _Pragma("unroll") for (int n = 0; n < 2; ++n) _Pragma("unroll") for (int k = 0; k < 2; ++k) \
;         acc[ai][bj][m][n] = __builtin_amdgcn_mfma_f32_16x16x32_bf16(Bt[n][k], At[m][k], acc[ai][bj][m][n], 0, 0, 0); __builtin_amdgcn_s_setprio(0); } while (0)
; #define PG8_WAIT_L(n) asm volatile("s_waitcnt lgkmcnt(" #n ")" ::: "memory")
; #define PG8_BAR __builtin_amdgcn_s_barrier()
; #define PG8_SCHED __builtin_amdgcn_sched_barrier(0)
; template <class Epi, class Sched, bool STAMP = false>
; __device__ __forceinline__ void gemm_phase(PG8_LAS unsigned char* lds, const Gemm g, const Sched& S, const Epi& E, unsigned long long* stamps) {
;     ...
;             PG8_LDB(B0, 0, 0); PG8_SCHED; PG8_LDA(At, 0, 0); PG8_STAGE(PG8_SA(1, 1), a1 + hstep, voffA);
;             PG8_WAIT_L(8); PG8_BAR; PG8_WAIT_L(0); PG8_MMA(0, 0, At, B0); PG8_BAR; PG8_SCHED;
;             PG8_LDB(B1, 0, 1); PG8_STAGE(PG8_SB(0, 0), b2, voffB);
;             PG8_BAR; PG8_WAIT_L(0); PG8_MMA(0, 1, At, B1); PG8_BAR;
;             PG8_LDA(At, 0, 1); PG8_STAGE(PG8_SA(0, 0), a2, voffA);
;             PG8_BAR; PG8_WAIT_L(0); PG8_MMA(1, 0, At, B0); PG8_BAR; PG8_SCHED;
.LBB0_1183:
	s_add_u32 s30, s26, 0x100
	s_addc_u32 s31, s27, 0
	s_add_i32 s14, 0, 0x10000
	v_add_u32_e32 v161, s14, v158
	ds_read_b128 v[154:157], v161
	ds_read_b128 v[162:165], v161 offset:1024
	ds_read_b128 v[166:169], v161 offset:2048
	ds_read_b128 v[170:173], v161 offset:3072
	s_cmp_eq_u32 s65, 60
	s_cselect_b32 s37, s7, s31
	s_cselect_b32 s36, s23, s30
	s_cselect_b32 s35, s5, s64
	s_cselect_b32 s34, s62, s63
	v_lshl_add_u64 v[182:183], s[26:27], 0, v[150:151]
	s_add_i32 m0, s25, 0xc000
	ds_read_b128 v[174:177], v160
	ds_read_b128 v[178:181], v160 offset:1024
	ds_read_b128 v[192:195], v160 offset:2048
	ds_read_b128 v[196:199], v160 offset:3072
	ds_read_b128 v[200:203], v160 offset:4096
	ds_read_b128 v[204:207], v160 offset:5120
	ds_read_b128 v[208:211], v160 offset:6144
	ds_read_b128 v[212:215], v160 offset:7168
	global_load_lds_dwordx4 v[182:183], off
	v_lshl_add_u64 v[182:183], s[26:27], 0, v[152:153]
	s_add_i32 m0, s25, 0xe000
	s_nop 0
	global_load_lds_dwordx4 v[182:183], off
	s_waitcnt lgkmcnt(8)
	s_barrier
	s_waitcnt lgkmcnt(0)
	s_setprio 1
	s_waitcnt lgkmcnt(0)
	v_mfma_f32_16x16x32_bf16 v[124:127], v[154:157], v[174:177], v[124:127]
	v_mfma_f32_16x16x32_bf16 v[120:123], v[166:169], v[174:177], v[120:123]
	v_mfma_f32_16x16x32_bf16 v[108:111], v[154:157], v[192:195], v[108:111]
	v_mfma_f32_16x16x32_bf16 v[104:107], v[166:169], v[192:195], v[104:107]
	v_mfma_f32_16x16x32_bf16 v[92:95], v[154:157], v[200:203], v[92:95]
	v_mfma_f32_16x16x32_bf16 v[88:91], v[166:169], v[200:203], v[88:91]
	v_mfma_f32_16x16x32_bf16 v[76:79], v[154:157], v[208:211], v[76:79]
	v_mfma_f32_16x16x32_bf16 v[72:75], v[166:169], v[208:211], v[72:75]
	v_mfma_f32_16x16x32_bf16 v[124:127], v[162:165], v[178:181], v[124:127]
	v_mfma_f32_16x16x32_bf16 v[120:123], v[170:173], v[178:181], v[120:123]
	v_mfma_f32_16x16x32_bf16 v[108:111], v[162:165], v[196:199], v[108:111]
	v_mfma_f32_16x16x32_bf16 v[104:107], v[170:173], v[196:199], v[104:107]
	v_mfma_f32_16x16x32_bf16 v[92:95], v[162:165], v[204:207], v[92:95]
	v_mfma_f32_16x16x32_bf16 v[88:91], v[170:173], v[204:207], v[88:91]
	v_mfma_f32_16x16x32_bf16 v[76:79], v[162:165], v[212:215], v[76:79]
	v_mfma_f32_16x16x32_bf16 v[72:75], v[170:173], v[212:215], v[72:75]
	s_setprio 0
	s_barrier
	s_add_i32 s16, 0, 0x14000
	s_add_i32 s14, s14, s49
	v_add_u32_e32 v161, s16, v158
	v_lshl_add_u64 v[182:183], s[34:35], 0, v[128:129]
	s_mov_b32 m0, s14
	ds_read_b128 v[216:219], v161
	ds_read_b128 v[220:223], v161 offset:1024
	ds_read_b128 v[224:227], v161 offset:2048
	ds_read_b128 v[228:231], v161 offset:3072
	global_load_lds_dwordx4 v[182:183], off
	v_lshl_add_u64 v[232:233], s[34:35], 0, v[148:149]
	s_add_i32 m0, s14, 0x2000
	s_nop 0
	global_load_lds_dwordx4 v[232:233], off
	s_barrier
	s_waitcnt lgkmcnt(0)
	s_setprio 1
	s_waitcnt lgkmcnt(0)
	v_mfma_f32_16x16x32_bf16 v[116:119], v[216:219], v[174:177], v[116:119]
	v_mfma_f32_16x16x32_bf16 v[112:115], v[224:227], v[174:177], v[112:115]
	v_mfma_f32_16x16x32_bf16 v[100:103], v[216:219], v[192:195], v[100:103]
	v_mfma_f32_16x16x32_bf16 v[96:99], v[224:227], v[192:195], v[96:99]
	v_mfma_f32_16x16x32_bf16 v[84:87], v[216:219], v[200:203], v[84:87]
	v_mfma_f32_16x16x32_bf16 v[80:83], v[224:227], v[200:203], v[80:83]
	v_mfma_f32_16x16x32_bf16 v[68:71], v[216:219], v[208:211], v[68:71]
	v_mfma_f32_16x16x32_bf16 v[64:67], v[224:227], v[208:211], v[64:67]
	v_mfma_f32_16x16x32_bf16 v[116:119], v[220:223], v[178:181], v[116:119]
	v_mfma_f32_16x16x32_bf16 v[112:115], v[228:231], v[178:181], v[112:115]
	v_mfma_f32_16x16x32_bf16 v[100:103], v[220:223], v[196:199], v[100:103]
	v_mfma_f32_16x16x32_bf16 v[96:99], v[228:231], v[196:199], v[96:99]
	v_mfma_f32_16x16x32_bf16 v[84:87], v[220:223], v[204:207], v[84:87]
	v_mfma_f32_16x16x32_bf16 v[80:83], v[228:231], v[204:207], v[80:83]
	v_mfma_f32_16x16x32_bf16 v[68:71], v[220:223], v[212:215], v[68:71]
	v_mfma_f32_16x16x32_bf16 v[64:67], v[228:231], v[212:215], v[64:67]
	s_setprio 0
	s_mov_b32 m0, s25
	v_lshl_add_u64 v[234:235], s[36:37], 0, v[128:129]
	s_barrier
	ds_read_b128 v[174:177], v160 offset:16384
	ds_read_b128 v[178:181], v160 offset:17408
	ds_read_b128 v[192:195], v160 offset:18432
	ds_read_b128 v[196:199], v160 offset:19456
	ds_read_b128 v[200:203], v160 offset:20480
	ds_read_b128 v[204:207], v160 offset:21504
	ds_read_b128 v[208:211], v160 offset:22528
	ds_read_b128 v[212:215], v160 offset:23552
	global_load_lds_dwordx4 v[234:235], off
	v_lshl_add_u64 v[236:237], s[36:37], 0, v[148:149]
	s_mov_b32 m0, s53
	s_nop 0
	global_load_lds_dwordx4 v[236:237], off
	s_barrier
	s_waitcnt lgkmcnt(0)
	s_setprio 1
	s_waitcnt lgkmcnt(0)
	v_mfma_f32_16x16x32_bf16 v[60:63], v[154:157], v[174:177], v[60:63]
	v_mfma_f32_16x16x32_bf16 v[56:59], v[166:169], v[174:177], v[56:59]
	v_mfma_f32_16x16x32_bf16 v[44:47], v[154:157], v[192:195], v[44:47]
	v_mfma_f32_16x16x32_bf16 v[40:43], v[166:169], v[192:195], v[40:43]
	v_mfma_f32_16x16x32_bf16 v[28:31], v[154:157], v[200:203], v[28:31]
	v_mfma_f32_16x16x32_bf16 v[24:27], v[166:169], v[200:203], v[24:27]
	v_mfma_f32_16x16x32_bf16 v[12:15], v[154:157], v[208:211], v[12:15]
	v_mfma_f32_16x16x32_bf16 v[8:11], v[166:169], v[208:211], v[8:11]
	v_mfma_f32_16x16x32_bf16 v[60:63], v[162:165], v[178:181], v[60:63]
	v_mfma_f32_16x16x32_bf16 v[56:59], v[170:173], v[178:181], v[56:59]
	v_mfma_f32_16x16x32_bf16 v[44:47], v[162:165], v[196:199], v[44:47]
	v_mfma_f32_16x16x32_bf16 v[40:43], v[170:173], v[196:199], v[40:43]
	v_mfma_f32_16x16x32_bf16 v[28:31], v[162:165], v[204:207], v[28:31]
	v_mfma_f32_16x16x32_bf16 v[24:27], v[170:173], v[204:207], v[24:27]
	v_mfma_f32_16x16x32_bf16 v[12:15], v[162:165], v[212:215], v[12:15]
	v_mfma_f32_16x16x32_bf16 v[8:11], v[170:173], v[212:215], v[8:11]
	s_setprio 0
	s_barrier
; #define PG8_STAGE(bufoff, gbase, voff) do { _Pragma("unroll") for (int _i = 0; _i < 2; ++_i) \
;         __builtin_amdgcn_global_load_lds((const unsigned*)((const char*)(gbase) + (voff)[_i]), (PG8_LAS unsigned*)(lds + (bufoff) + ldsw + _i * 8192), 16, 0, 0); } while (0)
; #define PG8_LDA(dst, b, h) do { _Pragma("unroll") for (int m = 0; m < 4; ++m) _Pragma("unroll") for (int k = 0; k < 2; ++k) dst[m][k] = *(const PG8_LAS bf16x8*)(lds + PG8_SA(b, h) + aoff + m * 2048 + k * 1024); } while (0)
; #define PG8_LDB(dst, b, h) do { _Pragma("unroll") for (int n = 0; n < 2; ++n) _Pragma("unroll") for (int k = 0; k < 2; ++k) dst[n][k] = *(const PG8_LAS bf16x8*)(lds + PG8_SB(b, h) + boff + n * 2048 + k * 1024); } while (0)
; #define PG8_MMA(ai, bj, At, Bt) do { __builtin_amdgcn_s_setprio(1); _Pragma("unroll") for (int m = 0; m < 4; ++m) _Pragma("unroll") for (int n = 0; n < 2; ++n) _Pragma("unroll") for (int k = 0; k < 2; ++k) \
;         acc[ai][bj][m][n] = __builtin_amdgcn_mfma_f32_16x16x32_bf16(Bt[n][k], At[m][k], acc[ai][bj][m][n], 0, 0, 0); __builtin_amdgcn_s_setprio(0); } while (0)
; #define PG8_WAIT_V(n) asm volatile("s_waitcnt vmcnt(" #n ")" ::: "memory")
; #define PG8_WAIT_L(n) asm volatile("s_waitcnt lgkmcnt(" #n ")" ::: "memory")
; #define PG8_BAR __builtin_amdgcn_s_barrier()
; #define PG8_SCHED __builtin_amdgcn_sched_barrier(0)
; template <class Epi, class Sched, bool STAMP = false>
; __device__ __forceinline__ void gemm_phase(PG8_LAS unsigned char* lds, const Gemm g, const Sched& S, const Epi& E, unsigned long long* stamps) {
;     ...
;             PG8_STAGE(PG8_SB(0, 1), b2 + hstep, voffB);
;             PG8_WAIT_V(6); PG8_BAR; PG8_MMA(1, 1, At, B1); PG8_BAR;
;             PG8_LDB(B0, 1, 0); PG8_SCHED; PG8_LDA(At, 1, 0); PG8_STAGE(PG8_SA(0, 1), a2 + hstep, voffA);
;             PG8_WAIT_L(8); PG8_BAR; PG8_WAIT_L(0); PG8_MMA(0, 0, At, B0); PG8_BAR; PG8_SCHED;
;             PG8_LDB(B1, 1, 1); PG8_STAGE(PG8_SB(1, 0), b3, voffB);
;             PG8_BAR; PG8_WAIT_L(0); PG8_MMA(0, 1, At, B1); PG8_BAR;
;             PG8_LDA(At, 1, 1); PG8_STAGE(PG8_SA(1, 0), a3, voffA);
;             PG8_BAR; PG8_WAIT_L(0); PG8_MMA(1, 0, At, B0); PG8_BAR; PG8_SCHED;
	s_add_u32 s14, s34, 0x100000
	s_addc_u32 s15, s35, 0
	s_add_i32 s16, s16, s49
	v_lshl_add_u64 v[154:155], s[14:15], 0, v[128:129]
	s_mov_b32 m0, s16
	s_nop 0
	global_load_lds_dwordx4 v[154:155], off
	v_lshl_add_u64 v[154:155], s[14:15], 0, v[148:149]
	s_add_i32 m0, s16, 0x2000
	s_nop 0
	global_load_lds_dwordx4 v[154:155], off
	s_waitcnt vmcnt(6)
	s_barrier
	s_setprio 1
	v_mfma_f32_16x16x32_bf16 v[52:55], v[216:219], v[174:177], v[52:55]
	v_mfma_f32_16x16x32_bf16 v[48:51], v[224:227], v[174:177], v[48:51]
	v_mfma_f32_16x16x32_bf16 v[36:39], v[216:219], v[192:195], v[36:39]
	v_mfma_f32_16x16x32_bf16 v[32:35], v[224:227], v[192:195], v[32:35]
	v_mfma_f32_16x16x32_bf16 v[20:23], v[216:219], v[200:203], v[20:23]
	v_mfma_f32_16x16x32_bf16 v[16:19], v[224:227], v[200:203], v[16:19]
	v_mfma_f32_16x16x32_bf16 v[4:7], v[216:219], v[208:211], v[4:7]
	v_mfma_f32_16x16x32_bf16 v[0:3], v[224:227], v[208:211], v[0:3]
	v_mfma_f32_16x16x32_bf16 v[52:55], v[220:223], v[178:181], v[52:55]
	v_mfma_f32_16x16x32_bf16 v[48:51], v[228:231], v[178:181], v[48:51]
	v_mfma_f32_16x16x32_bf16 v[36:39], v[220:223], v[196:199], v[36:39]
	v_mfma_f32_16x16x32_bf16 v[32:35], v[228:231], v[196:199], v[32:35]
	v_mfma_f32_16x16x32_bf16 v[20:23], v[220:223], v[204:207], v[20:23]
	v_mfma_f32_16x16x32_bf16 v[16:19], v[228:231], v[204:207], v[16:19]
	v_mfma_f32_16x16x32_bf16 v[4:7], v[220:223], v[212:215], v[4:7]
	v_mfma_f32_16x16x32_bf16 v[0:3], v[228:231], v[212:215], v[0:3]
	s_setprio 0
	s_add_i32 s16, 0, 0x18000
	v_add_u32_e32 v161, s16, v158
	s_barrier
	ds_read_b128 v[154:157], v161
	ds_read_b128 v[162:165], v161 offset:1024
	ds_read_b128 v[166:169], v161 offset:2048
	ds_read_b128 v[170:173], v161 offset:3072
	s_add_u32 s14, s36, 0x100000
	s_addc_u32 s15, s37, 0
	s_mov_b32 m0, s56
	v_lshl_add_u64 v[216:217], s[14:15], 0, v[128:129]
	ds_read_b128 v[174:177], v160 offset:32768
	ds_read_b128 v[178:181], v160 offset:33792
	ds_read_b128 v[192:195], v160 offset:34816
	ds_read_b128 v[196:199], v160 offset:35840
	ds_read_b128 v[200:203], v160 offset:36864
	ds_read_b128 v[204:207], v160 offset:37888
	ds_read_b128 v[208:211], v160 offset:38912
	ds_read_b128 v[212:215], v160 offset:39936
	global_load_lds_dwordx4 v[216:217], off
	v_lshl_add_u64 v[216:217], s[14:15], 0, v[148:149]
	s_mov_b32 m0, s57
	s_nop 0
	global_load_lds_dwordx4 v[216:217], off
	s_waitcnt lgkmcnt(8)
	s_barrier
	s_waitcnt lgkmcnt(0)
	s_setprio 1
	s_waitcnt lgkmcnt(0)
	v_mfma_f32_16x16x32_bf16 v[124:127], v[154:157], v[174:177], v[124:127]
	v_mfma_f32_16x16x32_bf16 v[120:123], v[166:169], v[174:177], v[120:123]
	v_mfma_f32_16x16x32_bf16 v[108:111], v[154:157], v[192:195], v[108:111]
	v_mfma_f32_16x16x32_bf16 v[104:107], v[166:169], v[192:195], v[104:107]
	v_mfma_f32_16x16x32_bf16 v[92:95], v[154:157], v[200:203], v[92:95]
	v_mfma_f32_16x16x32_bf16 v[88:91], v[166:169], v[200:203], v[88:91]
	v_mfma_f32_16x16x32_bf16 v[76:79], v[154:157], v[208:211], v[76:79]
	v_mfma_f32_16x16x32_bf16 v[72:75], v[166:169], v[208:211], v[72:75]
	v_mfma_f32_16x16x32_bf16 v[124:127], v[162:165], v[178:181], v[124:127]
	v_mfma_f32_16x16x32_bf16 v[120:123], v[170:173], v[178:181], v[120:123]
	v_mfma_f32_16x16x32_bf16 v[108:111], v[162:165], v[196:199], v[108:111]
	v_mfma_f32_16x16x32_bf16 v[104:107], v[170:173], v[196:199], v[104:107]
	v_mfma_f32_16x16x32_bf16 v[92:95], v[162:165], v[204:207], v[92:95]
	v_mfma_f32_16x16x32_bf16 v[88:91], v[170:173], v[204:207], v[88:91]
	v_mfma_f32_16x16x32_bf16 v[76:79], v[162:165], v[212:215], v[76:79]
	v_mfma_f32_16x16x32_bf16 v[72:75], v[170:173], v[212:215], v[72:75]
	s_setprio 0
	s_barrier
	s_add_i32 s17, 0, 0x1c000
	s_add_i32 s14, s16, s49
	v_add_u32_e32 v161, s17, v158
	v_lshl_add_u64 v[182:183], v[182:183], 0, s[18:19]
	s_mov_b32 m0, s14
	ds_read_b128 v[216:219], v161
	ds_read_b128 v[220:223], v161 offset:1024
	ds_read_b128 v[224:227], v161 offset:2048
	ds_read_b128 v[228:231], v161 offset:3072
	global_load_lds_dwordx4 v[182:183], off
	v_lshl_add_u64 v[182:183], v[232:233], 0, s[18:19]
	s_add_i32 m0, s14, 0x2000
	s_nop 0
	global_load_lds_dwordx4 v[182:183], off
	s_barrier
	s_waitcnt lgkmcnt(0)
	s_setprio 1
	s_waitcnt lgkmcnt(0)
	v_mfma_f32_16x16x32_bf16 v[116:119], v[216:219], v[174:177], v[116:119]
	v_mfma_f32_16x16x32_bf16 v[112:115], v[224:227], v[174:177], v[112:115]
	v_mfma_f32_16x16x32_bf16 v[100:103], v[216:219], v[192:195], v[100:103]
	v_mfma_f32_16x16x32_bf16 v[96:99], v[224:227], v[192:195], v[96:99]
	v_mfma_f32_16x16x32_bf16 v[84:87], v[216:219], v[200:203], v[84:87]
	v_mfma_f32_16x16x32_bf16 v[80:83], v[224:227], v[200:203], v[80:83]
	v_mfma_f32_16x16x32_bf16 v[68:71], v[216:219], v[208:211], v[68:71]
	v_mfma_f32_16x16x32_bf16 v[64:67], v[224:227], v[208:211], v[64:67]
	v_mfma_f32_16x16x32_bf16 v[116:119], v[220:223], v[178:181], v[116:119]
	v_mfma_f32_16x16x32_bf16 v[112:115], v[228:231], v[178:181], v[112:115]
	v_mfma_f32_16x16x32_bf16 v[100:103], v[220:223], v[196:199], v[100:103]
	v_mfma_f32_16x16x32_bf16 v[96:99], v[228:231], v[196:199], v[96:99]
	v_mfma_f32_16x16x32_bf16 v[84:87], v[220:223], v[204:207], v[84:87]
	v_mfma_f32_16x16x32_bf16 v[80:83], v[228:231], v[204:207], v[80:83]
	v_mfma_f32_16x16x32_bf16 v[68:71], v[220:223], v[212:215], v[68:71]
	v_mfma_f32_16x16x32_bf16 v[64:67], v[228:231], v[212:215], v[64:67]
	s_setprio 0
	s_mov_b32 m0, s59
	v_lshl_add_u64 v[182:183], v[234:235], 0, s[18:19]
	s_barrier
	ds_read_b128 v[174:177], v160 offset:49152
	ds_read_b128 v[178:181], v160 offset:50176
	ds_read_b128 v[192:195], v160 offset:51200
	ds_read_b128 v[196:199], v160 offset:52224
	ds_read_b128 v[200:203], v160 offset:53248
	ds_read_b128 v[204:207], v160 offset:54272
	ds_read_b128 v[208:211], v160 offset:55296
	ds_read_b128 v[212:215], v160 offset:56320
	global_load_lds_dwordx4 v[182:183], off
	v_lshl_add_u64 v[182:183], v[236:237], 0, s[18:19]
	s_mov_b32 m0, s60
	s_nop 0
	global_load_lds_dwordx4 v[182:183], off
	s_barrier
; __device__ __forceinline__ unsigned cvt_pk_bf16(float lo, float hi) { const f32x2_cv v = {lo, hi}; const bf16x2_cv b = __builtin_convertvector(v, bf16x2_cv); return __builtin_bit_cast(unsigned, b); }
; #define PG8_STAGE(bufoff, gbase, voff) do { _Pragma("unroll") for (int _i = 0; _i < 2; ++_i) \
;         __builtin_amdgcn_global_load_lds((const unsigned*)((const char*)(gbase) + (voff)[_i]), (PG8_LAS unsigned*)(lds + (bufoff) + ldsw + _i * 8192), 16, 0, 0); } while (0)
; #define PG8_WAIT_V(n) asm volatile("s_waitcnt vmcnt(" #n ")" ::: "memory")
; #define PG8_BAR __builtin_amdgcn_s_barrier()
; template <class Epi, class Sched, bool STAMP = false>
; __device__ __forceinline__ void gemm_phase(PG8_LAS unsigned char* lds, const Gemm g, const Sched& S, const Epi& E, unsigned long long* stamps) {
;     ...
;             PG8_BAR; PG8_WAIT_L(0); PG8_MMA(1, 0, At, B0); PG8_BAR; PG8_SCHED;
;             PG8_STAGE(PG8_SB(1, 1), b3 + hstep, voffB);
;             PG8_WAIT_V(6); PG8_BAR; PG8_MMA(1, 1, At, B1); PG8_BAR;
;     __device__ __forceinline__ void operator()(const f32x4 (&acc)[2][2][4][2], const pg8::Unit& u, int wr, int wc, int fr, int fq) const {
;         const int row0 = u.pm * 256 + wr * 64 + fr, col0 = u.pn * 256 + wc * 32 + 4 * fq;
; #pragma unroll
;         for (int ai = 0; ai < 2; ++ai)
; #pragma unroll
;             for (int m = 0; m < 4; ++m) {
;                 const int row = row0 + ai * 128 + m * 16;
;                 float* xp = X + (size_t)row * 1024 + col0; bf16_t* bp = XB + (size_t)row * 1024 + col0;
;                 const float* xi = Xp0 ? (row < T_P ? Xp0 + (size_t)row * 1024 + col0 : Xs0 + (size_t)(row - T_P) * 1024 + col0) : xp;
;                 float ss = 0.f;
; #pragma unroll
;                 for (int bj = 0; bj < 2; ++bj)
; #pragma unroll
;                     for (int n = 0; n < 2; ++n) {
;                         f32x4 xv = *(const f32x4*)(xi + bj * 128 + n * 16) + acc[ai][bj][m][n];
;                         *(f32x4*)(xp + bj * 128 + n * 16) = xv;
;                         ss += (xv[0] * xv[0] + xv[1] * xv[1]) + (xv[2] * xv[2] + xv[3] * xv[3]);
;                         u32x2 w; w.x = cvt_pk_bf16(xv[0], xv[1]); w.y = cvt_pk_bf16(xv[2], xv[3]);
;                         *(u32x2*)(bp + bj * 128 + n * 16) = w; }
;                 ss += __shfl_xor(ss, 16); ss += __shfl_xor(ss, 32);
;                 if (fq == 0) atomicAdd(rowss_out + row, ss); }
	s_waitcnt lgkmcnt(0)
	s_setprio 1
	s_waitcnt lgkmcnt(0)
	v_mfma_f32_16x16x32_bf16 v[60:63], v[154:157], v[174:177], v[60:63]
	v_mfma_f32_16x16x32_bf16 v[56:59], v[166:169], v[174:177], v[56:59]
	v_mfma_f32_16x16x32_bf16 v[44:47], v[154:157], v[192:195], v[44:47]
	v_mfma_f32_16x16x32_bf16 v[40:43], v[166:169], v[192:195], v[40:43]
	v_mfma_f32_16x16x32_bf16 v[28:31], v[154:157], v[200:203], v[28:31]
	v_mfma_f32_16x16x32_bf16 v[24:27], v[166:169], v[200:203], v[24:27]
	v_mfma_f32_16x16x32_bf16 v[12:15], v[154:157], v[208:211], v[12:15]
	v_mfma_f32_16x16x32_bf16 v[8:11], v[166:169], v[208:211], v[8:11]
	v_mfma_f32_16x16x32_bf16 v[60:63], v[162:165], v[178:181], v[60:63]
	v_mfma_f32_16x16x32_bf16 v[56:59], v[170:173], v[178:181], v[56:59]
	v_mfma_f32_16x16x32_bf16 v[44:47], v[162:165], v[196:199], v[44:47]
	v_mfma_f32_16x16x32_bf16 v[40:43], v[170:173], v[196:199], v[40:43]
	v_mfma_f32_16x16x32_bf16 v[28:31], v[162:165], v[204:207], v[28:31]
	v_mfma_f32_16x16x32_bf16 v[24:27], v[170:173], v[204:207], v[24:27]
	v_mfma_f32_16x16x32_bf16 v[12:15], v[162:165], v[212:215], v[12:15]
	v_mfma_f32_16x16x32_bf16 v[8:11], v[170:173], v[212:215], v[8:11]
	s_setprio 0
	s_barrier
	s_add_u32 s14, s34, 0x100080
	s_addc_u32 s15, s35, 0
	s_add_i32 s16, s17, s49
	v_lshl_add_u64 v[154:155], s[14:15], 0, v[128:129]
	s_mov_b32 m0, s16
	s_nop 0
	global_load_lds_dwordx4 v[154:155], off
	v_lshl_add_u64 v[154:155], s[14:15], 0, v[148:149]
	s_add_i32 m0, s16, 0x2000
	s_nop 0
	global_load_lds_dwordx4 v[154:155], off
	s_waitcnt vmcnt(6)
	s_barrier
	s_setprio 1
	v_mfma_f32_16x16x32_bf16 v[52:55], v[216:219], v[174:177], v[52:55]
	v_mfma_f32_16x16x32_bf16 v[48:51], v[224:227], v[174:177], v[48:51]
	v_mfma_f32_16x16x32_bf16 v[36:39], v[216:219], v[192:195], v[36:39]
	v_mfma_f32_16x16x32_bf16 v[32:35], v[224:227], v[192:195], v[32:35]
	v_mfma_f32_16x16x32_bf16 v[20:23], v[216:219], v[200:203], v[20:23]
	v_mfma_f32_16x16x32_bf16 v[16:19], v[224:227], v[200:203], v[16:19]
	v_mfma_f32_16x16x32_bf16 v[4:7], v[216:219], v[208:211], v[4:7]
	v_mfma_f32_16x16x32_bf16 v[0:3], v[224:227], v[208:211], v[0:3]
	v_mfma_f32_16x16x32_bf16 v[52:55], v[220:223], v[178:181], v[52:55]
	v_mfma_f32_16x16x32_bf16 v[48:51], v[228:231], v[178:181], v[48:51]
	v_mfma_f32_16x16x32_bf16 v[36:39], v[220:223], v[196:199], v[36:39]
	v_mfma_f32_16x16x32_bf16 v[32:35], v[228:231], v[196:199], v[32:35]
	v_mfma_f32_16x16x32_bf16 v[20:23], v[220:223], v[204:207], v[20:23]
	v_mfma_f32_16x16x32_bf16 v[16:19], v[228:231], v[204:207], v[16:19]
	v_mfma_f32_16x16x32_bf16 v[4:7], v[220:223], v[212:215], v[4:7]
	v_mfma_f32_16x16x32_bf16 v[0:3], v[228:231], v[212:215], v[0:3]
	s_setprio 0
	s_add_i32 s65, s65, 2
	s_add_u32 s63, s63, 0x100
	s_addc_u32 s64, s64, 0
	s_cmp_gt_u32 s65, 61
	s_mov_b64 s[26:27], s[30:31]
	s_barrier
	s_cbranch_scc0 .LBB0_1183
	v_lshl_add_u32 v156, s22, 8, v139
	v_ashrrev_i32_e32 v157, 31, v156
	v_lshl_or_b32 v154, s24, 8, v159
	v_lshlrev_b64 v[162:163], 12, v[156:157]
	v_ashrrev_i32_e32 v155, 31, v154
	v_lshl_add_u64 v[162:163], s[84:85], 0, v[162:163]
	v_lshl_add_u64 v[170:171], v[154:155], 2, v[162:163]
	global_load_dwordx4 v[192:195], v[170:171], off
	global_load_dwordx4 v[196:199], v[170:171], off offset:64
	global_load_dwordx4 v[200:203], v[170:171], off offset:512
	global_load_dwordx4 v[204:207], v[170:171], off offset:576
	v_add_co_u32_e32 v224, vcc, 0x10000, v170
	s_nop 1
	v_addc_co_u32_e32 v225, vcc, 0, v171, vcc
	global_load_dwordx4 v[208:211], v[224:225], off
	global_load_dwordx4 v[212:215], v[224:225], off offset:64
	global_load_dwordx4 v[216:219], v[224:225], off offset:512
	global_load_dwordx4 v[220:223], v[224:225], off offset:576
	v_lshlrev_b64 v[166:167], 11, v[156:157]
	v_lshl_add_u64 v[166:167], s[0:1], 0, v[166:167]
	v_lshl_add_u64 v[172:173], v[154:155], 1, v[166:167]
	v_xor_b32_e32 v161, 32, v189
	s_waitcnt vmcnt(4)
	v_mov_b32_e32 v162, v192
	v_mov_b32_e32 v163, v193
	v_mov_b32_e32 v164, v194
	v_mov_b32_e32 v165, v195
	v_pk_add_f32 v[126:127], v[126:127], v[164:165]
	v_pk_add_f32 v[124:125], v[124:125], v[162:163]
	v_cvt_pk_bf16_f32 v163, v126, v127
	v_cvt_pk_bf16_f32 v162, v124, v125
	global_store_dwordx4 v[170:171], v[124:127], off
	global_store_dwordx2 v[172:173], v[162:163], off
	s_nop 1
	v_mov_b32_e32 v162, v196
	v_mov_b32_e32 v163, v197
	v_mov_b32_e32 v164, v198
	v_mov_b32_e32 v165, v199
	v_pk_add_f32 v[122:123], v[122:123], v[164:165]
	v_pk_add_f32 v[120:121], v[120:121], v[162:163]
	v_cvt_pk_bf16_f32 v163, v122, v123
	v_cvt_pk_bf16_f32 v162, v120, v121
	global_store_dwordx4 v[170:171], v[120:123], off offset:64
	global_store_dwordx2 v[172:173], v[162:163], off offset:32
	s_nop 1
	v_mov_b32_e32 v162, v200
	v_mov_b32_e32 v163, v201
	v_mov_b32_e32 v164, v202
	v_mov_b32_e32 v165, v203
	v_pk_add_f32 v[164:165], v[118:119], v[164:165]
	v_pk_add_f32 v[162:163], v[116:117], v[162:163]
	v_cvt_pk_bf16_f32 v117, v164, v165
	v_cvt_pk_bf16_f32 v116, v162, v163
	global_store_dwordx4 v[170:171], v[162:165], off offset:512
	global_store_dwordx2 v[172:173], v[116:117], off offset:256
	s_nop 1
	v_mov_b32_e32 v166, v204
	v_mov_b32_e32 v167, v205
	v_mov_b32_e32 v168, v206
	v_mov_b32_e32 v169, v207
	v_mul_f32_e32 v118, v125, v125
	v_mul_f32_e32 v119, v127, v127
	v_fmac_f32_e32 v118, v124, v124
	v_fmac_f32_e32 v119, v126, v126
	v_add_f32_e32 v118, v118, v119
	v_mul_f32_e32 v119, v121, v121
	v_mul_f32_e32 v121, v123, v123
	v_fmac_f32_e32 v119, v120, v120
	v_fmac_f32_e32 v121, v122, v122
	v_add_f32_e32 v119, v119, v121
	v_add_f32_e32 v118, v118, v119
	v_mul_f32_e32 v119, v163, v163
	v_mul_f32_e32 v120, v165, v165
	v_fmac_f32_e32 v119, v162, v162
	v_fmac_f32_e32 v120, v164, v164
	v_add_f32_e32 v119, v119, v120
	v_and_b32_e32 v117, 64, v189
	v_add_f32_e32 v122, v118, v119
	v_xor_b32_e32 v116, 16, v189
	v_add_u32_e32 v117, 64, v117
	v_cmp_lt_i32_e32 vcc, v116, v117
	v_pk_add_f32 v[120:121], v[114:115], v[168:169]
	v_pk_add_f32 v[118:119], v[112:113], v[166:167]
	v_mul_f32_e32 v113, v121, v121
	v_mul_f32_e32 v112, v119, v119
	v_fmac_f32_e32 v112, v118, v118
	v_fmac_f32_e32 v113, v120, v120
	v_cndmask_b32_e32 v116, v189, v116, vcc
	v_add_f32_e32 v112, v112, v113
	v_lshlrev_b32_e32 v116, 2, v116
	v_add_f32_e32 v112, v122, v112
	ds_bpermute_b32 v113, v116, v112
	v_cmp_lt_i32_e32 vcc, v161, v117
	global_store_dwordx4 v[170:171], v[118:121], off offset:576
	s_waitcnt lgkmcnt(0)
	v_add_f32_e32 v115, v112, v113
	v_cndmask_b32_e32 v114, v189, v161, vcc
	v_lshlrev_b32_e32 v114, 2, v114
	ds_bpermute_b32 v117, v114, v115
	v_cvt_pk_bf16_f32 v112, v118, v119
	v_cvt_pk_bf16_f32 v113, v120, v121
	global_store_dwordx2 v[172:173], v[112:113], off offset:288
	v_lshl_add_u64 v[112:113], v[156:157], 2, s[2:3]
	s_and_saveexec_b64 s[22:23], s[38:39]
	s_cbranch_execz .LBB0_1186
	s_waitcnt lgkmcnt(0)
	v_add_f32_e32 v115, v115, v117
	global_atomic_add_f32 v[112:113], v115, off
; __device__ __forceinline__ unsigned cvt_pk_bf16(float lo, float hi) { const f32x2_cv v = {lo, hi}; const bf16x2_cv b = __builtin_convertvector(v, bf16x2_cv); return __builtin_bit_cast(unsigned, b); }
;     __device__ __forceinline__ void operator()(const f32x4 (&acc)[2][2][4][2], const pg8::Unit& u, int wr, int wc, int fr, int fq) const {
;     ...
;         for (int ai = 0; ai < 2; ++ai)
; #pragma unroll
;             for (int m = 0; m < 4; ++m) {
;                 const int row = row0 + ai * 128 + m * 16;
;                 float* xp = X + (size_t)row * 1024 + col0; bf16_t* bp = XB + (size_t)row * 1024 + col0;
;                 const float* xi = Xp0 ? (row < T_P ? Xp0 + (size_t)row * 1024 + col0 : Xs0 + (size_t)(row - T_P) * 1024 + col0) : xp;
;                 float ss = 0.f;
; #pragma unroll
;                 for (int bj = 0; bj < 2; ++bj)
; #pragma unroll
;                     for (int n = 0; n < 2; ++n) {
;                         f32x4 xv = *(const f32x4*)(xi + bj * 128 + n * 16) + acc[ai][bj][m][n];
;                         *(f32x4*)(xp + bj * 128 + n * 16) = xv;
;                         ss += (xv[0] * xv[0] + xv[1] * xv[1]) + (xv[2] * xv[2] + xv[3] * xv[3]);
;                         u32x2 w; w.x = cvt_pk_bf16(xv[0], xv[1]); w.y = cvt_pk_bf16(xv[2], xv[3]);
;                         *(u32x2*)(bp + bj * 128 + n * 16) = w; }
;                 ss += __shfl_xor(ss, 16); ss += __shfl_xor(ss, 32);
;                 if (fq == 0) atomicAdd(rowss_out + row, ss); }
.LBB0_1186:
	s_or_b64 exec, exec, s[22:23]
	v_or_b32_e32 v122, 16, v156
	v_ashrrev_i32_e32 v123, 31, v122
	v_lshlrev_b64 v[118:119], 12, v[122:123]
	v_lshl_add_u64 v[118:119], s[84:85], 0, v[118:119]
	v_lshl_add_u64 v[124:125], v[154:155], 2, v[118:119]
	v_add_co_u32_e32 v224, vcc, 0x10000, v124
	s_nop 1
	v_addc_co_u32_e32 v225, vcc, 0, v125, vcc
	global_load_dwordx4 v[192:195], v[224:225], off
	global_load_dwordx4 v[196:199], v[224:225], off offset:64
	global_load_dwordx4 v[200:203], v[224:225], off offset:512
	global_load_dwordx4 v[204:207], v[224:225], off offset:576
	v_lshlrev_b64 v[122:123], 11, v[122:123]
	v_lshl_add_u64 v[122:123], s[0:1], 0, v[122:123]
	v_lshl_add_u64 v[122:123], v[154:155], 1, v[122:123]
	s_waitcnt vmcnt(12)
	v_mov_b32_e32 v118, v208
	v_mov_b32_e32 v119, v209
	v_mov_b32_e32 v120, v210
	v_mov_b32_e32 v121, v211
	v_pk_add_f32 v[110:111], v[110:111], v[120:121]
	v_pk_add_f32 v[108:109], v[108:109], v[118:119]
	v_cvt_pk_bf16_f32 v119, v110, v111
	v_cvt_pk_bf16_f32 v118, v108, v109
	global_store_dwordx4 v[124:125], v[108:111], off
	global_store_dwordx2 v[122:123], v[118:119], off
	s_nop 1
	v_mov_b32_e32 v118, v212
	v_mov_b32_e32 v119, v213
	v_mov_b32_e32 v120, v214
	v_mov_b32_e32 v121, v215
	v_mul_f32_e32 v109, v109, v109
	v_mul_f32_e32 v111, v111, v111
	v_fmac_f32_e32 v109, v108, v108
	v_fmac_f32_e32 v111, v110, v110
	v_add_f32_e32 v108, v109, v111
	v_pk_add_f32 v[106:107], v[106:107], v[120:121]
	v_pk_add_f32 v[104:105], v[104:105], v[118:119]
	v_cvt_pk_bf16_f32 v119, v106, v107
	v_cvt_pk_bf16_f32 v118, v104, v105
	global_store_dwordx4 v[124:125], v[104:107], off offset:64
	global_store_dwordx2 v[122:123], v[118:119], off offset:32
	s_nop 1
	v_mov_b32_e32 v118, v216
	v_mov_b32_e32 v119, v217
	v_mov_b32_e32 v120, v218
	v_mov_b32_e32 v121, v219
	v_mul_f32_e32 v105, v105, v105
	v_mul_f32_e32 v107, v107, v107
	v_fmac_f32_e32 v105, v104, v104
	v_fmac_f32_e32 v107, v106, v106
	v_add_f32_e32 v104, v105, v107
	v_add_f32_e32 v104, v108, v104
	v_pk_add_f32 v[102:103], v[102:103], v[120:121]
	v_pk_add_f32 v[100:101], v[100:101], v[118:119]
	v_cvt_pk_bf16_f32 v119, v102, v103
	v_cvt_pk_bf16_f32 v118, v100, v101
	global_store_dwordx4 v[124:125], v[100:103], off offset:512
	global_store_dwordx2 v[122:123], v[118:119], off offset:256
	s_nop 1
	v_mov_b32_e32 v118, v220
	v_mov_b32_e32 v119, v221
	v_mov_b32_e32 v120, v222
	v_mov_b32_e32 v121, v223
	v_mul_f32_e32 v101, v101, v101
	v_mul_f32_e32 v103, v103, v103
	v_fmac_f32_e32 v101, v100, v100
	v_fmac_f32_e32 v103, v102, v102
	v_add_f32_e32 v100, v101, v103
	v_add_f32_e32 v102, v104, v100
	v_pk_add_f32 v[100:101], v[98:99], v[120:121]
	v_pk_add_f32 v[98:99], v[96:97], v[118:119]
	v_mul_f32_e32 v97, v101, v101
	v_mul_f32_e32 v96, v99, v99
	v_fmac_f32_e32 v96, v98, v98
	v_fmac_f32_e32 v97, v100, v100
	v_add_f32_e32 v96, v96, v97
	v_add_f32_e32 v96, v102, v96
	ds_bpermute_b32 v97, v116, v96
	global_store_dwordx4 v[124:125], v[98:101], off offset:576
	s_waitcnt lgkmcnt(0)
	v_add_f32_e32 v96, v96, v97
	ds_bpermute_b32 v97, v114, v96
	v_cvt_pk_bf16_f32 v98, v98, v99
	v_cvt_pk_bf16_f32 v99, v100, v101
	global_store_dwordx2 v[122:123], v[98:99], off offset:288
	s_and_saveexec_b64 s[22:23], s[38:39]
	s_mov_b32 s62, 0x1800000
	s_cbranch_execz .LBB0_1188
	s_waitcnt lgkmcnt(0)
	v_add_f32_e32 v96, v96, v97
	global_atomic_add_f32 v[112:113], v96, off offset:64
.LBB0_1188:
	s_or_b64 exec, exec, s[22:23]
	v_or_b32_e32 v100, 32, v156
	v_ashrrev_i32_e32 v101, 31, v100
	s_waitcnt lgkmcnt(0)
	v_lshlrev_b64 v[96:97], 12, v[100:101]
	v_lshl_add_u64 v[96:97], s[84:85], 0, v[96:97]
	v_lshl_add_u64 v[102:103], v[154:155], 2, v[96:97]
	v_add_co_u32_e32 v224, vcc, 0x10000, v102
	s_nop 1
	v_addc_co_u32_e32 v225, vcc, 0, v103, vcc
	global_load_dwordx4 v[208:211], v[224:225], off
	global_load_dwordx4 v[212:215], v[224:225], off offset:64
	global_load_dwordx4 v[216:219], v[224:225], off offset:512
	global_load_dwordx4 v[220:223], v[224:225], off offset:576
	v_lshlrev_b64 v[100:101], 11, v[100:101]
	v_lshl_add_u64 v[100:101], s[0:1], 0, v[100:101]
	v_lshl_add_u64 v[100:101], v[154:155], 1, v[100:101]
	s_waitcnt vmcnt(12)
	v_mov_b32_e32 v96, v192
	v_mov_b32_e32 v97, v193
	v_mov_b32_e32 v98, v194
	v_mov_b32_e32 v99, v195
	v_pk_add_f32 v[94:95], v[94:95], v[98:99]
	v_pk_add_f32 v[92:93], v[92:93], v[96:97]
	v_cvt_pk_bf16_f32 v97, v94, v95
	v_cvt_pk_bf16_f32 v96, v92, v93
	global_store_dwordx4 v[102:103], v[92:95], off
	global_store_dwordx2 v[100:101], v[96:97], off
	s_nop 1
	v_mov_b32_e32 v96, v196
	v_mov_b32_e32 v97, v197
	v_mov_b32_e32 v98, v198
	v_mov_b32_e32 v99, v199
	v_mul_f32_e32 v93, v93, v93
	v_mul_f32_e32 v95, v95, v95
	v_fmac_f32_e32 v93, v92, v92
	v_fmac_f32_e32 v95, v94, v94
	v_add_f32_e32 v92, v93, v95
	v_pk_add_f32 v[90:91], v[90:91], v[98:99]
	v_pk_add_f32 v[88:89], v[88:89], v[96:97]
	v_cvt_pk_bf16_f32 v97, v90, v91
	v_cvt_pk_bf16_f32 v96, v88, v89
	global_store_dwordx4 v[102:103], v[88:91], off offset:64
	global_store_dwordx2 v[100:101], v[96:97], off offset:32
	s_nop 1
	v_mov_b32_e32 v96, v200
	v_mov_b32_e32 v97, v201
	v_mov_b32_e32 v98, v202
	v_mov_b32_e32 v99, v203
	v_mul_f32_e32 v89, v89, v89
	v_mul_f32_e32 v91, v91, v91
	v_fmac_f32_e32 v89, v88, v88
	v_fmac_f32_e32 v91, v90, v90
	v_add_f32_e32 v88, v89, v91
	v_add_f32_e32 v88, v92, v88
	v_pk_add_f32 v[86:87], v[86:87], v[98:99]
	v_pk_add_f32 v[84:85], v[84:85], v[96:97]
	v_cvt_pk_bf16_f32 v97, v86, v87
	v_cvt_pk_bf16_f32 v96, v84, v85
	global_store_dwordx4 v[102:103], v[84:87], off offset:512
	global_store_dwordx2 v[100:101], v[96:97], off offset:256
	s_nop 1
	v_mov_b32_e32 v96, v204
	v_mov_b32_e32 v97, v205
	v_mov_b32_e32 v98, v206
	v_mov_b32_e32 v99, v207
	v_mul_f32_e32 v85, v85, v85
	v_mul_f32_e32 v87, v87, v87
	v_fmac_f32_e32 v85, v84, v84
	v_fmac_f32_e32 v87, v86, v86
	v_add_f32_e32 v84, v85, v87
	v_add_f32_e32 v86, v88, v84
	v_pk_add_f32 v[84:85], v[82:83], v[98:99]
	v_pk_add_f32 v[82:83], v[80:81], v[96:97]
	v_mul_f32_e32 v81, v85, v85
	v_mul_f32_e32 v80, v83, v83
	v_fmac_f32_e32 v80, v82, v82
	v_fmac_f32_e32 v81, v84, v84
	v_add_f32_e32 v80, v80, v81
	v_add_f32_e32 v80, v86, v80
	ds_bpermute_b32 v81, v116, v80
	global_store_dwordx4 v[102:103], v[82:85], off offset:576
	s_waitcnt lgkmcnt(0)
	v_add_f32_e32 v80, v80, v81
	ds_bpermute_b32 v81, v114, v80
	v_cvt_pk_bf16_f32 v82, v82, v83
	v_cvt_pk_bf16_f32 v83, v84, v85
	global_store_dwordx2 v[100:101], v[82:83], off offset:288
	s_and_saveexec_b64 s[22:23], s[38:39]
	s_cbranch_execz .LBB0_1190
	s_waitcnt lgkmcnt(0)
	v_add_f32_e32 v80, v80, v81
	global_atomic_add_f32 v[112:113], v80, off offset:128
; __device__ __forceinline__ unsigned cvt_pk_bf16(float lo, float hi) { const f32x2_cv v = {lo, hi}; const bf16x2_cv b = __builtin_convertvector(v, bf16x2_cv); return __builtin_bit_cast(unsigned, b); }
;     __device__ __forceinline__ void operator()(const f32x4 (&acc)[2][2][4][2], const pg8::Unit& u, int wr, int wc, int fr, int fq) const {
;     ...
;         for (int ai = 0; ai < 2; ++ai)
; #pragma unroll
;             for (int m = 0; m < 4; ++m) {
;                 const int row = row0 + ai * 128 + m * 16;
;                 float* xp = X + (size_t)row * 1024 + col0; bf16_t* bp = XB + (size_t)row * 1024 + col0;
;                 const float* xi = Xp0 ? (row < T_P ? Xp0 + (size_t)row * 1024 + col0 : Xs0 + (size_t)(row - T_P) * 1024 + col0) : xp;
;                 float ss = 0.f;
; #pragma unroll
;                 for (int bj = 0; bj < 2; ++bj)
; #pragma unroll
;                     for (int n = 0; n < 2; ++n) {
;                         f32x4 xv = *(const f32x4*)(xi + bj * 128 + n * 16) + acc[ai][bj][m][n];
;                         *(f32x4*)(xp + bj * 128 + n * 16) = xv;
;                         ss += (xv[0] * xv[0] + xv[1] * xv[1]) + (xv[2] * xv[2] + xv[3] * xv[3]);
;                         u32x2 w; w.x = cvt_pk_bf16(xv[0], xv[1]); w.y = cvt_pk_bf16(xv[2], xv[3]);
;                         *(u32x2*)(bp + bj * 128 + n * 16) = w; }
;                 ss += __shfl_xor(ss, 16); ss += __shfl_xor(ss, 32);
;                 if (fq == 0) atomicAdd(rowss_out + row, ss); }
.LBB0_1190:
	s_or_b64 exec, exec, s[22:23]
	v_or_b32_e32 v84, 48, v156
	v_ashrrev_i32_e32 v85, 31, v84
	s_waitcnt lgkmcnt(0)
	v_lshlrev_b64 v[80:81], 12, v[84:85]
	v_lshl_add_u64 v[80:81], s[84:85], 0, v[80:81]
	v_lshl_add_u64 v[86:87], v[154:155], 2, v[80:81]
	v_add_co_u32_e32 v224, vcc, 0x50000, v86
	s_nop 1
	v_addc_co_u32_e32 v225, vcc, 0, v87, vcc
	global_load_dwordx4 v[192:195], v[224:225], off
	global_load_dwordx4 v[196:199], v[224:225], off offset:64
	global_load_dwordx4 v[200:203], v[224:225], off offset:512
	global_load_dwordx4 v[204:207], v[224:225], off offset:576
	v_lshlrev_b64 v[84:85], 11, v[84:85]
	v_lshl_add_u64 v[84:85], s[0:1], 0, v[84:85]
	v_lshl_add_u64 v[84:85], v[154:155], 1, v[84:85]
	s_waitcnt vmcnt(12)
	v_mov_b32_e32 v80, v208
	v_mov_b32_e32 v81, v209
	v_mov_b32_e32 v82, v210
	v_mov_b32_e32 v83, v211
	v_pk_add_f32 v[78:79], v[78:79], v[82:83]
	v_pk_add_f32 v[76:77], v[76:77], v[80:81]
	v_cvt_pk_bf16_f32 v81, v78, v79
	v_cvt_pk_bf16_f32 v80, v76, v77
	global_store_dwordx4 v[86:87], v[76:79], off
	global_store_dwordx2 v[84:85], v[80:81], off
	s_nop 1
	v_mov_b32_e32 v80, v212
	v_mov_b32_e32 v81, v213
	v_mov_b32_e32 v82, v214
	v_mov_b32_e32 v83, v215
	v_mul_f32_e32 v77, v77, v77
	v_mul_f32_e32 v79, v79, v79
	v_fmac_f32_e32 v77, v76, v76
	v_fmac_f32_e32 v79, v78, v78
	v_add_f32_e32 v76, v77, v79
	v_pk_add_f32 v[74:75], v[74:75], v[82:83]
	v_pk_add_f32 v[72:73], v[72:73], v[80:81]
	v_cvt_pk_bf16_f32 v81, v74, v75
	v_cvt_pk_bf16_f32 v80, v72, v73
	global_store_dwordx4 v[86:87], v[72:75], off offset:64
	global_store_dwordx2 v[84:85], v[80:81], off offset:32
	s_nop 1
	v_mov_b32_e32 v80, v216
	v_mov_b32_e32 v81, v217
	v_mov_b32_e32 v82, v218
	v_mov_b32_e32 v83, v219
	v_mul_f32_e32 v73, v73, v73
	v_mul_f32_e32 v75, v75, v75
	v_fmac_f32_e32 v73, v72, v72
	v_fmac_f32_e32 v75, v74, v74
	v_add_f32_e32 v72, v73, v75
	v_add_f32_e32 v72, v76, v72
	v_pk_add_f32 v[70:71], v[70:71], v[82:83]
	v_pk_add_f32 v[68:69], v[68:69], v[80:81]
	v_cvt_pk_bf16_f32 v81, v70, v71
	v_cvt_pk_bf16_f32 v80, v68, v69
	global_store_dwordx4 v[86:87], v[68:71], off offset:512
	global_store_dwordx2 v[84:85], v[80:81], off offset:256
	s_nop 1
	v_mov_b32_e32 v80, v220
	v_mov_b32_e32 v81, v221
	v_mov_b32_e32 v82, v222
	v_mov_b32_e32 v83, v223
	v_mul_f32_e32 v69, v69, v69
	v_mul_f32_e32 v71, v71, v71
	v_fmac_f32_e32 v69, v68, v68
	v_fmac_f32_e32 v71, v70, v70
	v_add_f32_e32 v68, v69, v71
	v_add_f32_e32 v70, v72, v68
	v_pk_add_f32 v[68:69], v[66:67], v[82:83]
	v_pk_add_f32 v[66:67], v[64:65], v[80:81]
	v_mul_f32_e32 v65, v69, v69
	v_mul_f32_e32 v64, v67, v67
	v_fmac_f32_e32 v64, v66, v66
	v_fmac_f32_e32 v65, v68, v68
	v_add_f32_e32 v64, v64, v65
	v_add_f32_e32 v64, v70, v64
	ds_bpermute_b32 v65, v116, v64
	global_store_dwordx4 v[86:87], v[66:69], off offset:576
	s_waitcnt lgkmcnt(0)
	v_add_f32_e32 v64, v64, v65
	ds_bpermute_b32 v65, v114, v64
	v_cvt_pk_bf16_f32 v66, v66, v67
	v_cvt_pk_bf16_f32 v67, v68, v69
	global_store_dwordx2 v[84:85], v[66:67], off offset:288
	s_and_saveexec_b64 s[22:23], s[38:39]
	s_cbranch_execz .LBB0_1192
	s_waitcnt lgkmcnt(0)
	v_add_f32_e32 v64, v64, v65
	global_atomic_add_f32 v[112:113], v64, off offset:192
.LBB0_1192:
	s_or_b64 exec, exec, s[22:23]
	v_add_u32_e32 v68, 0x80, v156
	v_ashrrev_i32_e32 v69, 31, v68
	s_waitcnt lgkmcnt(0)
	v_lshlrev_b64 v[64:65], 12, v[68:69]
	v_lshl_add_u64 v[64:65], s[84:85], 0, v[64:65]
	v_lshl_add_u64 v[70:71], v[154:155], 2, v[64:65]
	v_add_co_u32_e32 v224, vcc, 0x10000, v70
	s_nop 1
	v_addc_co_u32_e32 v225, vcc, 0, v71, vcc
	global_load_dwordx4 v[208:211], v[224:225], off
	global_load_dwordx4 v[212:215], v[224:225], off offset:64
	global_load_dwordx4 v[216:219], v[224:225], off offset:512
	global_load_dwordx4 v[220:223], v[224:225], off offset:576
	v_lshlrev_b64 v[68:69], 11, v[68:69]
	v_lshl_add_u64 v[68:69], s[0:1], 0, v[68:69]
	v_lshl_add_u64 v[68:69], v[154:155], 1, v[68:69]
	s_waitcnt vmcnt(12)
	v_mov_b32_e32 v64, v192
	v_mov_b32_e32 v65, v193
	v_mov_b32_e32 v66, v194
	v_mov_b32_e32 v67, v195
	v_pk_add_f32 v[62:63], v[62:63], v[66:67]
	v_pk_add_f32 v[60:61], v[60:61], v[64:65]
	v_cvt_pk_bf16_f32 v65, v62, v63
	v_cvt_pk_bf16_f32 v64, v60, v61
	global_store_dwordx4 v[70:71], v[60:63], off
	global_store_dwordx2 v[68:69], v[64:65], off
	s_nop 1
	v_mov_b32_e32 v64, v196
	v_mov_b32_e32 v65, v197
	v_mov_b32_e32 v66, v198
	v_mov_b32_e32 v67, v199
	v_mul_f32_e32 v61, v61, v61
	v_mul_f32_e32 v63, v63, v63
	v_fmac_f32_e32 v61, v60, v60
	v_fmac_f32_e32 v63, v62, v62
	v_add_f32_e32 v60, v61, v63
	v_pk_add_f32 v[58:59], v[58:59], v[66:67]
	v_pk_add_f32 v[56:57], v[56:57], v[64:65]
	v_cvt_pk_bf16_f32 v65, v58, v59
	v_cvt_pk_bf16_f32 v64, v56, v57
	global_store_dwordx4 v[70:71], v[56:59], off offset:64
	global_store_dwordx2 v[68:69], v[64:65], off offset:32
	s_nop 1
	v_mov_b32_e32 v64, v200
	v_mov_b32_e32 v65, v201
	v_mov_b32_e32 v66, v202
	v_mov_b32_e32 v67, v203
	v_mul_f32_e32 v57, v57, v57
	v_mul_f32_e32 v59, v59, v59
	v_fmac_f32_e32 v57, v56, v56
	v_fmac_f32_e32 v59, v58, v58
	v_add_f32_e32 v56, v57, v59
	v_add_f32_e32 v56, v60, v56
	v_pk_add_f32 v[54:55], v[54:55], v[66:67]
	v_pk_add_f32 v[52:53], v[52:53], v[64:65]
	v_cvt_pk_bf16_f32 v65, v54, v55
	v_cvt_pk_bf16_f32 v64, v52, v53
	global_store_dwordx4 v[70:71], v[52:55], off offset:512
	global_store_dwordx2 v[68:69], v[64:65], off offset:256
	s_nop 1
	v_mov_b32_e32 v64, v204
	v_mov_b32_e32 v65, v205
	v_mov_b32_e32 v66, v206
	v_mov_b32_e32 v67, v207
	v_mul_f32_e32 v53, v53, v53
	v_mul_f32_e32 v55, v55, v55
	v_fmac_f32_e32 v53, v52, v52
	v_fmac_f32_e32 v55, v54, v54
	v_add_f32_e32 v52, v53, v55
	v_add_f32_e32 v54, v56, v52
	v_pk_add_f32 v[52:53], v[50:51], v[66:67]
	v_pk_add_f32 v[50:51], v[48:49], v[64:65]
	v_mul_f32_e32 v49, v53, v53
	v_mul_f32_e32 v48, v51, v51
	v_fmac_f32_e32 v48, v50, v50
	v_fmac_f32_e32 v49, v52, v52
	v_add_f32_e32 v48, v48, v49
	v_add_f32_e32 v48, v54, v48
	ds_bpermute_b32 v49, v116, v48
	global_store_dwordx4 v[70:71], v[50:53], off offset:576
	s_waitcnt lgkmcnt(0)
	v_add_f32_e32 v48, v48, v49
	ds_bpermute_b32 v49, v114, v48
	v_cvt_pk_bf16_f32 v50, v50, v51
	v_cvt_pk_bf16_f32 v51, v52, v53
	global_store_dwordx2 v[68:69], v[50:51], off offset:288
	s_and_saveexec_b64 s[22:23], s[38:39]
	s_cbranch_execz .LBB0_1194
	s_waitcnt lgkmcnt(0)
	v_add_f32_e32 v48, v48, v49
	global_atomic_add_f32 v[112:113], v48, off offset:512
; __device__ __forceinline__ unsigned cvt_pk_bf16(float lo, float hi) { const f32x2_cv v = {lo, hi}; const bf16x2_cv b = __builtin_convertvector(v, bf16x2_cv); return __builtin_bit_cast(unsigned, b); }
;     __device__ __forceinline__ void operator()(const f32x4 (&acc)[2][2][4][2], const pg8::Unit& u, int wr, int wc, int fr, int fq) const {
;     ...
;         for (int ai = 0; ai < 2; ++ai)
; #pragma unroll
;             for (int m = 0; m < 4; ++m) {
;                 const int row = row0 + ai * 128 + m * 16;
;                 float* xp = X + (size_t)row * 1024 + col0; bf16_t* bp = XB + (size_t)row * 1024 + col0;
;                 const float* xi = Xp0 ? (row < T_P ? Xp0 + (size_t)row * 1024 + col0 : Xs0 + (size_t)(row - T_P) * 1024 + col0) : xp;
;                 float ss = 0.f;
; #pragma unroll
;                 for (int bj = 0; bj < 2; ++bj)
; #pragma unroll
;                     for (int n = 0; n < 2; ++n) {
;                         f32x4 xv = *(const f32x4*)(xi + bj * 128 + n * 16) + acc[ai][bj][m][n];
;                         *(f32x4*)(xp + bj * 128 + n * 16) = xv;
;                         ss += (xv[0] * xv[0] + xv[1] * xv[1]) + (xv[2] * xv[2] + xv[3] * xv[3]);
;                         u32x2 w; w.x = cvt_pk_bf16(xv[0], xv[1]); w.y = cvt_pk_bf16(xv[2], xv[3]);
;                         *(u32x2*)(bp + bj * 128 + n * 16) = w; }
;                 ss += __shfl_xor(ss, 16); ss += __shfl_xor(ss, 32);
;                 if (fq == 0) atomicAdd(rowss_out + row, ss); }
.LBB0_1194:
	s_or_b64 exec, exec, s[22:23]
	v_add_u32_e32 v52, 0x90, v156
	v_ashrrev_i32_e32 v53, 31, v52
	s_waitcnt lgkmcnt(0)
	v_lshlrev_b64 v[48:49], 12, v[52:53]
	v_lshl_add_u64 v[48:49], s[84:85], 0, v[48:49]
	v_lshl_add_u64 v[54:55], v[154:155], 2, v[48:49]
	v_add_co_u32_e32 v224, vcc, 0x10000, v54
	s_nop 1
	v_addc_co_u32_e32 v225, vcc, 0, v55, vcc
	global_load_dwordx4 v[192:195], v[224:225], off
	global_load_dwordx4 v[196:199], v[224:225], off offset:64
	global_load_dwordx4 v[200:203], v[224:225], off offset:512
	global_load_dwordx4 v[204:207], v[224:225], off offset:576
	v_lshlrev_b64 v[52:53], 11, v[52:53]
	v_lshl_add_u64 v[52:53], s[0:1], 0, v[52:53]
	v_lshl_add_u64 v[52:53], v[154:155], 1, v[52:53]
	s_waitcnt vmcnt(12)
	v_mov_b32_e32 v48, v208
	v_mov_b32_e32 v49, v209
	v_mov_b32_e32 v50, v210
	v_mov_b32_e32 v51, v211
	v_pk_add_f32 v[46:47], v[46:47], v[50:51]
	v_pk_add_f32 v[44:45], v[44:45], v[48:49]
	v_cvt_pk_bf16_f32 v49, v46, v47
	v_cvt_pk_bf16_f32 v48, v44, v45
	global_store_dwordx4 v[54:55], v[44:47], off
	global_store_dwordx2 v[52:53], v[48:49], off
	s_nop 1
	v_mov_b32_e32 v48, v212
	v_mov_b32_e32 v49, v213
	v_mov_b32_e32 v50, v214
	v_mov_b32_e32 v51, v215
	v_mul_f32_e32 v45, v45, v45
	v_mul_f32_e32 v47, v47, v47
	v_fmac_f32_e32 v45, v44, v44
	v_fmac_f32_e32 v47, v46, v46
	v_add_f32_e32 v44, v45, v47
	v_pk_add_f32 v[42:43], v[42:43], v[50:51]
	v_pk_add_f32 v[40:41], v[40:41], v[48:49]
	v_cvt_pk_bf16_f32 v49, v42, v43
	v_cvt_pk_bf16_f32 v48, v40, v41
	global_store_dwordx4 v[54:55], v[40:43], off offset:64
	global_store_dwordx2 v[52:53], v[48:49], off offset:32
	s_nop 1
	v_mov_b32_e32 v48, v216
	v_mov_b32_e32 v49, v217
	v_mov_b32_e32 v50, v218
	v_mov_b32_e32 v51, v219
	v_mul_f32_e32 v41, v41, v41
	v_mul_f32_e32 v43, v43, v43
	v_fmac_f32_e32 v41, v40, v40
	v_fmac_f32_e32 v43, v42, v42
	v_add_f32_e32 v40, v41, v43
	v_add_f32_e32 v40, v44, v40
	v_pk_add_f32 v[38:39], v[38:39], v[50:51]
	v_pk_add_f32 v[36:37], v[36:37], v[48:49]
	v_cvt_pk_bf16_f32 v49, v38, v39
	v_cvt_pk_bf16_f32 v48, v36, v37
	global_store_dwordx4 v[54:55], v[36:39], off offset:512
	global_store_dwordx2 v[52:53], v[48:49], off offset:256
	s_nop 1
	v_mov_b32_e32 v48, v220
	v_mov_b32_e32 v49, v221
	v_mov_b32_e32 v50, v222
	v_mov_b32_e32 v51, v223
	v_mul_f32_e32 v37, v37, v37
	v_mul_f32_e32 v39, v39, v39
	v_fmac_f32_e32 v37, v36, v36
	v_fmac_f32_e32 v39, v38, v38
	v_add_f32_e32 v36, v37, v39
	v_add_f32_e32 v38, v40, v36
	v_pk_add_f32 v[36:37], v[34:35], v[50:51]
	v_pk_add_f32 v[34:35], v[32:33], v[48:49]
	v_mul_f32_e32 v33, v37, v37
	v_mul_f32_e32 v32, v35, v35
	v_fmac_f32_e32 v32, v34, v34
	v_fmac_f32_e32 v33, v36, v36
	v_add_f32_e32 v32, v32, v33
	v_add_f32_e32 v32, v38, v32
	ds_bpermute_b32 v33, v116, v32
	global_store_dwordx4 v[54:55], v[34:37], off offset:576
	s_waitcnt lgkmcnt(0)
	v_add_f32_e32 v32, v32, v33
	ds_bpermute_b32 v33, v114, v32
	v_cvt_pk_bf16_f32 v34, v34, v35
	v_cvt_pk_bf16_f32 v35, v36, v37
	global_store_dwordx2 v[52:53], v[34:35], off offset:288
	s_and_saveexec_b64 s[22:23], s[38:39]
	s_cbranch_execz .LBB0_1196
	s_waitcnt lgkmcnt(0)
	v_add_f32_e32 v32, v32, v33
	global_atomic_add_f32 v[112:113], v32, off offset:576
; __device__ __forceinline__ unsigned cvt_pk_bf16(float lo, float hi) { const f32x2_cv v = {lo, hi}; const bf16x2_cv b = __builtin_convertvector(v, bf16x2_cv); return __builtin_bit_cast(unsigned, b); }
;     __device__ __forceinline__ void operator()(const f32x4 (&acc)[2][2][4][2], const pg8::Unit& u, int wr, int wc, int fr, int fq) const {
;     ...
;         for (int ai = 0; ai < 2; ++ai)
; #pragma unroll
;             for (int m = 0; m < 4; ++m) {
;                 const int row = row0 + ai * 128 + m * 16;
;                 float* xp = X + (size_t)row * 1024 + col0; bf16_t* bp = XB + (size_t)row * 1024 + col0;
;                 const float* xi = Xp0 ? (row < T_P ? Xp0 + (size_t)row * 1024 + col0 : Xs0 + (size_t)(row - T_P) * 1024 + col0) : xp;
;                 float ss = 0.f;
; #pragma unroll
;                 for (int bj = 0; bj < 2; ++bj)
; #pragma unroll
;                     for (int n = 0; n < 2; ++n) {
;                         f32x4 xv = *(const f32x4*)(xi + bj * 128 + n * 16) + acc[ai][bj][m][n];
;                         *(f32x4*)(xp + bj * 128 + n * 16) = xv;
;                         ss += (xv[0] * xv[0] + xv[1] * xv[1]) + (xv[2] * xv[2] + xv[3] * xv[3]);
;                         u32x2 w; w.x = cvt_pk_bf16(xv[0], xv[1]); w.y = cvt_pk_bf16(xv[2], xv[3]);
;                         *(u32x2*)(bp + bj * 128 + n * 16) = w; }
;                 ss += __shfl_xor(ss, 16); ss += __shfl_xor(ss, 32);
;                 if (fq == 0) atomicAdd(rowss_out + row, ss); }
.LBB0_1196:
	s_or_b64 exec, exec, s[22:23]
	v_add_u32_e32 v36, 0xa0, v156
	v_ashrrev_i32_e32 v37, 31, v36
	s_waitcnt lgkmcnt(0)
	v_lshlrev_b64 v[32:33], 12, v[36:37]
	v_lshl_add_u64 v[32:33], s[84:85], 0, v[32:33]
	v_lshl_add_u64 v[38:39], v[154:155], 2, v[32:33]
	v_add_co_u32_e32 v224, vcc, 0x10000, v38
	s_nop 1
	v_addc_co_u32_e32 v225, vcc, 0, v39, vcc
	global_load_dwordx4 v[208:211], v[224:225], off
	global_load_dwordx4 v[212:215], v[224:225], off offset:64
	global_load_dwordx4 v[216:219], v[224:225], off offset:512
	global_load_dwordx4 v[220:223], v[224:225], off offset:576
	v_lshlrev_b64 v[36:37], 11, v[36:37]
	v_lshl_add_u64 v[36:37], s[0:1], 0, v[36:37]
	v_lshl_add_u64 v[36:37], v[154:155], 1, v[36:37]
	s_waitcnt vmcnt(12)
	v_mov_b32_e32 v32, v192
	v_mov_b32_e32 v33, v193
	v_mov_b32_e32 v34, v194
	v_mov_b32_e32 v35, v195
	v_pk_add_f32 v[30:31], v[30:31], v[34:35]
	v_pk_add_f32 v[28:29], v[28:29], v[32:33]
	v_cvt_pk_bf16_f32 v33, v30, v31
	v_cvt_pk_bf16_f32 v32, v28, v29
	global_store_dwordx4 v[38:39], v[28:31], off
	global_store_dwordx2 v[36:37], v[32:33], off
	s_nop 1
	v_mov_b32_e32 v32, v196
	v_mov_b32_e32 v33, v197
	v_mov_b32_e32 v34, v198
	v_mov_b32_e32 v35, v199
	v_mul_f32_e32 v29, v29, v29
	v_mul_f32_e32 v31, v31, v31
	v_fmac_f32_e32 v29, v28, v28
	v_fmac_f32_e32 v31, v30, v30
	v_add_f32_e32 v28, v29, v31
	v_pk_add_f32 v[26:27], v[26:27], v[34:35]
	v_pk_add_f32 v[24:25], v[24:25], v[32:33]
	v_cvt_pk_bf16_f32 v33, v26, v27
	v_cvt_pk_bf16_f32 v32, v24, v25
	global_store_dwordx4 v[38:39], v[24:27], off offset:64
	global_store_dwordx2 v[36:37], v[32:33], off offset:32
	s_nop 1
	v_mov_b32_e32 v32, v200
	v_mov_b32_e32 v33, v201
	v_mov_b32_e32 v34, v202
	v_mov_b32_e32 v35, v203
	v_mul_f32_e32 v25, v25, v25
	v_mul_f32_e32 v27, v27, v27
	v_fmac_f32_e32 v25, v24, v24
	v_fmac_f32_e32 v27, v26, v26
	v_add_f32_e32 v24, v25, v27
	v_add_f32_e32 v24, v28, v24
	v_pk_add_f32 v[22:23], v[22:23], v[34:35]
	v_pk_add_f32 v[20:21], v[20:21], v[32:33]
	v_cvt_pk_bf16_f32 v33, v22, v23
	v_cvt_pk_bf16_f32 v32, v20, v21
	global_store_dwordx4 v[38:39], v[20:23], off offset:512
	global_store_dwordx2 v[36:37], v[32:33], off offset:256
	s_nop 1
	v_mov_b32_e32 v32, v204
	v_mov_b32_e32 v33, v205
	v_mov_b32_e32 v34, v206
	v_mov_b32_e32 v35, v207
	v_mul_f32_e32 v21, v21, v21
	v_mul_f32_e32 v23, v23, v23
	v_fmac_f32_e32 v21, v20, v20
	v_fmac_f32_e32 v23, v22, v22
	v_add_f32_e32 v20, v21, v23
	v_add_f32_e32 v22, v24, v20
	v_pk_add_f32 v[20:21], v[18:19], v[34:35]
	v_pk_add_f32 v[18:19], v[16:17], v[32:33]
	v_mul_f32_e32 v17, v21, v21
	v_mul_f32_e32 v16, v19, v19
	v_fmac_f32_e32 v16, v18, v18
	v_fmac_f32_e32 v17, v20, v20
	v_add_f32_e32 v16, v16, v17
	v_add_f32_e32 v16, v22, v16
	ds_bpermute_b32 v17, v116, v16
	global_store_dwordx4 v[38:39], v[18:21], off offset:576
	s_waitcnt lgkmcnt(0)
	v_add_f32_e32 v16, v16, v17
	ds_bpermute_b32 v17, v114, v16
	v_cvt_pk_bf16_f32 v18, v18, v19
	v_cvt_pk_bf16_f32 v19, v20, v21
	global_store_dwordx2 v[36:37], v[18:19], off offset:288
	s_and_saveexec_b64 s[22:23], s[38:39]
	s_cbranch_execz .LBB0_1198
	s_waitcnt lgkmcnt(0)
	v_add_f32_e32 v16, v16, v17
	global_atomic_add_f32 v[112:113], v16, off offset:640
.LBB0_1198:
	s_or_b64 exec, exec, s[22:23]
	v_add_u32_e32 v16, 0xb0, v156
	s_waitcnt lgkmcnt(0)
	v_ashrrev_i32_e32 v17, 31, v16
	v_lshlrev_b64 v[18:19], 12, v[16:17]
	v_lshl_add_u64 v[18:19], s[84:85], 0, v[18:19]
	v_lshl_add_u64 v[22:23], v[154:155], 2, v[18:19]
	v_lshlrev_b64 v[16:17], 11, v[16:17]
	v_lshl_add_u64 v[16:17], s[0:1], 0, v[16:17]
	v_lshl_add_u64 v[16:17], v[154:155], 1, v[16:17]
	s_waitcnt vmcnt(8)
	v_mov_b32_e32 v18, v208
	v_mov_b32_e32 v19, v209
	v_mov_b32_e32 v20, v210
	v_mov_b32_e32 v21, v211
	v_pk_add_f32 v[12:13], v[12:13], v[18:19]
	v_pk_add_f32 v[14:15], v[14:15], v[20:21]
	v_mul_f32_e32 v18, v13, v13
	global_store_dwordx4 v[22:23], v[12:15], off
	v_fmac_f32_e32 v18, v12, v12
	v_mul_f32_e32 v19, v15, v15
	v_cvt_pk_bf16_f32 v12, v12, v13
	v_cvt_pk_bf16_f32 v13, v14, v15
	global_store_dwordx2 v[16:17], v[12:13], off
	v_fmac_f32_e32 v19, v14, v14
	s_nop 1
	v_mov_b32_e32 v12, v212
	v_mov_b32_e32 v13, v213
	v_mov_b32_e32 v14, v214
	v_mov_b32_e32 v15, v215
	v_add_f32_e32 v18, v18, v19
	v_pk_add_f32 v[8:9], v[8:9], v[12:13]
	v_pk_add_f32 v[10:11], v[10:11], v[14:15]
	v_mul_f32_e32 v12, v9, v9
	global_store_dwordx4 v[22:23], v[8:11], off offset:64
	v_fmac_f32_e32 v12, v8, v8
	v_mul_f32_e32 v13, v11, v11
	v_cvt_pk_bf16_f32 v8, v8, v9
	v_cvt_pk_bf16_f32 v9, v10, v11
	global_store_dwordx2 v[16:17], v[8:9], off offset:32
	v_fmac_f32_e32 v13, v10, v10
	s_nop 1
	v_mov_b32_e32 v8, v216
	v_mov_b32_e32 v9, v217
	v_mov_b32_e32 v10, v218
	v_mov_b32_e32 v11, v219
	v_add_f32_e32 v12, v12, v13
	v_add_f32_e32 v12, v18, v12
	v_pk_add_f32 v[4:5], v[4:5], v[8:9]
	v_pk_add_f32 v[6:7], v[6:7], v[10:11]
	v_mul_f32_e32 v8, v5, v5
	global_store_dwordx4 v[22:23], v[4:7], off offset:512
	v_fmac_f32_e32 v8, v4, v4
	v_mul_f32_e32 v9, v7, v7
	v_cvt_pk_bf16_f32 v4, v4, v5
	v_cvt_pk_bf16_f32 v5, v6, v7
	global_store_dwordx2 v[16:17], v[4:5], off offset:256
	v_fmac_f32_e32 v9, v6, v6
	s_nop 1
	v_mov_b32_e32 v4, v220
	v_mov_b32_e32 v5, v221
	v_mov_b32_e32 v6, v222
	v_mov_b32_e32 v7, v223
	v_add_f32_e32 v8, v8, v9
	v_add_f32_e32 v8, v12, v8
	v_pk_add_f32 v[2:3], v[2:3], v[6:7]
	v_pk_add_f32 v[0:1], v[0:1], v[4:5]
	v_mul_f32_e32 v5, v3, v3
	v_mul_f32_e32 v4, v1, v1
	v_fmac_f32_e32 v4, v0, v0
	v_fmac_f32_e32 v5, v2, v2
	v_add_f32_e32 v4, v4, v5
	global_store_dwordx4 v[22:23], v[0:3], off offset:576
	v_add_f32_e32 v4, v8, v4
	s_nop 0
	v_cvt_pk_bf16_f32 v0, v0, v1
	v_cvt_pk_bf16_f32 v1, v2, v3
	global_store_dwordx2 v[16:17], v[0:1], off offset:288
	ds_bpermute_b32 v0, v116, v4
	s_waitcnt lgkmcnt(0)
	v_add_f32_e32 v0, v4, v0
	ds_bpermute_b32 v1, v114, v0
	s_and_saveexec_b64 s[22:23], s[38:39]
	s_cbranch_execz .LBB0_1175
	s_waitcnt lgkmcnt(0)
	v_add_f32_e32 v0, v0, v1
	global_atomic_add_f32 v[112:113], v0, off offset:704
	s_branch .LBB0_1175
